# v55 + hyena loop: 111 register-pair copies removed by swapping register roles (pure renaming, checked by value numbering)
# speedup vs baseline: 1.0161x; 1.0012x over previous
; template <int R, bool INV> DEV void dft_regs(cf (&v)[R]) {
; #pragma unroll
;     for (int s = R; s >= 2; s >>= 1) {
;         const int h = s >> 1;
; #pragma unroll
;         for (int b = 0; b < R; b += s) {
; #pragma unroll
;             for (int k = 0; k < h; ++k) {
;                 const cf a = v[b + k], c = v[b + k + h];
;                 v[b + k] = a + c;
;                 const cf d = a - c;
;                 const int m = k * (32 / s);
;                 const float wr = tw_cos(m), wi = INV ? tw_sin(m) : -tw_sin(m);
;                 v[b + k + h] = cf{d.x * wr - d.y * wi, d.x * wi + d.y * wr};
;             }
;         }
;     }
; }
; DEV void fft_i1x2(LAS cf* buf0, LAS cf* buf1, cf (&y0)[8], cf (&y1)[8], int tid) {
;     ...
;     dft_regs<16, true>(v); dft_regs<16, true>(u);
; #pragma unroll
;     for (int q = 0; q < 8; ++q) { y0[q] = v[BR16[q]]; y1[q] = u[BR16[q]]; }
.LBB0_518:
	v_pk_add_f32 v[126:127], v[76:77], v[100:101]
	v_pk_add_f32 v[76:77], v[76:77], v[100:101] neg_lo:[0,1] neg_hi:[0,1]
	s_mov_b32 s10, s85
	s_mov_b32 s8, s97
	s_xor_b64 s[2:3], s[22:23], -1
	v_pk_add_f32 v[164:165], v[78:79], v[112:113]
	v_pk_add_f32 v[78:79], v[78:79], v[112:113] neg_lo:[0,1] neg_hi:[0,1]
	s_lshl_b64 s[6:7], s[6:7], 2
	v_pk_mul_f32 v[100:101], v[78:79], s[84:85] op_sel_hi:[1,0]
	s_add_u32 s22, s76, s6
	v_pk_fma_f32 v[112:113], v[78:79], s[10:11], v[100:101] op_sel:[0,0,1] op_sel_hi:[1,0,0] neg_lo:[0,0,1]
	s_addc_u32 s23, s77, s7
	v_pk_add_f32 v[78:79], v[82:83], v[116:117]
	v_pk_add_f32 v[82:83], v[82:83], v[116:117] neg_lo:[0,1] neg_hi:[0,1]
	s_add_u32 s6, s74, s6
	v_pk_mul_f32 v[100:101], v[82:83], s[8:9] op_sel_hi:[1,0]
	s_waitcnt lgkmcnt(0)
	v_pk_fma_f32 v[116:117], v[82:83], s[8:9], v[100:101] op_sel:[0,0,1] op_sel_hi:[1,0,0] neg_lo:[0,0,1] neg_hi:[0,0,1]
	v_pk_fma_f32 v[82:83], v[82:83], s[8:9], v[100:101] op_sel_hi:[1,0,0]
	v_pk_add_f32 v[100:101], v[84:85], v[118:119]
	v_pk_add_f32 v[84:85], v[84:85], v[118:119] neg_lo:[0,1] neg_hi:[0,1]
	v_mov_b32_e32 v117, v83
	v_pk_mul_f32 v[118:119], v[84:85], s[10:11] op_sel_hi:[1,0]
	s_barrier
	v_pk_fma_f32 v[166:167], v[84:85], s[84:85], v[118:119] op_sel:[0,0,1] op_sel_hi:[1,0,0] neg_lo:[0,0,1]
	v_pk_add_f32 v[84:85], v[86:87], v[120:121]
	v_pk_add_f32 v[86:87], v[86:87], v[120:121] neg_lo:[0,1] neg_hi:[0,1]
	s_addc_u32 s7, s75, s7
	v_pk_add_f32 v[118:119], v[86:87], 0 op_sel:[1,0] op_sel_hi:[0,0] neg_lo:[1,0]
	s_mov_b32 s19, 1
	v_pk_add_f32 v[86:87], v[90:91], v[122:123]
	v_pk_add_f32 v[90:91], v[90:91], v[122:123] neg_lo:[0,1] neg_hi:[0,1]
	v_pk_add_f32 v[122:123], v[98:99], v[92:93]
	v_pk_add_f32 v[92:93], v[98:99], v[92:93] neg_lo:[0,1] neg_hi:[0,1]
	v_pk_mul_f32 v[120:121], v[90:91], s[24:25] op_sel:[1,0]
	v_pk_mul_f32 v[98:99], v[92:93], s[84:85] op_sel:[1,0]
	v_pk_fma_f32 v[90:91], v[90:91], s[0:1], v[120:121] op_sel_hi:[0,1,1] neg_lo:[0,0,1] neg_hi:[0,0,1]
	v_pk_fma_f32 v[92:93], v[92:93], s[88:89], v[98:99] op_sel_hi:[0,1,1] neg_lo:[0,0,1] neg_hi:[0,0,1]
	v_pk_add_f32 v[98:99], v[126:127], v[84:85]
	v_pk_add_f32 v[84:85], v[126:127], v[84:85] neg_lo:[0,1] neg_hi:[0,1]
	v_pk_add_f32 v[120:121], v[94:95], v[124:125]
	v_pk_add_f32 v[94:95], v[94:95], v[124:125] neg_lo:[0,1] neg_hi:[0,1]
	v_mul_f32_e32 v82, 0x3f3504f3, v95
	v_pk_fma_f32 v[94:95], v[94:95], s[96:97], v[82:83] op_sel_hi:[0,1,0] neg_lo:[0,0,1] neg_hi:[0,0,1]
	v_pk_add_f32 v[126:127], v[164:165], v[86:87]
	v_pk_add_f32 v[164:165], v[164:165], v[86:87] neg_lo:[0,1] neg_hi:[0,1]
	v_pk_add_f32 v[82:83], v[116:117], v[94:95]
	v_pk_mul_f32 v[86:87], v[164:165], s[8:9] op_sel_hi:[1,0]
	s_mov_b64 s[26:27], -1
	v_pk_fma_f32 v[124:125], v[164:165], s[8:9], v[86:87] op_sel:[0,0,1] op_sel_hi:[1,0,0] neg_lo:[0,0,1] neg_hi:[0,0,1]
	v_pk_fma_f32 v[164:165], v[164:165], s[8:9], v[86:87] op_sel_hi:[1,0,0]
	v_pk_add_f32 v[86:87], v[78:79], v[120:121]
	v_pk_add_f32 v[78:79], v[78:79], v[120:121] neg_lo:[0,1] neg_hi:[0,1]
	v_mov_b32_e32 v125, v165
	v_pk_add_f32 v[120:121], v[78:79], 0 op_sel:[1,0] op_sel_hi:[0,0] neg_lo:[1,0]
	v_pk_add_f32 v[78:79], v[100:101], v[122:123]
	v_pk_add_f32 v[100:101], v[100:101], v[122:123] neg_lo:[0,1] neg_hi:[0,1]
	v_pk_add_f32 v[122:123], v[76:77], v[118:119]
	v_pk_add_f32 v[118:119], v[76:77], v[118:119] neg_lo:[0,1] neg_hi:[0,1]
	v_mul_f32_e32 v164, 0x3f3504f3, v101
	v_pk_fma_f32 v[100:101], v[100:101], s[96:97], v[164:165] op_sel_hi:[0,1,0] neg_lo:[0,0,1] neg_hi:[0,0,1]
	v_mov_b32_e32 v168, v118
	v_mov_b32_e32 v169, v119
	v_pk_add_f32 v[118:119], v[112:113], v[90:91]
	v_pk_add_f32 v[90:91], v[112:113], v[90:91] neg_lo:[0,1] neg_hi:[0,1]
	v_pk_mul_f32 v[112:113], v[90:91], s[8:9] op_sel_hi:[1,0]
	v_pk_fma_f32 v[76:77], v[90:91], s[8:9], v[112:113] op_sel:[0,0,1] op_sel_hi:[1,0,0] neg_lo:[0,0,1]
	v_pk_add_f32 v[112:113], v[98:99], v[86:87]
	v_pk_add_f32 v[86:87], v[98:99], v[86:87] neg_lo:[0,1] neg_hi:[0,1]
	v_pk_add_f32 v[90:91], v[116:117], v[94:95] neg_lo:[0,1] neg_hi:[0,1]
	v_pk_add_f32 v[98:99], v[84:85], v[120:121] neg_lo:[0,1] neg_hi:[0,1]
	v_pk_add_f32 v[116:117], v[126:127], v[78:79]
	v_pk_add_f32 v[78:79], v[126:127], v[78:79] neg_lo:[0,1] neg_hi:[0,1]
	v_pk_add_f32 v[94:95], v[90:91], 0 op_sel:[1,0] op_sel_hi:[0,0] neg_lo:[1,0]
	v_pk_add_f32 v[126:127], v[78:79], 0 op_sel:[1,0] op_sel_hi:[0,0] neg_lo:[1,0]
	v_pk_add_f32 v[78:79], v[84:85], v[120:121]
	v_pk_add_f32 v[90:91], v[166:167], v[92:93]
	v_pk_add_f32 v[92:93], v[166:167], v[92:93] neg_lo:[0,1] neg_hi:[0,1]
	v_mul_f32_e32 v164, 0x3f3504f3, v93
	v_pk_add_f32 v[84:85], v[124:125], v[100:101] neg_lo:[0,1] neg_hi:[0,1]
	v_pk_fma_f32 v[92:93], v[92:93], s[96:97], v[164:165] op_sel_hi:[0,1,0] neg_lo:[0,0,1] neg_hi:[0,0,1]
	v_pk_add_f32 v[164:165], v[124:125], v[100:101]
	v_pk_add_f32 v[100:101], v[84:85], 0 op_sel:[1,0] op_sel_hi:[0,0] neg_lo:[1,0]
	v_pk_add_f32 v[120:121], v[122:123], v[82:83]
	v_pk_add_f32 v[82:83], v[122:123], v[82:83] neg_lo:[0,1] neg_hi:[0,1]
	v_pk_add_f32 v[124:125], v[168:169], v[94:95]
	v_pk_add_f32 v[84:85], v[78:79], v[164:165]
	v_pk_add_f32 v[122:123], v[118:119], v[90:91]
	v_pk_add_f32 v[90:91], v[118:119], v[90:91] neg_lo:[0,1] neg_hi:[0,1]
	v_pk_add_f32 v[164:165], v[16:17], v[88:89]
	v_pk_add_f32 v[118:119], v[90:91], 0 op_sel:[1,0] op_sel_hi:[0,0] neg_lo:[1,0]
	v_pk_add_f32 v[16:17], v[16:17], v[88:89] neg_lo:[0,1] neg_hi:[0,1]
	v_pk_add_f32 v[90:91], v[168:169], v[94:95] neg_lo:[0,1] neg_hi:[0,1]
	v_pk_add_f32 v[112:113], v[112:113], v[116:117]
	v_mov_b32_e32 v166, v90
	v_mov_b32_e32 v167, v91
	v_pk_add_f32 v[94:95], v[76:77], v[92:93]
	v_pk_add_f32 v[90:91], v[76:77], v[92:93] neg_lo:[0,1] neg_hi:[0,1]
; #define SYNC() __syncthreads()
; template <int R, bool INV> DEV void dft_regs(cf (&v)[R]) {
; #pragma unroll
;     for (int s = R; s >= 2; s >>= 1) {
;         const int h = s >> 1;
; #pragma unroll
;         for (int b = 0; b < R; b += s) {
; #pragma unroll
;             for (int k = 0; k < h; ++k) {
;                 const cf a = v[b + k], c = v[b + k + h];
;                 v[b + k] = a + c;
;                 const cf d = a - c;
;                 const int m = k * (32 / s);
;                 const float wr = tw_cos(m), wi = INV ? tw_sin(m) : -tw_sin(m);
;                 v[b + k + h] = cf{d.x * wr - d.y * wi, d.x * wi + d.y * wr};
;             }
;         }
;     }
; }
; DEV void hyena_units(int c0, int cstride, const bf16_t* UT, bf16_t* YHT, const unsigned* KF, const float* convw  , const float* convb  , const float* hyb  , LAS unsigned char* lds, int tid, bool abl = false) {
;     ...
;                 for (int i = 0; i < 8; ++i) { y[0][i] = z[0][i]; y[1][i] = z[1][i]; }
;             } else fft_i1x2(buf0, buf1, y[0], y[1], tid);
;             SYNC();
;             hyena_commit_rows(lds, r, tid);
;             if (o == 1 && c + cstride < 1024) hyena_issue_rows(UT, 0, c + cstride, r, tid);
;             SYNC();
;             const int col = (1 + o) * 1024 + c;
;             hyena_conv_rows<1>(lds, 0, convw[col], convw[3072 + col], convw[6144 + col], convb[col], z, y, hyb[o * 1024 + c], tid);
	v_pk_add_f32 v[92:93], v[86:87], v[126:127]
	v_pk_add_f32 v[76:77], v[90:91], 0 op_sel:[1,0] op_sel_hi:[0,0] neg_lo:[1,0]
	v_pk_add_f32 v[126:127], v[18:19], v[96:97]
	v_pk_add_f32 v[18:19], v[18:19], v[96:97] neg_lo:[0,1] neg_hi:[0,1]
	v_pk_mul_f32 v[78:79], v[18:19], s[84:85] op_sel_hi:[1,0]
	v_pk_fma_f32 v[88:89], v[18:19], s[10:11], v[78:79] op_sel:[0,0,1] op_sel_hi:[1,0,0] neg_lo:[0,0,1]
	v_pk_add_f32 v[90:91], v[82:83], v[118:119]
	v_pk_add_f32 v[18:19], v[66:67], v[102:103]
	v_pk_add_f32 v[66:67], v[66:67], v[102:103] neg_lo:[0,1] neg_hi:[0,1]
	v_pk_add_f32 v[86:87], v[98:99], v[100:101]
	v_pk_mul_f32 v[78:79], v[66:67], s[8:9] op_sel_hi:[1,0]
	v_pk_add_f32 v[100:101], v[120:121], v[122:123]
	v_pk_fma_f32 v[96:97], v[66:67], s[8:9], v[78:79] op_sel:[0,0,1] op_sel_hi:[1,0,0] neg_lo:[0,0,1]
	v_pk_add_f32 v[94:95], v[124:125], v[94:95]
	v_pk_add_f32 v[66:67], v[68:69], v[104:105]
	v_pk_add_f32 v[68:69], v[68:69], v[104:105] neg_lo:[0,1] neg_hi:[0,1]
	v_pk_add_f32 v[82:83], v[166:167], v[76:77]
	v_pk_mul_f32 v[78:79], v[68:69], s[10:11] op_sel_hi:[1,0]
	v_pk_fma_f32 v[102:103], v[68:69], s[84:85], v[78:79] op_sel:[0,0,1] op_sel_hi:[1,0,0] neg_lo:[0,0,1]
	v_pk_add_f32 v[68:69], v[70:71], v[106:107]
	v_pk_add_f32 v[70:71], v[70:71], v[106:107] neg_lo:[0,1] neg_hi:[0,1]
	v_pk_add_f32 v[78:79], v[70:71], 0 op_sel:[1,0] op_sel_hi:[0,0] neg_lo:[1,0]
	v_pk_add_f32 v[70:71], v[72:73], v[108:109]
	v_pk_add_f32 v[72:73], v[72:73], v[108:109] neg_lo:[0,1] neg_hi:[0,1]
	v_pk_add_f32 v[120:121], v[16:17], v[78:79]
	v_pk_mul_f32 v[104:105], v[72:73], s[24:25] op_sel:[1,0]
	v_pk_fma_f32 v[72:73], v[72:73], s[0:1], v[104:105] op_sel_hi:[0,1,1] neg_lo:[0,0,1] neg_hi:[0,0,1]
	v_pk_add_f32 v[104:105], v[74:75], v[110:111]
	v_pk_add_f32 v[74:75], v[74:75], v[110:111] neg_lo:[0,1] neg_hi:[0,1]
	v_pk_add_f32 v[116:117], v[18:19], v[104:105]
	v_mul_f32_e32 v106, 0x3f3504f3, v75
	v_pk_fma_f32 v[74:75], v[74:75], s[96:97], v[106:107] op_sel_hi:[0,1,0] neg_lo:[0,0,1] neg_hi:[0,0,1]
	v_pk_add_f32 v[106:107], v[80:81], v[114:115]
	v_pk_add_f32 v[80:81], v[80:81], v[114:115] neg_lo:[0,1] neg_hi:[0,1]
	v_pk_add_f32 v[118:119], v[66:67], v[106:107]
	v_pk_mul_f32 v[108:109], v[80:81], s[84:85] op_sel:[1,0]
	v_pk_fma_f32 v[80:81], v[80:81], s[88:89], v[108:109] op_sel_hi:[0,1,1] neg_lo:[0,0,1] neg_hi:[0,0,1]
	v_pk_add_f32 v[108:109], v[164:165], v[68:69]
	v_pk_add_f32 v[68:69], v[164:165], v[68:69] neg_lo:[0,1] neg_hi:[0,1]
	v_mov_b32_e32 v110, v68
	v_mov_b32_e32 v111, v69
	v_pk_add_f32 v[76:77], v[126:127], v[70:71]
	v_pk_add_f32 v[126:127], v[126:127], v[70:71] neg_lo:[0,1] neg_hi:[0,1]
	v_pk_mul_f32 v[68:69], v[126:127], s[8:9] op_sel_hi:[1,0]
	v_pk_fma_f32 v[114:115], v[126:127], s[8:9], v[68:69] op_sel:[0,0,1] op_sel_hi:[1,0,0] neg_lo:[0,0,1]
	v_pk_add_f32 v[126:127], v[18:19], v[104:105] neg_lo:[0,1] neg_hi:[0,1]
	v_pk_add_f32 v[104:105], v[126:127], 0 op_sel:[1,0] op_sel_hi:[0,0] neg_lo:[1,0]
	v_pk_add_f32 v[126:127], v[66:67], v[106:107] neg_lo:[0,1] neg_hi:[0,1]
	v_mul_f32_e32 v18, 0x3f3504f3, v127
	v_pk_fma_f32 v[106:107], v[126:127], s[96:97], v[18:19] op_sel_hi:[0,1,0] neg_lo:[0,0,1] neg_hi:[0,0,1]
	v_pk_add_f32 v[126:127], v[16:17], v[78:79] neg_lo:[0,1] neg_hi:[0,1]
	v_pk_add_f32 v[98:99], v[88:89], v[72:73]
	v_mov_b32_e32 v78, v126
	v_mov_b32_e32 v79, v127
	v_pk_add_f32 v[16:17], v[88:89], v[72:73] neg_lo:[0,1] neg_hi:[0,1]
	v_pk_add_f32 v[88:89], v[96:97], v[74:75]
	v_pk_mul_f32 v[18:19], v[16:17], s[8:9] op_sel_hi:[1,0]
	v_pk_fma_f32 v[72:73], v[16:17], s[8:9], v[18:19] op_sel:[0,0,1] op_sel_hi:[1,0,0] neg_lo:[0,0,1]
	v_pk_add_f32 v[16:17], v[96:97], v[74:75] neg_lo:[0,1] neg_hi:[0,1]
	v_pk_add_f32 v[96:97], v[102:103], v[80:81]
	v_pk_fma_f32 v[74:75], v[16:17], 0, v[16:17] op_sel:[0,0,1] op_sel_hi:[1,0,0] neg_lo:[0,0,1] neg_hi:[0,0,1]
	v_pk_fma_f32 v[16:17], v[16:17], 0, v[16:17] op_sel:[0,0,1] op_sel_hi:[1,0,0]
	global_load_dword v18, v20, s[22:23]
	global_load_dword v66, v245, s[22:23]
	global_load_dword v16, v206, s[22:23]
	s_add_i32 s22, s5, s78
	s_ashr_i32 s23, s22, 31
	s_lshl_b64 s[22:23], s[22:23], 2
	s_add_u32 s22, s72, s22
	s_addc_u32 s23, s73, s23
	global_load_dword v68, v20, s[6:7]
	global_load_dword v70, v20, s[22:23]
	v_pk_add_f32 v[80:81], v[102:103], v[80:81] neg_lo:[0,1] neg_hi:[0,1]
	v_mov_b32_e32 v75, v17
	v_mul_f32_e32 v102, 0x3f3504f3, v81
	v_pk_fma_f32 v[80:81], v[80:81], s[96:97], v[102:103] op_sel_hi:[0,1,0] neg_lo:[0,0,1] neg_hi:[0,0,1]
	v_pk_add_f32 v[102:103], v[108:109], v[116:117]
	v_pk_add_f32 v[108:109], v[108:109], v[116:117] neg_lo:[0,1] neg_hi:[0,1]
	v_pk_add_f32 v[124:125], v[78:79], v[74:75]
	v_pk_add_f32 v[74:75], v[78:79], v[74:75] neg_lo:[0,1] neg_hi:[0,1]
	v_pk_add_f32 v[122:123], v[76:77], v[118:119]
	v_pk_add_f32 v[76:77], v[76:77], v[118:119] neg_lo:[0,1] neg_hi:[0,1]
	v_mov_b32_e32 v126, v74
	v_mov_b32_e32 v127, v75
	v_pk_add_f32 v[116:117], v[76:77], 0 op_sel:[1,0] op_sel_hi:[0,0] neg_lo:[1,0]
	v_pk_add_f32 v[76:77], v[110:111], v[104:105]
	v_pk_add_f32 v[104:105], v[110:111], v[104:105] neg_lo:[0,1] neg_hi:[0,1]
	v_pk_add_f32 v[78:79], v[108:109], v[116:117]
	v_pk_add_f32 v[164:165], v[72:73], v[80:81]
	v_pk_add_f32 v[118:119], v[114:115], v[106:107]
	v_pk_add_f32 v[106:107], v[114:115], v[106:107] neg_lo:[0,1] neg_hi:[0,1]
	v_pk_add_f32 v[72:73], v[72:73], v[80:81] neg_lo:[0,1] neg_hi:[0,1]
	v_pk_add_f32 v[110:111], v[106:107], 0 op_sel:[1,0] op_sel_hi:[0,0] neg_lo:[1,0]
	v_pk_add_f32 v[80:81], v[124:125], v[164:165]
	v_pk_add_f32 v[106:107], v[120:121], v[88:89]
	v_pk_add_f32 v[88:89], v[120:121], v[88:89] neg_lo:[0,1] neg_hi:[0,1]
	v_pk_add_f32 v[74:75], v[104:105], v[110:111]
	v_pk_fma_f32 v[166:167], v[72:73], 0, v[72:73] op_sel:[0,0,1] op_sel_hi:[1,0,0] neg_lo:[0,0,1]
	v_mov_b32_e32 v120, v88
	v_mov_b32_e32 v121, v89
	v_pk_add_f32 v[88:89], v[98:99], v[96:97]
	v_pk_add_f32 v[98:99], v[98:99], v[96:97] neg_lo:[0,1] neg_hi:[0,1]
	v_pk_add_f32 v[96:97], v[102:103], v[122:123]
	ds_read2st64_b32 v[102:103], v130 offset1:32
	v_pk_add_f32 v[114:115], v[98:99], 0 op_sel:[1,0] op_sel_hi:[0,0] neg_lo:[1,0]
	v_pk_add_f32 v[88:89], v[106:107], v[88:89]
	v_pk_add_f32 v[98:99], v[76:77], v[118:119]
	ds_read2st64_b32 v[104:105], v129 offset1:32
	s_waitcnt lgkmcnt(1)
; #define LAS __attribute__((address_space(3)))
; #define U2F(x) __uint_as_float(x)
; template <int MODE> DEV void hyena_conv_rows(const LAS unsigned char* lds, int slot0, float w0, float w1, float w2, float bs, cf (&z)[2][8], const cf (&y)[2][8], float hb, int tid) {
;     ...
;         for (int i = 0; i < 8; ++i) {
;             const int t = tid + 512 * i, par = tid & 1, d0 = (tid >> 1) + par;
;             const LAS unsigned* rw = (const LAS unsigned*)row + d0;
;             const unsigned dw0 = (i == 0) ? rw[d0 > 0 ? -1 : 0] : rw[256 * i - 1], dw1 = rw[256 * i];
;             float um = par ? U2F(dw0 << 16) : U2F(dw0 & 0xffff0000u);
;             const float u0 = par ? U2F(dw0 & 0xffff0000u) : U2F(dw1 << 16);
;             float up = par ? U2F(dw1 << 16) : U2F(dw1 & 0xffff0000u);
;             um = (t > 0) ? um : 0.f; up = (t < 4095) ? up : 0.f;
;             const float r = um * w0 + u0 * w1 + up * w2 + bs;
;             if (MODE == 0) { if (b & 1) z[b >> 1][i].y = r; else z[b >> 1][i].x = r; }
;             else { if (b & 1) z[b >> 1][i].y = r * (y[b >> 1][i].y + hb * z[b >> 1][i].y); else z[b >> 1][i].x = r * (y[b >> 1][i].x + hb * z[b >> 1][i].x); }
	v_and_b32_e32 v17, 0xffff0000, v103
	v_and_b32_e32 v19, 0xffff0000, v102
	v_lshlrev_b32_e32 v67, 16, v103
	v_lshlrev_b32_e32 v69, 16, v102
	v_cndmask_b32_e64 v69, v69, v19, s[38:39]
	v_cndmask_b32_e64 v67, v67, v17, s[38:39]
	v_cndmask_b32_e64 v103, 0, v67, s[40:41]
	v_cndmask_b32_e64 v102, 0, v69, s[40:41]
	s_waitcnt lgkmcnt(0)
	v_lshlrev_b32_e32 v67, 16, v104
	v_lshlrev_b32_e32 v69, 16, v105
	v_cndmask_b32_e64 v107, v17, v69, s[38:39]
	v_cndmask_b32_e64 v106, v19, v67, s[38:39]
	v_and_b32_e32 v17, 0xffff0000, v105
	v_cndmask_b32_e64 v17, v69, v17, s[38:39]
	v_cndmask_b32_e64 v105, 0, v17, s[42:43]
	v_pk_add_f32 v[76:77], v[120:121], v[114:115]
	s_waitcnt vmcnt(3)
	v_pk_mul_f32 v[106:107], v[66:67], v[106:107] op_sel_hi:[0,1]
	v_pk_fma_f32 v[102:103], v[18:19], v[102:103], v[106:107] op_sel_hi:[0,1,1]
	v_and_b32_e32 v19, 0xffff0000, v104
	v_cndmask_b32_e64 v19, v67, v19, s[38:39]
	v_cndmask_b32_e64 v104, 0, v19, s[42:43]
	s_waitcnt vmcnt(2)
	v_pk_fma_f32 v[102:103], v[16:17], v[104:105], v[102:103] op_sel_hi:[0,1,1]
	s_waitcnt vmcnt(1)
	v_pk_add_f32 v[102:103], v[68:69], v[102:103] op_sel_hi:[0,1]
	s_waitcnt vmcnt(0)
	v_pk_fma_f32 v[24:25], v[24:25], v[70:71], v[112:113] op_sel_hi:[1,0,1]
	v_pk_fma_f32 v[30:31], v[30:31], v[70:71], v[100:101] op_sel_hi:[1,0,1]
	v_pk_mul_f32 v[24:25], v[24:25], v[102:103]
	ds_read2_b32 v[106:107], v138 offset1:1
	ds_read2_b32 v[108:109], v131 offset1:1
	ds_read2_b32 v[110:111], v135 offset1:1
	ds_read2_b32 v[102:103], v136 offset1:1
	ds_read2_b32 v[104:105], v137 offset1:1
	s_waitcnt lgkmcnt(4)
	v_and_b32_e32 v17, 0xffff0000, v106
	s_waitcnt lgkmcnt(3)
	v_and_b32_e32 v19, 0xffff0000, v108
	v_lshlrev_b32_e32 v67, 16, v106
	v_lshlrev_b32_e32 v69, 16, v108
	v_cndmask_b32_e64 v69, v69, v19, s[38:39]
	v_cndmask_b32_e64 v67, v67, v17, s[38:39]
	v_cndmask_b32_e64 v119, 0, v67, s[44:45]
	v_cndmask_b32_e64 v118, 0, v69, s[44:45]
	v_lshlrev_b32_e32 v67, 16, v109
	v_lshlrev_b32_e32 v69, 16, v107
	v_cndmask_b32_e64 v121, v17, v69, s[38:39]
	v_cndmask_b32_e64 v120, v19, v67, s[38:39]
	ds_read2_b32 v[112:113], v132 offset1:1
	ds_read2_b32 v[114:115], v133 offset1:1
	ds_read2_b32 v[116:117], v134 offset1:1
	v_pk_mul_f32 v[120:121], v[66:67], v[120:121] op_sel_hi:[0,1]
	ds_read2_b32 v[100:101], v139 offset1:1
	v_pk_fma_f32 v[118:119], v[18:19], v[118:119], v[120:121] op_sel_hi:[0,1,1]
	v_and_b32_e32 v17, 0xffff0000, v107
	v_and_b32_e32 v19, 0xffff0000, v109
	v_cndmask_b32_e64 v19, v67, v19, s[38:39]
	v_cndmask_b32_e64 v17, v69, v17, s[38:39]
	v_cndmask_b32_e64 v107, 0, v17, s[46:47]
	v_cndmask_b32_e64 v106, 0, v19, s[46:47]
	v_pk_fma_f32 v[106:107], v[16:17], v[106:107], v[118:119] op_sel_hi:[0,1,1]
	v_pk_add_f32 v[106:107], v[68:69], v[106:107] op_sel_hi:[0,1]
	s_waitcnt lgkmcnt(0)
	v_and_b32_e32 v17, 0xffff0000, v100
	v_and_b32_e32 v19, 0xffff0000, v112
	v_lshlrev_b32_e32 v67, 16, v100
	v_lshlrev_b32_e32 v69, 16, v112
	v_cndmask_b32_e64 v69, v69, v19, s[38:39]
	v_cndmask_b32_e64 v67, v67, v17, s[38:39]
	v_cndmask_b32_e64 v121, 0, v67, s[48:49]
	v_cndmask_b32_e64 v120, 0, v69, s[48:49]
	v_lshlrev_b32_e32 v67, 16, v113
	v_lshlrev_b32_e32 v69, 16, v101
	v_cndmask_b32_e64 v123, v17, v69, s[38:39]
	v_cndmask_b32_e64 v122, v19, v67, s[38:39]
	v_pk_mul_f32 v[122:123], v[66:67], v[122:123] op_sel_hi:[0,1]
	v_pk_fma_f32 v[120:121], v[18:19], v[120:121], v[122:123] op_sel_hi:[0,1,1]
	v_and_b32_e32 v17, 0xffff0000, v101
	v_and_b32_e32 v19, 0xffff0000, v113
	v_pk_mul_f32 v[30:31], v[30:31], v[106:107]
	ds_read2_b32 v[106:107], v140 offset1:1
	ds_read2_b32 v[108:109], v141 offset1:1
	ds_read2_b32 v[118:119], v142 offset1:1
	v_cndmask_b32_e64 v19, v67, v19, s[38:39]
	v_cndmask_b32_e64 v17, v69, v17, s[38:39]
	v_cndmask_b32_e64 v101, 0, v17, s[50:51]
	v_cndmask_b32_e64 v100, 0, v19, s[50:51]
	v_pk_fma_f32 v[100:101], v[16:17], v[100:101], v[120:121] op_sel_hi:[0,1,1]
	v_pk_add_f32 v[100:101], v[68:69], v[100:101] op_sel_hi:[0,1]
	s_waitcnt lgkmcnt(2)
	v_and_b32_e32 v17, 0xffff0000, v106
	v_and_b32_e32 v19, 0xffff0000, v114
	v_lshlrev_b32_e32 v67, 16, v106
	v_lshlrev_b32_e32 v69, 16, v114
	v_cndmask_b32_e64 v69, v69, v19, s[38:39]
	v_cndmask_b32_e64 v67, v67, v17, s[38:39]
	v_pk_fma_f32 v[28:29], v[28:29], v[70:71], v[84:85] op_sel_hi:[1,0,1]
	v_cndmask_b32_e64 v85, 0, v67, s[52:53]
	v_cndmask_b32_e64 v84, 0, v69, s[52:53]
	v_lshlrev_b32_e32 v67, 16, v115
	v_lshlrev_b32_e32 v69, 16, v107
	v_pk_mul_f32 v[28:29], v[28:29], v[100:101]
	v_cndmask_b32_e64 v101, v17, v69, s[38:39]
	v_cndmask_b32_e64 v100, v19, v67, s[38:39]
	v_pk_mul_f32 v[100:101], v[66:67], v[100:101] op_sel_hi:[0,1]
	v_pk_fma_f32 v[84:85], v[18:19], v[84:85], v[100:101] op_sel_hi:[0,1,1]
	v_and_b32_e32 v17, 0xffff0000, v107
	v_and_b32_e32 v19, 0xffff0000, v115
	v_cndmask_b32_e64 v19, v67, v19, s[38:39]
	v_cndmask_b32_e64 v17, v69, v17, s[38:39]
	v_cndmask_b32_e64 v101, 0, v17, s[54:55]
	v_cndmask_b32_e64 v100, 0, v19, s[54:55]
	v_pk_fma_f32 v[84:85], v[16:17], v[100:101], v[84:85] op_sel_hi:[0,1,1]
	v_pk_add_f32 v[84:85], v[68:69], v[84:85] op_sel_hi:[0,1]
	s_waitcnt lgkmcnt(1)
	v_and_b32_e32 v17, 0xffff0000, v108
	v_and_b32_e32 v19, 0xffff0000, v116
	v_lshlrev_b32_e32 v67, 16, v108
	v_lshlrev_b32_e32 v69, 16, v116
	v_cndmask_b32_e64 v69, v69, v19, s[38:39]
	v_cndmask_b32_e64 v67, v67, v17, s[38:39]
	v_pk_fma_f32 v[26:27], v[26:27], v[70:71], v[94:95] op_sel_hi:[1,0,1]
	v_cndmask_b32_e64 v95, 0, v67, s[56:57]
	v_cndmask_b32_e64 v94, 0, v69, s[56:57]
	v_lshlrev_b32_e32 v67, 16, v117
	v_lshlrev_b32_e32 v69, 16, v109
	v_pk_mul_f32 v[26:27], v[26:27], v[84:85]
	v_cndmask_b32_e64 v85, v17, v69, s[38:39]
	v_cndmask_b32_e64 v84, v19, v67, s[38:39]
	v_pk_mul_f32 v[84:85], v[66:67], v[84:85] op_sel_hi:[0,1]
	v_pk_fma_f32 v[94:95], v[18:19], v[94:95], v[84:85] op_sel_hi:[0,1,1]
	v_and_b32_e32 v17, 0xffff0000, v109
	v_and_b32_e32 v19, 0xffff0000, v117
	v_cndmask_b32_e64 v19, v67, v19, s[38:39]
	v_cndmask_b32_e64 v17, v69, v17, s[38:39]
	v_cndmask_b32_e64 v85, 0, v17, s[58:59]
	v_cndmask_b32_e64 v84, 0, v19, s[58:59]
	v_pk_fma_f32 v[94:95], v[16:17], v[84:85], v[94:95] op_sel_hi:[0,1,1]
	v_pk_add_f32 v[94:95], v[68:69], v[94:95] op_sel_hi:[0,1]
	s_waitcnt lgkmcnt(0)
; #define LAS __attribute__((address_space(3)))
; #define U2F(x) __uint_as_float(x)
; template <int MODE> DEV void hyena_conv_rows(const LAS unsigned char* lds, int slot0, float w0, float w1, float w2, float bs, cf (&z)[2][8], const cf (&y)[2][8], float hb, int tid) {
;     ...
;         for (int i = 0; i < 8; ++i) {
;             const int t = tid + 512 * i, par = tid & 1, d0 = (tid >> 1) + par;
;             const LAS unsigned* rw = (const LAS unsigned*)row + d0;
;             const unsigned dw0 = (i == 0) ? rw[d0 > 0 ? -1 : 0] : rw[256 * i - 1], dw1 = rw[256 * i];
;             float um = par ? U2F(dw0 << 16) : U2F(dw0 & 0xffff0000u);
;             const float u0 = par ? U2F(dw0 & 0xffff0000u) : U2F(dw1 << 16);
;             float up = par ? U2F(dw1 << 16) : U2F(dw1 & 0xffff0000u);
;             um = (t > 0) ? um : 0.f; up = (t < 4095) ? up : 0.f;
;             const float r = um * w0 + u0 * w1 + up * w2 + bs;
;             if (MODE == 0) { if (b & 1) z[b >> 1][i].y = r; else z[b >> 1][i].x = r; }
;             else { if (b & 1) z[b >> 1][i].y = r * (y[b >> 1][i].y + hb * z[b >> 1][i].y); else z[b >> 1][i].x = r * (y[b >> 1][i].x + hb * z[b >> 1][i].x); }
	v_and_b32_e32 v17, 0xffff0000, v118
	v_and_b32_e32 v19, 0xffff0000, v110
	v_lshlrev_b32_e32 v67, 16, v118
	v_lshlrev_b32_e32 v69, 16, v110
	v_cndmask_b32_e64 v69, v69, v19, s[38:39]
	v_cndmask_b32_e64 v67, v67, v17, s[38:39]
	v_pk_fma_f32 v[22:23], v[22:23], v[70:71], v[92:93] op_sel_hi:[1,0,1]
	v_cndmask_b32_e64 v93, 0, v67, s[60:61]
	v_cndmask_b32_e64 v92, 0, v69, s[60:61]
	v_lshlrev_b32_e32 v67, 16, v111
	v_lshlrev_b32_e32 v69, 16, v119
	v_pk_mul_f32 v[22:23], v[22:23], v[94:95]
	v_cndmask_b32_e64 v95, v17, v69, s[38:39]
	v_cndmask_b32_e64 v94, v19, v67, s[38:39]
	v_pk_mul_f32 v[94:95], v[66:67], v[94:95] op_sel_hi:[0,1]
	v_pk_fma_f32 v[92:93], v[18:19], v[92:93], v[94:95] op_sel_hi:[0,1,1]
	v_and_b32_e32 v17, 0xffff0000, v119
	v_and_b32_e32 v19, 0xffff0000, v111
	v_cndmask_b32_e64 v19, v67, v19, s[38:39]
	v_cndmask_b32_e64 v17, v69, v17, s[38:39]
	v_cndmask_b32_e64 v95, 0, v17, s[62:63]
	v_cndmask_b32_e64 v94, 0, v19, s[62:63]
	v_pk_fma_f32 v[92:93], v[16:17], v[94:95], v[92:93] op_sel_hi:[0,1,1]
	ds_read2_b32 v[94:95], v143 offset1:1
	v_pk_add_f32 v[92:93], v[68:69], v[92:93] op_sel_hi:[0,1]
	v_and_b32_e32 v19, 0xffff0000, v102
	v_lshlrev_b32_e32 v69, 16, v102
	v_cndmask_b32_e64 v69, v69, v19, s[38:39]
	s_waitcnt lgkmcnt(0)
	v_and_b32_e32 v17, 0xffff0000, v94
	v_lshlrev_b32_e32 v67, 16, v94
	v_cndmask_b32_e64 v67, v67, v17, s[38:39]
	v_cndmask_b32_e64 v101, 0, v67, s[64:65]
	v_cndmask_b32_e64 v100, 0, v69, s[64:65]
	v_lshlrev_b32_e32 v67, 16, v103
	v_lshlrev_b32_e32 v69, 16, v95
	v_cndmask_b32_e64 v107, v17, v69, s[38:39]
	v_cndmask_b32_e64 v106, v19, v67, s[38:39]
	v_pk_mul_f32 v[106:107], v[66:67], v[106:107] op_sel_hi:[0,1]
	v_pk_fma_f32 v[32:33], v[32:33], v[70:71], v[90:91] op_sel_hi:[1,0,1]
	v_pk_fma_f32 v[100:101], v[18:19], v[100:101], v[106:107] op_sel_hi:[0,1,1]
	v_and_b32_e32 v17, 0xffff0000, v95
	v_and_b32_e32 v19, 0xffff0000, v103
	v_pk_mul_f32 v[32:33], v[32:33], v[92:93]
	ds_read2_b32 v[84:85], v144 offset1:1
	ds_read2_b32 v[90:91], v145 offset1:1
	ds_read2_b32 v[92:93], v146 offset1:1
	v_cndmask_b32_e64 v19, v67, v19, s[38:39]
	v_cndmask_b32_e64 v17, v69, v17, s[38:39]
	v_cndmask_b32_e64 v95, 0, v17, s[66:67]
	v_cndmask_b32_e64 v94, 0, v19, s[66:67]
	v_pk_fma_f32 v[94:95], v[16:17], v[94:95], v[100:101] op_sel_hi:[0,1,1]
	v_pk_add_f32 v[94:95], v[68:69], v[94:95] op_sel_hi:[0,1]
	s_waitcnt lgkmcnt(2)
	v_and_b32_e32 v17, 0xffff0000, v84
	v_and_b32_e32 v19, 0xffff0000, v104
	v_lshlrev_b32_e32 v67, 16, v84
	v_lshlrev_b32_e32 v69, 16, v104
	v_cndmask_b32_e64 v69, v69, v19, s[38:39]
	v_cndmask_b32_e64 v67, v67, v17, s[38:39]
	v_pk_fma_f32 v[34:35], v[34:35], v[70:71], v[86:87] op_sel_hi:[1,0,1]
	v_cndmask_b32_e64 v87, 0, v67, s[68:69]
	v_cndmask_b32_e64 v86, 0, v69, s[68:69]
	v_lshlrev_b32_e32 v67, 16, v105
	v_lshlrev_b32_e32 v69, 16, v85
	v_pk_mul_f32 v[34:35], v[34:35], v[94:95]
	v_cndmask_b32_e64 v95, v17, v69, s[38:39]
	v_cndmask_b32_e64 v94, v19, v67, s[38:39]
	v_pk_mul_f32 v[94:95], v[66:67], v[94:95] op_sel_hi:[0,1]
	v_pk_fma_f32 v[86:87], v[18:19], v[86:87], v[94:95] op_sel_hi:[0,1,1]
	v_and_b32_e32 v17, 0xffff0000, v85
	v_and_b32_e32 v19, 0xffff0000, v105
	v_cndmask_b32_e64 v19, v67, v19, s[38:39]
	v_cndmask_b32_e64 v17, v69, v17, s[38:39]
	v_cndmask_b32_e64 v95, 0, v17, s[70:71]
	v_cndmask_b32_e64 v94, 0, v19, s[70:71]
	v_pk_fma_f32 v[86:87], v[16:17], v[94:95], v[86:87] op_sel_hi:[0,1,1]
	ds_read2st64_b32 v[94:95], v130 offset0:64 offset1:96
	v_pk_fma_f32 v[36:37], v[36:37], v[70:71], v[82:83] op_sel_hi:[1,0,1]
	ds_read2st64_b32 v[82:83], v129 offset0:64 offset1:96
	v_pk_add_f32 v[86:87], v[68:69], v[86:87] op_sel_hi:[0,1]
	v_pk_mul_f32 v[36:37], v[36:37], v[86:87]
	s_waitcnt lgkmcnt(1)
	v_and_b32_e32 v17, 0xffff0000, v95
	v_and_b32_e32 v19, 0xffff0000, v94
	v_lshlrev_b32_e32 v67, 16, v95
	v_lshlrev_b32_e32 v69, 16, v94
	v_cndmask_b32_e64 v69, v69, v19, s[38:39]
	v_cndmask_b32_e64 v67, v67, v17, s[38:39]
	v_cndmask_b32_e64 v87, 0, v67, s[40:41]
	v_cndmask_b32_e64 v86, 0, v69, s[40:41]
	s_waitcnt lgkmcnt(0)
	v_lshlrev_b32_e32 v67, 16, v82
	v_lshlrev_b32_e32 v69, 16, v83
	v_cndmask_b32_e64 v95, v17, v69, s[38:39]
	v_cndmask_b32_e64 v94, v19, v67, s[38:39]
	v_pk_mul_f32 v[94:95], v[66:67], v[94:95] op_sel_hi:[0,1]
	v_pk_fma_f32 v[86:87], v[18:19], v[86:87], v[94:95] op_sel_hi:[0,1,1]
	v_and_b32_e32 v17, 0xffff0000, v83
	v_and_b32_e32 v19, 0xffff0000, v82
	v_cndmask_b32_e64 v19, v67, v19, s[38:39]
	v_cndmask_b32_e64 v17, v69, v17, s[38:39]
	v_cndmask_b32_e64 v83, 0, v17, s[42:43]
	v_cndmask_b32_e64 v82, 0, v19, s[42:43]
	v_pk_fma_f32 v[82:83], v[16:17], v[82:83], v[86:87] op_sel_hi:[0,1,1]
	ds_read2_b32 v[86:87], v152 offset1:1
	v_pk_add_f32 v[82:83], v[68:69], v[82:83] op_sel_hi:[0,1]
	v_and_b32_e32 v19, 0xffff0000, v90
	v_lshlrev_b32_e32 v69, 16, v90
	v_cndmask_b32_e64 v69, v69, v19, s[38:39]
	s_waitcnt lgkmcnt(0)
	v_and_b32_e32 v17, 0xffff0000, v86
	v_lshlrev_b32_e32 v67, 16, v86
	v_cndmask_b32_e64 v67, v67, v17, s[38:39]
	v_cndmask_b32_e64 v85, 0, v67, s[44:45]
	v_cndmask_b32_e64 v84, 0, v69, s[44:45]
	v_lshlrev_b32_e32 v67, 16, v91
	v_lshlrev_b32_e32 v69, 16, v87
	v_cndmask_b32_e64 v101, v17, v69, s[38:39]
	v_cndmask_b32_e64 v100, v19, v67, s[38:39]
	v_pk_mul_f32 v[100:101], v[66:67], v[100:101] op_sel_hi:[0,1]
	v_pk_fma_f32 v[38:39], v[38:39], v[70:71], v[96:97] op_sel_hi:[1,0,1]
	v_pk_fma_f32 v[84:85], v[18:19], v[84:85], v[100:101] op_sel_hi:[0,1,1]
	v_and_b32_e32 v17, 0xffff0000, v87
	v_and_b32_e32 v19, 0xffff0000, v91
	v_pk_mul_f32 v[38:39], v[38:39], v[82:83]
	ds_read2_b32 v[82:83], v153 offset1:1
	ds_read2_b32 v[94:95], v154 offset1:1
	ds_read2_b32 v[96:97], v151 offset1:1
	v_cndmask_b32_e64 v19, v67, v19, s[38:39]
	v_cndmask_b32_e64 v17, v69, v17, s[38:39]
	v_cndmask_b32_e64 v87, 0, v17, s[46:47]
	v_cndmask_b32_e64 v86, 0, v19, s[46:47]
	v_pk_fma_f32 v[86:87], v[16:17], v[86:87], v[84:85] op_sel_hi:[0,1,1]
	v_pk_add_f32 v[86:87], v[68:69], v[86:87] op_sel_hi:[0,1]
	s_waitcnt lgkmcnt(2)
; #define LAS __attribute__((address_space(3)))
; #define U2F(x) __uint_as_float(x)
; template <int MODE> DEV void hyena_conv_rows(const LAS unsigned char* lds, int slot0, float w0, float w1, float w2, float bs, cf (&z)[2][8], const cf (&y)[2][8], float hb, int tid) {
;     ...
;         for (int i = 0; i < 8; ++i) {
;             const int t = tid + 512 * i, par = tid & 1, d0 = (tid >> 1) + par;
;             const LAS unsigned* rw = (const LAS unsigned*)row + d0;
;             const unsigned dw0 = (i == 0) ? rw[d0 > 0 ? -1 : 0] : rw[256 * i - 1], dw1 = rw[256 * i];
;             float um = par ? U2F(dw0 << 16) : U2F(dw0 & 0xffff0000u);
;             const float u0 = par ? U2F(dw0 & 0xffff0000u) : U2F(dw1 << 16);
;             float up = par ? U2F(dw1 << 16) : U2F(dw1 & 0xffff0000u);
;             um = (t > 0) ? um : 0.f; up = (t < 4095) ? up : 0.f;
;             const float r = um * w0 + u0 * w1 + up * w2 + bs;
;             if (MODE == 0) { if (b & 1) z[b >> 1][i].y = r; else z[b >> 1][i].x = r; }
;             else { if (b & 1) z[b >> 1][i].y = r * (y[b >> 1][i].y + hb * z[b >> 1][i].y); else z[b >> 1][i].x = r * (y[b >> 1][i].x + hb * z[b >> 1][i].x); }
	v_and_b32_e32 v17, 0xffff0000, v82
	v_and_b32_e32 v19, 0xffff0000, v92
	v_lshlrev_b32_e32 v67, 16, v82
	v_lshlrev_b32_e32 v69, 16, v92
	v_pk_fma_f32 v[42:43], v[42:43], v[70:71], v[88:89] op_sel_hi:[1,0,1]
	v_cndmask_b32_e64 v69, v69, v19, s[38:39]
	v_cndmask_b32_e64 v67, v67, v17, s[38:39]
	v_pk_mul_f32 v[42:43], v[42:43], v[86:87]
	v_cndmask_b32_e64 v87, 0, v67, s[48:49]
	v_cndmask_b32_e64 v86, 0, v69, s[48:49]
	v_lshlrev_b32_e32 v67, 16, v93
	v_lshlrev_b32_e32 v69, 16, v83
	v_cndmask_b32_e64 v89, v17, v69, s[38:39]
	v_cndmask_b32_e64 v88, v19, v67, s[38:39]
	v_pk_mul_f32 v[88:89], v[66:67], v[88:89] op_sel_hi:[0,1]
	v_pk_fma_f32 v[86:87], v[18:19], v[86:87], v[88:89] op_sel_hi:[0,1,1]
	v_and_b32_e32 v17, 0xffff0000, v83
	v_and_b32_e32 v19, 0xffff0000, v93
	v_cndmask_b32_e64 v19, v67, v19, s[38:39]
	v_cndmask_b32_e64 v17, v69, v17, s[38:39]
	v_cndmask_b32_e64 v83, 0, v17, s[50:51]
	v_cndmask_b32_e64 v82, 0, v19, s[50:51]
	v_pk_fma_f32 v[82:83], v[16:17], v[82:83], v[86:87] op_sel_hi:[0,1,1]
	v_pk_add_f32 v[82:83], v[68:69], v[82:83] op_sel_hi:[0,1]
	v_pk_fma_f32 v[44:45], v[44:45], v[70:71], v[98:99] op_sel_hi:[1,0,1]
	s_waitcnt lgkmcnt(1)
	v_and_b32_e32 v17, 0xffff0000, v94
	v_pk_mul_f32 v[44:45], v[44:45], v[82:83]
	ds_read2_b32 v[82:83], v147 offset1:1
	v_lshlrev_b32_e32 v67, 16, v94
	v_cndmask_b32_e64 v67, v67, v17, s[38:39]
	v_cndmask_b32_e64 v91, 0, v67, s[52:53]
	ds_read2_b32 v[84:85], v148 offset1:1
	ds_read2_b32 v[86:87], v149 offset1:1
	ds_read2_b32 v[88:89], v150 offset1:1
	s_waitcnt lgkmcnt(3)
	v_and_b32_e32 v19, 0xffff0000, v82
	v_lshlrev_b32_e32 v69, 16, v82
	v_cndmask_b32_e64 v69, v69, v19, s[38:39]
	v_cndmask_b32_e64 v90, 0, v69, s[52:53]
	v_lshlrev_b32_e32 v67, 16, v83
	v_lshlrev_b32_e32 v69, 16, v95
	v_cndmask_b32_e64 v93, v17, v69, s[38:39]
	v_cndmask_b32_e64 v92, v19, v67, s[38:39]
	v_pk_mul_f32 v[92:93], v[66:67], v[92:93] op_sel_hi:[0,1]
	v_pk_fma_f32 v[50:51], v[50:51], v[70:71], v[80:81] op_sel_hi:[1,0,1]
	ds_read2_b32 v[80:81], v155 offset1:1
	v_pk_fma_f32 v[90:91], v[18:19], v[90:91], v[92:93] op_sel_hi:[0,1,1]
	v_and_b32_e32 v17, 0xffff0000, v95
	v_and_b32_e32 v19, 0xffff0000, v83
	v_cndmask_b32_e64 v19, v67, v19, s[38:39]
	v_cndmask_b32_e64 v17, v69, v17, s[38:39]
	v_cndmask_b32_e64 v83, 0, v17, s[54:55]
	v_cndmask_b32_e64 v82, 0, v19, s[54:55]
	v_pk_fma_f32 v[82:83], v[16:17], v[82:83], v[90:91] op_sel_hi:[0,1,1]
	v_pk_add_f32 v[82:83], v[68:69], v[82:83] op_sel_hi:[0,1]
	s_waitcnt lgkmcnt(0)
	v_and_b32_e32 v17, 0xffff0000, v80
	v_and_b32_e32 v19, 0xffff0000, v84
	v_lshlrev_b32_e32 v67, 16, v80
	v_lshlrev_b32_e32 v69, 16, v84
	v_cndmask_b32_e64 v69, v69, v19, s[38:39]
	v_cndmask_b32_e64 v67, v67, v17, s[38:39]
	v_cndmask_b32_e64 v95, 0, v67, s[56:57]
	v_cndmask_b32_e64 v94, 0, v69, s[56:57]
	v_lshlrev_b32_e32 v67, 16, v85
	v_lshlrev_b32_e32 v69, 16, v81
	v_cndmask_b32_e64 v99, v17, v69, s[38:39]
	v_cndmask_b32_e64 v98, v19, v67, s[38:39]
	v_pk_mul_f32 v[98:99], v[66:67], v[98:99] op_sel_hi:[0,1]
	v_pk_fma_f32 v[94:95], v[18:19], v[94:95], v[98:99] op_sel_hi:[0,1,1]
	v_and_b32_e32 v17, 0xffff0000, v81
	v_and_b32_e32 v19, 0xffff0000, v85
	v_pk_mul_f32 v[50:51], v[50:51], v[82:83]
	ds_read2_b32 v[82:83], v156 offset1:1
	ds_read2_b32 v[90:91], v157 offset1:1
	ds_read2_b32 v[92:93], v158 offset1:1
	v_cndmask_b32_e64 v19, v67, v19, s[38:39]
	v_cndmask_b32_e64 v17, v69, v17, s[38:39]
	v_cndmask_b32_e64 v81, 0, v17, s[58:59]
	v_cndmask_b32_e64 v80, 0, v19, s[58:59]
	v_pk_fma_f32 v[80:81], v[16:17], v[80:81], v[94:95] op_sel_hi:[0,1,1]
	v_pk_add_f32 v[80:81], v[68:69], v[80:81] op_sel_hi:[0,1]
	s_waitcnt lgkmcnt(2)
	v_and_b32_e32 v17, 0xffff0000, v82
	v_and_b32_e32 v19, 0xffff0000, v86
	v_lshlrev_b32_e32 v67, 16, v82
	v_lshlrev_b32_e32 v69, 16, v86
	v_cndmask_b32_e64 v69, v69, v19, s[38:39]
	v_cndmask_b32_e64 v67, v67, v17, s[38:39]
	v_pk_fma_f32 v[46:47], v[46:47], v[70:71], v[78:79] op_sel_hi:[1,0,1]
	v_cndmask_b32_e64 v79, 0, v67, s[60:61]
	v_cndmask_b32_e64 v78, 0, v69, s[60:61]
	v_lshlrev_b32_e32 v67, 16, v87
	v_lshlrev_b32_e32 v69, 16, v83
	v_pk_mul_f32 v[46:47], v[46:47], v[80:81]
	v_cndmask_b32_e64 v81, v17, v69, s[38:39]
	v_cndmask_b32_e64 v80, v19, v67, s[38:39]
	v_pk_mul_f32 v[80:81], v[66:67], v[80:81] op_sel_hi:[0,1]
	v_pk_fma_f32 v[78:79], v[18:19], v[78:79], v[80:81] op_sel_hi:[0,1,1]
	v_and_b32_e32 v17, 0xffff0000, v83
	v_and_b32_e32 v19, 0xffff0000, v87
	v_cndmask_b32_e64 v19, v67, v19, s[38:39]
	v_cndmask_b32_e64 v17, v69, v17, s[38:39]
	v_cndmask_b32_e64 v81, 0, v17, s[62:63]
	v_cndmask_b32_e64 v80, 0, v19, s[62:63]
	v_pk_fma_f32 v[78:79], v[16:17], v[80:81], v[78:79] op_sel_hi:[0,1,1]
	v_pk_add_f32 v[78:79], v[68:69], v[78:79] op_sel_hi:[0,1]
	s_waitcnt lgkmcnt(1)
	v_and_b32_e32 v17, 0xffff0000, v90
	v_and_b32_e32 v19, 0xffff0000, v88
	v_lshlrev_b32_e32 v67, 16, v90
	v_lshlrev_b32_e32 v69, 16, v88
	v_cndmask_b32_e64 v69, v69, v19, s[38:39]
	v_cndmask_b32_e64 v67, v67, v17, s[38:39]
	v_pk_fma_f32 v[48:49], v[48:49], v[70:71], v[76:77] op_sel_hi:[1,0,1]
	v_cndmask_b32_e64 v77, 0, v67, s[64:65]
	v_cndmask_b32_e64 v76, 0, v69, s[64:65]
	v_lshlrev_b32_e32 v67, 16, v89
	v_lshlrev_b32_e32 v69, 16, v91
	v_pk_mul_f32 v[48:49], v[48:49], v[78:79]
	v_cndmask_b32_e64 v79, v17, v69, s[38:39]
	v_cndmask_b32_e64 v78, v19, v67, s[38:39]
	v_pk_mul_f32 v[78:79], v[66:67], v[78:79] op_sel_hi:[0,1]
	v_pk_fma_f32 v[76:77], v[18:19], v[76:77], v[78:79] op_sel_hi:[0,1,1]
	v_and_b32_e32 v17, 0xffff0000, v91
	v_and_b32_e32 v19, 0xffff0000, v89
	v_cndmask_b32_e64 v19, v67, v19, s[38:39]
	v_cndmask_b32_e64 v17, v69, v17, s[38:39]
	v_cndmask_b32_e64 v79, 0, v17, s[66:67]
	v_cndmask_b32_e64 v78, 0, v19, s[66:67]
	v_pk_fma_f32 v[76:77], v[16:17], v[78:79], v[76:77] op_sel_hi:[0,1,1]
	v_pk_add_f32 v[76:77], v[68:69], v[76:77] op_sel_hi:[0,1]
	v_and_b32_e32 v19, 0xffff0000, v96
	v_lshlrev_b32_e32 v69, 16, v96
	v_cndmask_b32_e64 v69, v69, v19, s[38:39]
	v_pk_fma_f32 v[52:53], v[52:53], v[70:71], v[74:75] op_sel_hi:[1,0,1]
	s_waitcnt lgkmcnt(0)
; #define U2F(x) __uint_as_float(x)
; DEV void fft_f1x2(LAS cf* buf0, LAS cf* buf1, const cf (&z0)[8], const cf (&z1)[8], int tid) {
;     ...
;     cf v[16], u[16];
; #pragma unroll
;     for (int q = 0; q < 8; ++q) { v[q] = z0[q]; v[q + 8] = cf{0.f, 0.f}; u[q] = z1[q]; u[q + 8] = cf{0.f, 0.f}; }
;     dft_regs<16, false>(v); dft_regs<16, false>(u);
; template <int MODE> DEV void hyena_conv_rows(const LAS unsigned char* lds, int slot0, float w0, float w1, float w2, float bs, cf (&z)[2][8], const cf (&y)[2][8], float hb, int tid) {
;     ...
;             float um = par ? U2F(dw0 << 16) : U2F(dw0 & 0xffff0000u);
;             const float u0 = par ? U2F(dw0 & 0xffff0000u) : U2F(dw1 << 16);
;             float up = par ? U2F(dw1 << 16) : U2F(dw1 & 0xffff0000u);
;             um = (t > 0) ? um : 0.f; up = (t < 4095) ? up : 0.f;
;             const float r = um * w0 + u0 * w1 + up * w2 + bs;
;             if (MODE == 0) { if (b & 1) z[b >> 1][i].y = r; else z[b >> 1][i].x = r; }
;             else { if (b & 1) z[b >> 1][i].y = r * (y[b >> 1][i].y + hb * z[b >> 1][i].y); else z[b >> 1][i].x = r * (y[b >> 1][i].x + hb * z[b >> 1][i].x); }
	v_and_b32_e32 v17, 0xffff0000, v92
	v_lshlrev_b32_e32 v67, 16, v92
	v_cndmask_b32_e64 v74, 0, v69, s[68:69]
	v_lshlrev_b32_e32 v69, 16, v97
	v_lshlrev_b32_e32 v71, 16, v93
	v_pk_mul_f32 v[52:53], v[52:53], v[76:77]
	v_cndmask_b32_e64 v67, v67, v17, s[38:39]
	v_cndmask_b32_e64 v77, v17, v71, s[38:39]
	v_cndmask_b32_e64 v76, v19, v69, s[38:39]
	v_cndmask_b32_e64 v75, 0, v67, s[68:69]
	v_pk_mul_f32 v[66:67], v[66:67], v[76:77] op_sel_hi:[0,1]
	v_pk_fma_f32 v[18:19], v[18:19], v[74:75], v[66:67] op_sel_hi:[0,1,1]
	v_and_b32_e32 v17, 0xffff0000, v93
	v_and_b32_e32 v66, 0xffff0000, v97
	v_cndmask_b32_e64 v66, v69, v66, s[38:39]
	v_cndmask_b32_e64 v17, v71, v17, s[38:39]
	v_cndmask_b32_e64 v67, 0, v17, s[70:71]
	v_cndmask_b32_e64 v66, 0, v66, s[70:71]
	v_pk_add_f32 v[72:73], v[126:127], v[166:167]
	v_pk_fma_f32 v[16:17], v[16:17], v[66:67], v[18:19] op_sel_hi:[0,1,1]
	v_pk_add_f32 v[16:17], v[68:69], v[16:17] op_sel_hi:[0,1]
	v_pk_fma_f32 v[18:19], v[40:41], v[70:71], v[72:73] op_sel_hi:[1,0,1]
	s_mov_b64 s[22:23], 0
	v_pk_mul_f32 v[40:41], v[18:19], v[16:17]
	s_and_b64 vcc, exec, s[2:3]
	s_barrier
	s_cbranch_vccnz .LBB0_522
.LBB0_519:
	v_pk_mul_f32 v[16:17], v[26:27], s[16:17] op_sel_hi:[1,0]
	v_pk_add_f32 v[0:1], v[24:25], 0 op_sel_hi:[1,0]
	v_pk_fma_f32 v[18:19], v[26:27], s[84:85], v[16:17] op_sel:[0,0,1] op_sel_hi:[1,0,0] neg_hi:[0,0,1]
	v_pk_add_f32 v[16:17], v[22:23], 0 op_sel_hi:[1,0]
	v_mov_b32_e32 v4, v24
	v_mov_b32_e32 v5, v25
	v_pk_add_f32 v[80:81], v[0:1], v[16:17]
	v_pk_add_f32 v[0:1], v[0:1], v[16:17] neg_lo:[0,1] neg_hi:[0,1]
	v_pk_fma_f32 v[66:67], v[22:23], 0, v[22:23] op_sel:[0,0,1] op_sel_hi:[1,0,0] neg_hi:[0,0,1]
	v_mov_b32_e32 v5, v25
	v_pk_add_f32 v[2:3], v[30:31], 0 op_sel_hi:[1,0]
	v_pk_mul_f32 v[6:7], v[30:31], s[84:85] op_sel_hi:[1,0]
	v_pk_add_f32 v[68:69], v[32:33], 0 op_sel_hi:[1,0]
	v_pk_fma_f32 v[8:9], v[30:31], s[16:17], v[6:7] op_sel:[0,0,1] op_sel_hi:[1,0,0] neg_hi:[0,0,1]
	v_pk_add_f32 v[82:83], v[2:3], v[68:69]
	v_pk_add_f32 v[2:3], v[2:3], v[68:69] neg_lo:[0,1] neg_hi:[0,1]
	v_pk_add_f32 v[6:7], v[28:29], 0 op_sel_hi:[1,0]
	v_pk_add_f32 v[72:73], v[34:35], 0 op_sel_hi:[1,0]
	v_pk_mul_f32 v[16:17], v[2:3], s[18:19] op_sel_hi:[1,0]
	v_pk_mul_f32 v[10:11], v[28:29], s[18:19] op_sel_hi:[1,0]
	v_pk_fma_f32 v[68:69], v[2:3], s[18:19], v[16:17] op_sel:[0,0,1] op_sel_hi:[1,0,0]
	v_pk_fma_f32 v[2:3], v[2:3], s[18:19], v[16:17] op_sel_hi:[1,0,0] neg_lo:[0,0,1] neg_hi:[0,0,1]
	v_pk_add_f32 v[16:17], v[6:7], v[72:73]
	v_pk_add_f32 v[6:7], v[6:7], v[72:73] neg_lo:[0,1] neg_hi:[0,1]
	v_pk_add_f32 v[14:15], v[26:27], 0 op_sel_hi:[1,0]
	v_pk_add_f32 v[76:77], v[36:37], 0 op_sel_hi:[1,0]
	v_pk_add_f32 v[72:73], v[6:7], 0 op_sel:[1,0] op_sel_hi:[0,0] neg_hi:[1,0]
	v_pk_fma_f32 v[12:13], v[28:29], s[18:19], v[10:11] op_sel:[0,0,1] op_sel_hi:[1,0,0]
	v_pk_fma_f32 v[10:11], v[28:29], s[18:19], v[10:11] op_sel_hi:[1,0,0] neg_lo:[0,0,1] neg_hi:[0,0,1]
	v_pk_add_f32 v[6:7], v[14:15], v[76:77]
	v_pk_add_f32 v[14:15], v[14:15], v[76:77] neg_lo:[0,1] neg_hi:[0,1]
	v_pk_add_f32 v[76:77], v[4:5], v[66:67]
	v_pk_add_f32 v[4:5], v[4:5], v[66:67] neg_lo:[0,1] neg_hi:[0,1]
	v_mov_b32_e32 v10, v33
	s_mov_b32 s30, s85
	s_mov_b32 s31, s0
	v_pk_mul_f32 v[70:71], v[32:33], s[84:85] op_sel_hi:[0,1]
	v_pk_fma_f32 v[70:71], v[10:11], s[30:31], v[70:71] op_sel_hi:[0,1,1] neg_lo:[0,0,1] neg_hi:[0,0,1]
	v_mul_f32_e32 v10, 0x3f3504f3, v34
	v_mov_b32_e32 v74, v35
	s_mov_b32 s28, s97
	s_mov_b32 s29, s96
	s_mov_b32 s24, s85
	s_mov_b32 s25, s84
	v_pk_add_f32 v[84:85], v[8:9], v[70:71]
	v_pk_add_f32 v[8:9], v[8:9], v[70:71] neg_lo:[0,1] neg_hi:[0,1]
	v_pk_fma_f32 v[74:75], v[74:75], s[28:29], v[10:11] op_sel_hi:[0,1,0] neg_lo:[0,0,1] neg_hi:[0,0,1]
	v_mov_b32_e32 v10, v37
	s_mov_b32 s34, s84
	s_mov_b32 s35, s88
	v_pk_mul_f32 v[78:79], v[36:37], s[24:25] op_sel_hi:[0,1]
	v_pk_mul_f32 v[66:67], v[8:9], s[18:19] op_sel_hi:[1,0]
	v_mov_b32_e32 v13, v11
	v_pk_fma_f32 v[78:79], v[10:11], s[34:35], v[78:79] op_sel_hi:[0,1,1] neg_lo:[0,0,1] neg_hi:[0,0,1]
	v_pk_fma_f32 v[70:71], v[8:9], s[18:19], v[66:67] op_sel:[0,0,1] op_sel_hi:[1,0,0] neg_hi:[0,0,1]
	v_pk_add_f32 v[10:11], v[12:13], v[74:75] neg_lo:[0,1] neg_hi:[0,1]
	v_pk_add_f32 v[66:67], v[80:81], v[16:17]
	v_pk_add_f32 v[16:17], v[80:81], v[16:17] neg_lo:[0,1] neg_hi:[0,1]
	v_pk_add_f32 v[8:9], v[12:13], v[74:75]
	v_pk_add_f32 v[12:13], v[10:11], 0 op_sel:[1,0] op_sel_hi:[0,0] neg_hi:[1,0]
	v_pk_add_f32 v[10:11], v[18:19], v[78:79]
	v_pk_add_f32 v[18:19], v[18:19], v[78:79] neg_lo:[0,1] neg_hi:[0,1]
	v_mul_f32_e32 v2, 0x3f3504f3, v14
	v_pk_add_f32 v[78:79], v[82:83], v[6:7]
	v_pk_add_f32 v[82:83], v[82:83], v[6:7] neg_lo:[0,1] neg_hi:[0,1]
	v_pk_add_f32 v[74:75], v[0:1], v[72:73]
	v_pk_add_f32 v[6:7], v[82:83], 0 op_sel:[1,0] op_sel_hi:[0,0] neg_hi:[1,0]
	v_pk_fma_f32 v[14:15], v[14:15], s[28:29], v[2:3] op_sel:[1,0,0] op_sel_hi:[1,1,0] neg_lo:[0,0,1] neg_hi:[0,0,1]
	v_pk_add_f32 v[82:83], v[0:1], v[72:73] neg_lo:[0,1] neg_hi:[0,1]
	v_mov_b32_e32 v69, v3
	v_mul_f32_e32 v2, 0x3f3504f3, v18
	v_mov_b32_e32 v80, v82
	v_mov_b32_e32 v81, v83
	v_pk_fma_f32 v[18:19], v[18:19], s[28:29], v[2:3] op_sel:[1,0,0] op_sel_hi:[1,1,0] neg_lo:[0,0,1] neg_hi:[0,0,1]
	v_pk_add_f32 v[0:1], v[68:69], v[14:15] neg_lo:[0,1] neg_hi:[0,1]
	v_pk_add_f32 v[2:3], v[68:69], v[14:15]
	v_pk_add_f32 v[14:15], v[0:1], 0 op_sel:[1,0] op_sel_hi:[0,0] neg_hi:[1,0]
	v_pk_add_f32 v[72:73], v[76:77], v[8:9]
	v_pk_add_f32 v[0:1], v[76:77], v[8:9] neg_lo:[0,1] neg_hi:[0,1]
	v_pk_add_f32 v[86:87], v[4:5], v[12:13]
	v_pk_add_f32 v[68:69], v[66:67], v[78:79]
	v_pk_add_f32 v[8:9], v[84:85], v[10:11]
	v_pk_add_f32 v[82:83], v[84:85], v[10:11] neg_lo:[0,1] neg_hi:[0,1]
; DEV void fft_f1x2(LAS cf* buf0, LAS cf* buf1, const cf (&z0)[8], const cf (&z1)[8], int tid) {
;     ...
;     cf v[16], u[16];
; #pragma unroll
;     for (int q = 0; q < 8; ++q) { v[q] = z0[q]; v[q + 8] = cf{0.f, 0.f}; u[q] = z1[q]; u[q + 8] = cf{0.f, 0.f}; }
;     dft_regs<16, false>(v); dft_regs<16, false>(u);
; DEV void fft_midx2(LAS cf* buf0, LAS cf* buf1, const unsigned* Kp, int blk) {
;     ...
;     for (int j = 0; j < 4; ++j) kw[j] = *(const u32x4*)(Kp + base + 4 * j);
	v_pk_add_f32 v[88:89], v[70:71], v[18:19]
	v_pk_add_f32 v[10:11], v[82:83], 0 op_sel:[1,0] op_sel_hi:[0,0] neg_hi:[1,0]
	v_pk_add_f32 v[76:77], v[72:73], v[8:9]
	v_pk_add_f32 v[82:83], v[4:5], v[12:13] neg_lo:[0,1] neg_hi:[0,1]
	v_pk_add_f32 v[8:9], v[72:73], v[8:9] neg_lo:[0,1] neg_hi:[0,1]
	v_pk_add_f32 v[72:73], v[0:1], v[10:11]
	v_mov_b32_e32 v4, v82
	v_mov_b32_e32 v5, v83
	v_pk_add_f32 v[10:11], v[0:1], v[10:11] neg_lo:[0,1] neg_hi:[0,1]
	v_pk_add_f32 v[0:1], v[70:71], v[18:19] neg_lo:[0,1] neg_hi:[0,1]
	v_pk_add_f32 v[70:71], v[74:75], v[2:3]
	v_pk_add_f32 v[90:91], v[0:1], 0 op_sel:[1,0] op_sel_hi:[0,0] neg_hi:[1,0]
	v_pk_add_f32 v[2:3], v[74:75], v[2:3] neg_lo:[0,1] neg_hi:[0,1]
	v_pk_add_f32 v[0:1], v[66:67], v[78:79] neg_lo:[0,1] neg_hi:[0,1]
	v_pk_add_f32 v[78:79], v[16:17], v[6:7]
	v_pk_add_f32 v[6:7], v[16:17], v[6:7] neg_lo:[0,1] neg_hi:[0,1]
	v_mov_b32_e32 v84, v0
	v_mov_b32_e32 v85, v1
	v_mov_b32_e32 v0, v6
	v_mov_b32_e32 v1, v7
	v_mov_b32_e32 v6, v2
	v_mov_b32_e32 v7, v3
	v_pk_add_f32 v[12:13], v[80:81], v[14:15] neg_lo:[0,1] neg_hi:[0,1]
	v_pk_add_f32 v[18:19], v[80:81], v[14:15]
	v_mov_b32_e32 v2, v12
	v_mov_b32_e32 v3, v13
	v_mov_b32_e32 v12, v8
	v_mov_b32_e32 v13, v9
	v_mov_b32_e32 v8, v10
	v_mov_b32_e32 v9, v11
	v_pk_mul_f32 v[92:93], v[50:51], s[16:17] op_sel_hi:[1,0]
	v_pk_add_f32 v[10:11], v[86:87], v[88:89] neg_lo:[0,1] neg_hi:[0,1]
	v_pk_fma_f32 v[94:95], v[50:51], s[84:85], v[92:93] op_sel:[0,0,1] op_sel_hi:[1,0,0] neg_hi:[0,0,1]
	v_mov_b32_e32 v14, v10
	v_mov_b32_e32 v15, v11
	v_pk_add_f32 v[66:67], v[4:5], v[90:91] neg_lo:[0,1] neg_hi:[0,1]
	v_mov_b32_e32 v10, v66
	v_mov_b32_e32 v11, v67
	v_pk_add_f32 v[92:93], v[46:47], 0 op_sel_hi:[1,0]
	v_pk_add_f32 v[66:67], v[38:39], 0 op_sel_hi:[1,0]
	v_mov_b32_e32 v108, v41
	v_pk_mul_f32 v[110:111], v[40:41], s[24:25] op_sel_hi:[0,1]
	v_pk_fma_f32 v[108:109], v[108:109], s[34:35], v[110:111] op_sel_hi:[0,1,1] neg_lo:[0,0,1] neg_hi:[0,0,1]
	v_pk_add_f32 v[110:111], v[66:67], v[92:93]
	v_pk_add_f32 v[66:67], v[66:67], v[92:93] neg_lo:[0,1] neg_hi:[0,1]
	v_mov_b32_e32 v82, v38
	v_mov_b32_e32 v83, v39
	v_pk_fma_f32 v[96:97], v[46:47], 0, v[46:47] op_sel:[0,0,1] op_sel_hi:[1,0,0] neg_hi:[0,0,1]
	v_mov_b32_e32 v83, v39
	v_pk_add_f32 v[80:81], v[42:43], 0 op_sel_hi:[1,0]
	v_pk_add_f32 v[98:99], v[48:49], 0 op_sel_hi:[1,0]
	v_mov_b32_e32 v112, v66
	v_mov_b32_e32 v113, v67
	v_pk_add_f32 v[74:75], v[4:5], v[90:91]
	v_pk_mul_f32 v[4:5], v[42:43], s[84:85] op_sel_hi:[1,0]
	v_pk_add_f32 v[66:67], v[80:81], v[98:99]
	v_pk_add_f32 v[80:81], v[80:81], v[98:99] neg_lo:[0,1] neg_hi:[0,1]
	v_pk_add_f32 v[16:17], v[86:87], v[88:89]
	v_pk_fma_f32 v[86:87], v[42:43], s[16:17], v[4:5] op_sel:[0,0,1] op_sel_hi:[1,0,0] neg_hi:[0,0,1]
	v_mov_b32_e32 v100, v49
	v_pk_mul_f32 v[102:103], v[48:49], s[84:85] op_sel_hi:[0,1]
	v_pk_mul_f32 v[92:93], v[80:81], s[18:19] op_sel_hi:[1,0]
	v_pk_add_f32 v[4:5], v[44:45], 0 op_sel_hi:[1,0]
	v_pk_mul_f32 v[88:89], v[44:45], s[18:19] op_sel_hi:[1,0]
	v_pk_fma_f32 v[100:101], v[100:101], s[30:31], v[102:103] op_sel_hi:[0,1,1] neg_lo:[0,0,1] neg_hi:[0,0,1]
	v_pk_add_f32 v[102:103], v[52:53], 0 op_sel_hi:[1,0]
	v_pk_fma_f32 v[98:99], v[80:81], s[18:19], v[92:93] op_sel:[0,0,1] op_sel_hi:[1,0,0] neg_hi:[0,0,1]
	v_pk_fma_f32 v[90:91], v[44:45], s[18:19], v[88:89] op_sel:[0,0,1] op_sel_hi:[1,0,0] neg_hi:[0,0,1]
	v_mul_f32_e32 v104, 0x3f3504f3, v52
	v_mov_b32_e32 v106, v53
	v_pk_add_f32 v[80:81], v[4:5], v[102:103]
	v_pk_add_f32 v[4:5], v[4:5], v[102:103] neg_lo:[0,1] neg_hi:[0,1]
	v_pk_add_f32 v[88:89], v[50:51], 0 op_sel_hi:[1,0]
	v_pk_fma_f32 v[104:105], v[106:107], s[28:29], v[104:105] op_sel_hi:[0,1,0] neg_lo:[0,0,1] neg_hi:[0,0,1]
	v_pk_add_f32 v[106:107], v[40:41], 0 op_sel_hi:[1,0]
	v_pk_add_f32 v[92:93], v[4:5], 0 op_sel:[1,0] op_sel_hi:[0,0] neg_hi:[1,0]
	v_mov_b32_e32 v114, v21
	v_pk_add_f32 v[4:5], v[88:89], v[106:107]
	v_pk_add_f32 v[88:89], v[88:89], v[106:107] neg_lo:[0,1] neg_hi:[0,1]
	s_mov_b32 s2, s86
	v_mul_f32_e32 v102, 0x3f3504f3, v88
	v_pk_fma_f32 v[88:89], v[88:89], s[28:29], v[102:103] op_sel:[1,0,0] op_sel_hi:[1,1,0] neg_lo:[0,0,1] neg_hi:[0,0,1]
	v_pk_add_f32 v[102:103], v[82:83], v[96:97]
	v_pk_add_f32 v[82:83], v[82:83], v[96:97] neg_lo:[0,1] neg_hi:[0,1]
	s_mov_b32 s3, s4
	s_mov_b32 s10, s4
	s_mov_b32 s6, s94
	v_pk_add_f32 v[106:107], v[86:87], v[100:101]
	v_pk_add_f32 v[86:87], v[86:87], v[100:101] neg_lo:[0,1] neg_hi:[0,1]
	s_mov_b32 s7, s82
	v_pk_mul_f32 v[96:97], v[86:87], s[18:19] op_sel_hi:[1,0]
	s_mov_b32 s8, s82
	v_pk_fma_f32 v[100:101], v[86:87], s[18:19], v[96:97] op_sel:[0,0,1] op_sel_hi:[1,0,0] neg_hi:[0,0,1]
	s_lshl_b32 s92, s19, 13
	v_lshl_add_u64 v[232:233], s[92:93], 2, v[54:55]
	global_load_dwordx4 v[170:173], v[232:233], off offset:48
	global_load_dwordx4 v[174:177], v[232:233], off offset:32
	global_load_dwordx4 v[178:181], v[232:233], off offset:16
	global_load_dwordx4 v[182:185], v[232:233], off
	v_pk_add_f32 v[86:87], v[90:91], v[104:105]
	v_pk_add_f32 v[90:91], v[90:91], v[104:105] neg_lo:[0,1] neg_hi:[0,1]
	s_mov_b32 s1, s85
	v_pk_add_f32 v[96:97], v[90:91], 0 op_sel:[1,0] op_sel_hi:[0,0] neg_hi:[1,0]
	s_mov_b32 s89, s84
	v_pk_add_f32 v[90:91], v[94:95], v[108:109]
	v_pk_add_f32 v[94:95], v[94:95], v[108:109] neg_lo:[0,1] neg_hi:[0,1]
	v_mul_f32_e32 v104, 0x3f3504f3, v94
	v_pk_fma_f32 v[94:95], v[94:95], s[28:29], v[104:105] op_sel:[1,0,0] op_sel_hi:[1,1,0] neg_lo:[0,0,1] neg_hi:[0,0,1]
	v_pk_add_f32 v[104:105], v[110:111], v[80:81]
	v_pk_add_f32 v[80:81], v[110:111], v[80:81] neg_lo:[0,1] neg_hi:[0,1]
	v_pk_add_f32 v[110:111], v[66:67], v[4:5]
	v_pk_add_f32 v[66:67], v[66:67], v[4:5] neg_lo:[0,1] neg_hi:[0,1]
; #define LAS __attribute__((address_space(3)))
; #define SINCOSPI(x, s, c) do { const float hx_ = 0.5f * (x); *(s) = __builtin_amdgcn_sinf(hx_); *(c) = __builtin_amdgcn_cosf(hx_); } while (0)
; DEV void fft_f1x2(LAS cf* buf0, LAS cf* buf1, const cf (&z0)[8], const cf (&z1)[8], int tid) {
;     ...
;     cf v[16], u[16];
; #pragma unroll
;     for (int q = 0; q < 8; ++q) { v[q] = z0[q]; v[q + 8] = cf{0.f, 0.f}; u[q] = z1[q]; u[q + 8] = cf{0.f, 0.f}; }
;     dft_regs<16, false>(v); dft_regs<16, false>(u);
;     float sn, cs; SINCOSPI(-(float)tid * (2.0f / 8192.0f), &sn, &cs);
;     const cf w = cf{cs, sn}; cf wp = cf{1.f, 0.f};
;     LAS cf* p0 = buf0 + PADI(tid); LAS cf* p1 = buf1 + PADI(tid);
; #pragma unroll
;     for (int p = 0; p < 16; ++p) { p0[544 * p] = cmul(v[BR16[p]], wp); p1[544 * p] = cmul(u[BR16[p]], wp); wp = cmul(wp, w); }
	v_pk_add_f32 v[4:5], v[66:67], 0 op_sel:[1,0] op_sel_hi:[0,0] neg_hi:[1,0]
	v_pk_add_f32 v[66:67], v[112:113], v[92:93]
	v_pk_add_f32 v[92:93], v[112:113], v[92:93] neg_lo:[0,1] neg_hi:[0,1]
	v_pk_add_f32 v[112:113], v[98:99], v[88:89]
	v_pk_add_f32 v[88:89], v[98:99], v[88:89] neg_lo:[0,1] neg_hi:[0,1]
	v_pk_add_f32 v[98:99], v[88:89], 0 op_sel:[1,0] op_sel_hi:[0,0] neg_hi:[1,0]
	v_pk_add_f32 v[88:89], v[102:103], v[86:87]
	v_pk_add_f32 v[86:87], v[102:103], v[86:87] neg_lo:[0,1] neg_hi:[0,1]
	v_pk_add_f32 v[108:109], v[106:107], v[90:91]
	v_pk_add_f32 v[106:107], v[106:107], v[90:91] neg_lo:[0,1] neg_hi:[0,1]
	v_pk_add_f32 v[90:91], v[106:107], 0 op_sel:[1,0] op_sel_hi:[0,0] neg_hi:[1,0]
	v_pk_add_f32 v[106:107], v[82:83], v[96:97]
	v_pk_add_f32 v[96:97], v[82:83], v[96:97] neg_lo:[0,1] neg_hi:[0,1]
	v_pk_add_f32 v[82:83], v[100:101], v[94:95]
	v_pk_add_f32 v[94:95], v[100:101], v[94:95] neg_lo:[0,1] neg_hi:[0,1]
	v_pk_add_f32 v[100:101], v[94:95], 0 op_sel:[1,0] op_sel_hi:[0,0] neg_hi:[1,0]
	v_pk_add_f32 v[94:95], v[104:105], v[110:111]
	v_pk_add_f32 v[110:111], v[104:105], v[110:111] neg_lo:[0,1] neg_hi:[0,1]
	v_pk_add_f32 v[104:105], v[80:81], v[4:5]
	v_pk_add_f32 v[4:5], v[80:81], v[4:5] neg_lo:[0,1] neg_hi:[0,1]
	v_pk_add_f32 v[80:81], v[66:67], v[112:113]
	v_pk_add_f32 v[66:67], v[66:67], v[112:113] neg_lo:[0,1] neg_hi:[0,1]
	v_mov_b32_e32 v102, v66
	v_mov_b32_e32 v103, v67
	v_pk_add_f32 v[112:113], v[92:93], v[98:99]
	v_pk_add_f32 v[66:67], v[92:93], v[98:99] neg_lo:[0,1] neg_hi:[0,1]
	v_mov_b32_e32 v92, v66
	v_mov_b32_e32 v93, v67
	v_pk_add_f32 v[98:99], v[88:89], v[108:109]
	v_pk_add_f32 v[66:67], v[88:89], v[108:109] neg_lo:[0,1] neg_hi:[0,1]
	v_mov_b32_e32 v88, v66
	v_mov_b32_e32 v89, v67
	v_pk_add_f32 v[108:109], v[86:87], v[90:91]
	v_pk_add_f32 v[66:67], v[86:87], v[90:91] neg_lo:[0,1] neg_hi:[0,1]
	v_mov_b32_e32 v86, v66
	v_mov_b32_e32 v87, v67
	v_pk_add_f32 v[90:91], v[106:107], v[82:83]
	v_pk_add_f32 v[66:67], v[106:107], v[82:83] neg_lo:[0,1] neg_hi:[0,1]
	v_mov_b32_e32 v82, v66
	v_mov_b32_e32 v83, v67
	v_pk_add_f32 v[106:107], v[96:97], v[100:101]
	v_pk_add_f32 v[66:67], v[96:97], v[100:101] neg_lo:[0,1] neg_hi:[0,1]
	v_mov_b32_e32 v96, v66
	v_mov_b32_e32 v97, v67
	s_nop 0
	v_cvt_f32_i32_e32 v66, v114
	v_mul_f32_e32 v66, 0xb9800000, v66
	v_mul_f32_e32 v66, 0.5, v66
	v_sin_f32_e32 v101, v66
	v_cos_f32_e32 v100, v66
	v_ashrrev_i32_e32 v66, 4, v114
	v_add_lshl_u32 v66, v66, v114, 3
	v_add_u32_e32 v116, 0, v66
	v_add_u32_e32 v117, s33, v66
	v_mov_b64_e32 v[66:67], s[90:91]
	v_pk_mul_f32 v[114:115], v[68:69], v[66:67] op_sel:[1,1] op_sel_hi:[1,0] neg_lo:[1,0]
	v_pk_fma_f32 v[68:69], v[68:69], v[66:67], v[114:115] op_sel_hi:[0,1,1]
	ds_write_b64 v116, v[68:69]
	v_pk_mul_f32 v[114:115], v[94:95], v[66:67] op_sel:[1,1] op_sel_hi:[1,0] neg_lo:[1,0]
	v_pk_fma_f32 v[68:69], v[94:95], v[66:67], v[114:115] op_sel_hi:[0,1,1]
	ds_write_b64 v117, v[68:69]
	v_pk_mul_f32 v[68:69], v[66:67], v[100:101] op_sel:[1,1] op_sel_hi:[1,0] neg_lo:[1,0]
	v_pk_fma_f32 v[94:95], v[66:67], v[100:101], v[68:69] op_sel_hi:[0,1,1]
	v_pk_mul_f32 v[114:115], v[76:77], v[94:95] op_sel:[1,1] op_sel_hi:[1,0] neg_lo:[1,0]
	v_pk_fma_f32 v[68:69], v[76:77], v[94:95], v[114:115] op_sel_hi:[0,1,1]
	ds_write_b64 v116, v[68:69] offset:4352
	v_pk_mul_f32 v[76:77], v[98:99], v[94:95] op_sel:[1,1] op_sel_hi:[1,0] neg_lo:[1,0]
	v_pk_fma_f32 v[68:69], v[98:99], v[94:95], v[76:77] op_sel_hi:[0,1,1]
	ds_write_b64 v117, v[68:69] offset:4352
	v_pk_mul_f32 v[68:69], v[94:95], v[100:101] op_sel:[1,1] op_sel_hi:[1,0] neg_lo:[1,0]
	v_pk_fma_f32 v[76:77], v[94:95], v[100:101], v[68:69] op_sel_hi:[0,1,1]
	v_pk_mul_f32 v[94:95], v[70:71], v[76:77] op_sel:[1,1] op_sel_hi:[1,0] neg_lo:[1,0]
	v_pk_fma_f32 v[68:69], v[70:71], v[76:77], v[94:95] op_sel_hi:[0,1,1]
	ds_write_b64 v116, v[68:69] offset:8704
	v_pk_mul_f32 v[70:71], v[80:81], v[76:77] op_sel:[1,1] op_sel_hi:[1,0] neg_lo:[1,0]
	v_pk_fma_f32 v[68:69], v[80:81], v[76:77], v[70:71] op_sel_hi:[0,1,1]
	ds_write_b64 v117, v[68:69] offset:8704
	v_pk_mul_f32 v[68:69], v[76:77], v[100:101] op_sel:[1,1] op_sel_hi:[1,0] neg_lo:[1,0]
	v_pk_fma_f32 v[70:71], v[76:77], v[100:101], v[68:69] op_sel_hi:[0,1,1]
	v_pk_mul_f32 v[76:77], v[16:17], v[70:71] op_sel:[1,1] op_sel_hi:[1,0] neg_lo:[1,0]
	v_pk_fma_f32 v[68:69], v[16:17], v[70:71], v[76:77] op_sel_hi:[0,1,1]
	ds_write_b64 v116, v[68:69] offset:13056
	v_pk_mul_f32 v[76:77], v[90:91], v[70:71] op_sel:[1,1] op_sel_hi:[1,0] neg_lo:[1,0]
	v_pk_fma_f32 v[68:69], v[90:91], v[70:71], v[76:77] op_sel_hi:[0,1,1]
	ds_write_b64 v117, v[68:69] offset:13056
	v_pk_mul_f32 v[68:69], v[70:71], v[100:101] op_sel:[1,1] op_sel_hi:[1,0] neg_lo:[1,0]
	v_pk_fma_f32 v[70:71], v[70:71], v[100:101], v[68:69] op_sel_hi:[0,1,1]
	v_pk_mul_f32 v[68:69], v[78:79], v[70:71] op_sel:[1,1] op_sel_hi:[1,0] neg_lo:[1,0]
	v_pk_fma_f32 v[16:17], v[78:79], v[70:71], v[68:69] op_sel_hi:[0,1,1]
	ds_write_b64 v116, v[16:17] offset:17408
	v_pk_mul_f32 v[68:69], v[104:105], v[70:71] op_sel:[1,1] op_sel_hi:[1,0] neg_lo:[1,0]
	v_pk_fma_f32 v[16:17], v[104:105], v[70:71], v[68:69] op_sel_hi:[0,1,1]
	ds_write_b64 v117, v[16:17] offset:17408
	v_pk_mul_f32 v[16:17], v[70:71], v[100:101] op_sel:[1,1] op_sel_hi:[1,0] neg_lo:[1,0]
	v_pk_fma_f32 v[68:69], v[70:71], v[100:101], v[16:17] op_sel_hi:[0,1,1]
	v_pk_mul_f32 v[70:71], v[72:73], v[68:69] op_sel:[1,1] op_sel_hi:[1,0] neg_lo:[1,0]
	v_pk_fma_f32 v[16:17], v[72:73], v[68:69], v[70:71] op_sel_hi:[0,1,1]
	ds_write_b64 v116, v[16:17] offset:21760
	v_pk_mul_f32 v[70:71], v[108:109], v[68:69] op_sel:[1,1] op_sel_hi:[1,0] neg_lo:[1,0]
	v_pk_fma_f32 v[16:17], v[108:109], v[68:69], v[70:71] op_sel_hi:[0,1,1]
; #define LAS __attribute__((address_space(3)))
; #define SINCOSPI(x, s, c) do { const float hx_ = 0.5f * (x); *(s) = __builtin_amdgcn_sinf(hx_); *(c) = __builtin_amdgcn_cosf(hx_); } while (0)
; DEV void fft_f1x2(LAS cf* buf0, LAS cf* buf1, const cf (&z0)[8], const cf (&z1)[8], int tid) {
;     ...
;     float sn, cs; SINCOSPI(-(float)tid * (2.0f / 8192.0f), &sn, &cs);
;     const cf w = cf{cs, sn}; cf wp = cf{1.f, 0.f};
;     LAS cf* p0 = buf0 + PADI(tid); LAS cf* p1 = buf1 + PADI(tid);
; #pragma unroll
;     for (int p = 0; p < 16; ++p) { p0[544 * p] = cmul(v[BR16[p]], wp); p1[544 * p] = cmul(u[BR16[p]], wp); wp = cmul(wp, w); }
	ds_write_b64 v117, v[16:17] offset:21760
	v_pk_mul_f32 v[16:17], v[68:69], v[100:101] op_sel:[1,1] op_sel_hi:[1,0] neg_lo:[1,0]
	v_pk_fma_f32 v[68:69], v[68:69], v[100:101], v[16:17] op_sel_hi:[0,1,1]
	v_pk_mul_f32 v[70:71], v[18:19], v[68:69] op_sel:[1,1] op_sel_hi:[1,0] neg_lo:[1,0]
	v_pk_fma_f32 v[16:17], v[18:19], v[68:69], v[70:71] op_sel_hi:[0,1,1]
	ds_write_b64 v116, v[16:17] offset:26112
	v_pk_mul_f32 v[18:19], v[112:113], v[68:69] op_sel:[1,1] op_sel_hi:[1,0] neg_lo:[1,0]
	v_pk_fma_f32 v[16:17], v[112:113], v[68:69], v[18:19] op_sel_hi:[0,1,1]
	ds_write_b64 v117, v[16:17] offset:26112
	v_pk_mul_f32 v[16:17], v[68:69], v[100:101] op_sel:[1,1] op_sel_hi:[1,0] neg_lo:[1,0]
	v_pk_fma_f32 v[18:19], v[68:69], v[100:101], v[16:17] op_sel_hi:[0,1,1]
	v_pk_mul_f32 v[68:69], v[74:75], v[18:19] op_sel:[1,1] op_sel_hi:[1,0] neg_lo:[1,0]
	v_pk_fma_f32 v[16:17], v[74:75], v[18:19], v[68:69] op_sel_hi:[0,1,1]
	ds_write_b64 v116, v[16:17] offset:30464
	v_pk_mul_f32 v[68:69], v[106:107], v[18:19] op_sel:[1,1] op_sel_hi:[1,0] neg_lo:[1,0]
	v_pk_fma_f32 v[16:17], v[106:107], v[18:19], v[68:69] op_sel_hi:[0,1,1]
	ds_write_b64 v117, v[16:17] offset:30464
	v_pk_mul_f32 v[16:17], v[18:19], v[100:101] op_sel:[1,1] op_sel_hi:[1,0] neg_lo:[1,0]
	v_pk_fma_f32 v[18:19], v[18:19], v[100:101], v[16:17] op_sel_hi:[0,1,1]
	v_pk_mul_f32 v[16:17], v[84:85], v[18:19] op_sel:[1,1] op_sel_hi:[1,0] neg_lo:[1,0]
	v_pk_fma_f32 v[80:81], v[84:85], v[18:19], v[16:17] op_sel_hi:[0,1,1]
	ds_write_b64 v116, v[80:81] offset:34816
	v_pk_mul_f32 v[16:17], v[110:111], v[18:19] op_sel:[1,1] op_sel_hi:[1,0] neg_lo:[1,0]
	v_pk_fma_f32 v[80:81], v[110:111], v[18:19], v[16:17] op_sel_hi:[0,1,1]
	ds_write_b64 v117, v[80:81] offset:34816
	v_pk_mul_f32 v[80:81], v[18:19], v[100:101] op_sel:[1,1] op_sel_hi:[1,0] neg_lo:[1,0]
	v_pk_fma_f32 v[16:17], v[18:19], v[100:101], v[80:81] op_sel_hi:[0,1,1]
	v_pk_mul_f32 v[18:19], v[12:13], v[16:17] op_sel:[1,1] op_sel_hi:[1,0] neg_lo:[1,0]
	v_pk_fma_f32 v[80:81], v[12:13], v[16:17], v[18:19] op_sel_hi:[0,1,1]
	ds_write_b64 v116, v[80:81] offset:39168
	v_pk_mul_f32 v[12:13], v[88:89], v[16:17] op_sel:[1,1] op_sel_hi:[1,0] neg_lo:[1,0]
	v_pk_fma_f32 v[80:81], v[88:89], v[16:17], v[12:13] op_sel_hi:[0,1,1]
	ds_write_b64 v117, v[80:81] offset:39168
	v_pk_mul_f32 v[80:81], v[16:17], v[100:101] op_sel:[1,1] op_sel_hi:[1,0] neg_lo:[1,0]
	v_pk_fma_f32 v[12:13], v[16:17], v[100:101], v[80:81] op_sel_hi:[0,1,1]
	v_pk_mul_f32 v[16:17], v[6:7], v[12:13] op_sel:[1,1] op_sel_hi:[1,0] neg_lo:[1,0]
	v_pk_fma_f32 v[80:81], v[6:7], v[12:13], v[16:17] op_sel_hi:[0,1,1]
	ds_write_b64 v116, v[80:81] offset:43520
	v_pk_mul_f32 v[6:7], v[102:103], v[12:13] op_sel:[1,1] op_sel_hi:[1,0] neg_lo:[1,0]
	v_pk_fma_f32 v[80:81], v[102:103], v[12:13], v[6:7] op_sel_hi:[0,1,1]
	ds_write_b64 v117, v[80:81] offset:43520
	v_pk_mul_f32 v[80:81], v[12:13], v[100:101] op_sel:[1,1] op_sel_hi:[1,0] neg_lo:[1,0]
	v_pk_fma_f32 v[6:7], v[12:13], v[100:101], v[80:81] op_sel_hi:[0,1,1]
	v_pk_mul_f32 v[12:13], v[14:15], v[6:7] op_sel:[1,1] op_sel_hi:[1,0] neg_lo:[1,0]
	v_pk_fma_f32 v[80:81], v[14:15], v[6:7], v[12:13] op_sel_hi:[0,1,1]
	ds_write_b64 v116, v[80:81] offset:47872
	v_pk_mul_f32 v[12:13], v[82:83], v[6:7] op_sel:[1,1] op_sel_hi:[1,0] neg_lo:[1,0]
	v_pk_fma_f32 v[80:81], v[82:83], v[6:7], v[12:13] op_sel_hi:[0,1,1]
	ds_write_b64 v117, v[80:81] offset:47872
	v_pk_mul_f32 v[80:81], v[6:7], v[100:101] op_sel:[1,1] op_sel_hi:[1,0] neg_lo:[1,0]
	v_pk_fma_f32 v[6:7], v[6:7], v[100:101], v[80:81] op_sel_hi:[0,1,1]
	v_pk_mul_f32 v[80:81], v[0:1], v[6:7] op_sel:[1,1] op_sel_hi:[1,0] neg_lo:[1,0]
	v_pk_fma_f32 v[0:1], v[0:1], v[6:7], v[80:81] op_sel_hi:[0,1,1]
	ds_write_b64 v116, v[0:1] offset:52224
	v_pk_mul_f32 v[80:81], v[4:5], v[6:7] op_sel:[1,1] op_sel_hi:[1,0] neg_lo:[1,0]
	v_pk_fma_f32 v[0:1], v[4:5], v[6:7], v[80:81] op_sel_hi:[0,1,1]
	ds_write_b64 v117, v[0:1] offset:52224
	v_pk_mul_f32 v[0:1], v[6:7], v[100:101] op_sel:[1,1] op_sel_hi:[1,0] neg_lo:[1,0]
	v_pk_fma_f32 v[4:5], v[6:7], v[100:101], v[0:1] op_sel_hi:[0,1,1]
	v_pk_mul_f32 v[6:7], v[8:9], v[4:5] op_sel:[1,1] op_sel_hi:[1,0] neg_lo:[1,0]
	v_pk_fma_f32 v[0:1], v[8:9], v[4:5], v[6:7] op_sel_hi:[0,1,1]
	ds_write_b64 v116, v[0:1] offset:56576
	v_pk_mul_f32 v[6:7], v[86:87], v[4:5] op_sel:[1,1] op_sel_hi:[1,0] neg_lo:[1,0]
	v_pk_fma_f32 v[0:1], v[86:87], v[4:5], v[6:7] op_sel_hi:[0,1,1]
	ds_write_b64 v117, v[0:1] offset:56576
	v_pk_mul_f32 v[0:1], v[4:5], v[100:101] op_sel:[1,1] op_sel_hi:[1,0] neg_lo:[1,0]
	v_pk_fma_f32 v[4:5], v[4:5], v[100:101], v[0:1] op_sel_hi:[0,1,1]
	v_pk_mul_f32 v[6:7], v[2:3], v[4:5] op_sel:[1,1] op_sel_hi:[1,0] neg_lo:[1,0]
	v_pk_fma_f32 v[0:1], v[2:3], v[4:5], v[6:7] op_sel_hi:[0,1,1]
	ds_write_b64 v116, v[0:1] offset:60928
	v_pk_mul_f32 v[2:3], v[92:93], v[4:5] op_sel:[1,1] op_sel_hi:[1,0] neg_lo:[1,0]
	v_pk_fma_f32 v[0:1], v[92:93], v[4:5], v[2:3] op_sel_hi:[0,1,1]
	ds_write_b64 v117, v[0:1] offset:60928
	v_pk_mul_f32 v[0:1], v[4:5], v[100:101] op_sel:[1,1] op_sel_hi:[1,0] neg_lo:[1,0]
	v_pk_fma_f32 v[2:3], v[4:5], v[100:101], v[0:1] op_sel_hi:[0,1,1]
	v_pk_mul_f32 v[4:5], v[10:11], v[2:3] op_sel:[1,1] op_sel_hi:[1,0] neg_lo:[1,0]
	v_pk_fma_f32 v[0:1], v[10:11], v[2:3], v[4:5] op_sel_hi:[0,1,1]
	ds_write_b64 v116, v[0:1] offset:65280
	v_pk_mul_f32 v[4:5], v[96:97], v[2:3] op_sel:[1,1] op_sel_hi:[1,0] neg_lo:[1,0]
	v_pk_fma_f32 v[0:1], v[96:97], v[2:3], v[4:5] op_sel_hi:[0,1,1]
	ds_write_b64 v117, v[0:1] offset:65280
	v_mov_b32_e32 v0, v160
	s_waitcnt lgkmcnt(0)
	s_barrier
; #define LAS __attribute__((address_space(3)))
; #define OPAQUE_I(x) asm volatile("" : "+v"(x))
; DEV void fft_f2(LAS cf* buf, int t8) {
;     OPAQUE_I(t8);
;     LAS cf* pb = buf + (t8 >> 4) * 544 + (t8 & 15);
;     cf v[32];
; #pragma unroll
;     for (int q = 0; q < 32; ++q) v[q] = pb[17 * q];
;     dft_regs<32, false>(v);
	s_nop 0
	v_lshrrev_b32_e32 v1, 4, v0
	v_and_b32_e32 v3, 15, v0
	v_mul_lo_u32 v1, v1, s15
	v_lshlrev_b32_e32 v0, 3, v3
	v_add3_u32 v2, v159, v1, v0
	ds_read2_b64 v[4:7], v2 offset1:17
	ds_read2_b64 v[8:11], v2 offset0:34 offset1:51
	ds_read2_b64 v[12:15], v2 offset0:68 offset1:85
	ds_read2_b64 v[16:19], v2 offset0:102 offset1:119
	ds_read2_b64 v[68:71], v2 offset0:136 offset1:153
	ds_read2_b64 v[72:75], v2 offset0:170 offset1:187
	ds_read2_b64 v[76:79], v2 offset0:204 offset1:221
	ds_read2_b64 v[80:83], v2 offset0:238 offset1:255
	v_add_u32_e32 v0, 0x800, v2
	ds_read2_b64 v[84:87], v0 offset0:16 offset1:33
	ds_read2_b64 v[88:91], v0 offset0:50 offset1:67
	ds_read2_b64 v[92:95], v0 offset0:84 offset1:101
	ds_read2_b64 v[96:99], v0 offset0:118 offset1:135
	ds_read2_b64 v[100:103], v0 offset0:152 offset1:169
	ds_read2_b64 v[104:107], v0 offset0:186 offset1:203
	ds_read2_b64 v[108:111], v0 offset0:220 offset1:237
	s_waitcnt lgkmcnt(6)
	v_pk_add_f32 v[116:117], v[4:5], v[84:85]
	v_pk_add_f32 v[4:5], v[4:5], v[84:85] neg_lo:[0,1] neg_hi:[0,1]
	v_add_u32_e32 v1, 0xc00, v2
	ds_read2_b64 v[112:115], v1 offset0:126 offset1:143
	v_cvt_f32_ubyte0_e32 v3, v3
	v_pk_add_f32 v[118:119], v[6:7], v[86:87]
	v_pk_add_f32 v[6:7], v[6:7], v[86:87] neg_lo:[0,1] neg_hi:[0,1]
	v_mul_f32_e32 v3, 0xbb800000, v3
	v_pk_mul_f32 v[84:85], v[6:7], s[82:83] op_sel_hi:[1,0]
	v_mul_f32_e32 v3, 0.5, v3
	v_pk_fma_f32 v[86:87], v[6:7], s[94:95], v[84:85] op_sel:[0,0,1] op_sel_hi:[1,0,0] neg_hi:[0,0,1]
	s_waitcnt lgkmcnt(6)
	v_pk_add_f32 v[6:7], v[8:9], v[88:89]
	v_pk_add_f32 v[8:9], v[8:9], v[88:89] neg_lo:[0,1] neg_hi:[0,1]
	v_pk_mul_f32 v[84:85], v[8:9], s[84:85] op_sel_hi:[1,0]
	v_pk_fma_f32 v[88:89], v[8:9], s[16:17], v[84:85] op_sel:[0,0,1] op_sel_hi:[1,0,0] neg_hi:[0,0,1]
	v_pk_add_f32 v[8:9], v[10:11], v[90:91]
	v_pk_add_f32 v[10:11], v[10:11], v[90:91] neg_lo:[0,1] neg_hi:[0,1]
	v_pk_mul_f32 v[84:85], v[10:11], s[4:5] op_sel_hi:[1,0]
	v_pk_fma_f32 v[90:91], v[10:11], s[86:87], v[84:85] op_sel:[0,0,1] op_sel_hi:[1,0,0] neg_hi:[0,0,1]
	s_waitcnt lgkmcnt(5)
	v_pk_add_f32 v[10:11], v[12:13], v[92:93]
	v_pk_add_f32 v[12:13], v[12:13], v[92:93] neg_lo:[0,1] neg_hi:[0,1]
	v_pk_mul_f32 v[84:85], v[12:13], s[18:19] op_sel_hi:[1,0]
	v_pk_fma_f32 v[92:93], v[12:13], s[18:19], v[84:85] op_sel:[0,0,1] op_sel_hi:[1,0,0] neg_hi:[0,0,1]
	v_pk_add_f32 v[12:13], v[14:15], v[94:95]
	v_pk_add_f32 v[14:15], v[14:15], v[94:95] neg_lo:[0,1] neg_hi:[0,1]
	v_pk_mul_f32 v[84:85], v[14:15], s[86:87] op_sel_hi:[1,0]
	v_pk_fma_f32 v[94:95], v[14:15], s[4:5], v[84:85] op_sel:[0,0,1] op_sel_hi:[1,0,0] neg_hi:[0,0,1]
	s_mov_b32 s5, s86
	s_waitcnt lgkmcnt(4)
	v_pk_add_f32 v[14:15], v[16:17], v[96:97]
	v_pk_add_f32 v[16:17], v[16:17], v[96:97] neg_lo:[0,1] neg_hi:[0,1]
	v_pk_mul_f32 v[84:85], v[16:17], s[16:17] op_sel_hi:[1,0]
	v_pk_fma_f32 v[96:97], v[16:17], s[84:85], v[84:85] op_sel:[0,0,1] op_sel_hi:[1,0,0] neg_hi:[0,0,1]
	v_pk_add_f32 v[16:17], v[18:19], v[98:99]
	v_pk_add_f32 v[18:19], v[18:19], v[98:99] neg_lo:[0,1] neg_hi:[0,1]
	v_pk_mul_f32 v[84:85], v[18:19], s[94:95] op_sel_hi:[1,0]
	v_pk_fma_f32 v[98:99], v[18:19], s[82:83], v[84:85] op_sel:[0,0,1] op_sel_hi:[1,0,0] neg_hi:[0,0,1]
	s_mov_b32 s83, s94
	s_waitcnt lgkmcnt(3)
	v_pk_add_f32 v[18:19], v[68:69], v[100:101]
	v_pk_add_f32 v[68:69], v[68:69], v[100:101] neg_lo:[0,1] neg_hi:[0,1]
	v_pk_add_f32 v[84:85], v[68:69], 0 op_sel:[1,0] op_sel_hi:[0,0] neg_hi:[1,0]
	v_pk_add_f32 v[68:69], v[70:71], v[102:103]
	v_pk_add_f32 v[70:71], v[70:71], v[102:103] neg_lo:[0,1] neg_hi:[0,1]
	v_pk_mul_f32 v[100:101], v[70:71], s[82:83] op_sel_hi:[0,1]
	v_pk_fma_f32 v[70:71], v[70:71], s[94:95], v[100:101] op_sel:[1,0,0] neg_lo:[0,0,1] neg_hi:[0,0,1]
	s_waitcnt lgkmcnt(2)
	v_pk_add_f32 v[100:101], v[72:73], v[104:105]
	v_pk_add_f32 v[72:73], v[72:73], v[104:105] neg_lo:[0,1] neg_hi:[0,1]
	v_pk_mul_f32 v[102:103], v[72:73], s[84:85] op_sel_hi:[0,1]
	v_pk_fma_f32 v[72:73], v[72:73], s[30:31], v[102:103] op_sel:[1,0,0] neg_lo:[0,0,1] neg_hi:[0,0,1]
	v_pk_add_f32 v[102:103], v[74:75], v[106:107]
	v_pk_add_f32 v[74:75], v[74:75], v[106:107] neg_lo:[0,1] neg_hi:[0,1]
	v_pk_mul_f32 v[104:105], v[74:75], s[4:5] op_sel_hi:[0,1]
	v_pk_fma_f32 v[74:75], v[74:75], s[86:87], v[104:105] op_sel:[1,0,0] neg_lo:[0,0,1] neg_hi:[0,0,1]
	s_waitcnt lgkmcnt(1)
	v_pk_add_f32 v[104:105], v[76:77], v[108:109]
	v_pk_add_f32 v[76:77], v[76:77], v[108:109] neg_lo:[0,1] neg_hi:[0,1]
	v_mul_f32_e32 v106, 0x3f3504f3, v76
	v_pk_fma_f32 v[76:77], v[76:77], s[28:29], v[106:107] op_sel:[1,0,0] op_sel_hi:[1,1,0] neg_lo:[0,0,1] neg_hi:[0,0,1]
	v_pk_add_f32 v[106:107], v[78:79], v[110:111]
	v_pk_add_f32 v[78:79], v[78:79], v[110:111] neg_lo:[0,1] neg_hi:[0,1]
	v_pk_mul_f32 v[108:109], v[78:79], s[2:3] op_sel_hi:[0,1]
	v_pk_fma_f32 v[78:79], v[78:79], s[10:11], v[108:109] op_sel:[1,0,0] neg_lo:[0,0,1] neg_hi:[0,0,1]
	s_waitcnt lgkmcnt(0)
; template <int R, bool INV> DEV void dft_regs(cf (&v)[R]) {
; #pragma unroll
;     for (int s = R; s >= 2; s >>= 1) {
;         const int h = s >> 1;
; #pragma unroll
;         for (int b = 0; b < R; b += s) {
; #pragma unroll
;             for (int k = 0; k < h; ++k) {
;                 const cf a = v[b + k], c = v[b + k + h];
;                 v[b + k] = a + c;
;                 const cf d = a - c;
;                 const int m = k * (32 / s);
;                 const float wr = tw_cos(m), wi = INV ? tw_sin(m) : -tw_sin(m);
;                 v[b + k + h] = cf{d.x * wr - d.y * wi, d.x * wi + d.y * wr};
;             }
;         }
;     }
; }
; DEV void fft_f2(LAS cf* buf, int t8) {
;     ...
;     dft_regs<32, false>(v);
	v_pk_add_f32 v[108:109], v[80:81], v[112:113]
	v_pk_add_f32 v[80:81], v[80:81], v[112:113] neg_lo:[0,1] neg_hi:[0,1]
	v_pk_mul_f32 v[110:111], v[80:81], s[24:25] op_sel_hi:[0,1]
	v_pk_fma_f32 v[80:81], v[80:81], s[34:35], v[110:111] op_sel:[1,0,0] neg_lo:[0,0,1] neg_hi:[0,0,1]
	v_pk_add_f32 v[110:111], v[82:83], v[114:115]
	v_pk_add_f32 v[82:83], v[82:83], v[114:115] neg_lo:[0,1] neg_hi:[0,1]
	v_pk_mul_f32 v[112:113], v[82:83], s[6:7] op_sel_hi:[0,1]
	v_pk_fma_f32 v[82:83], v[82:83], s[8:9], v[112:113] op_sel:[1,0,0] neg_lo:[0,0,1] neg_hi:[0,0,1]
	v_pk_add_f32 v[112:113], v[116:117], v[18:19]
	v_pk_add_f32 v[18:19], v[116:117], v[18:19] neg_lo:[0,1] neg_hi:[0,1]
	v_pk_add_f32 v[116:117], v[118:119], v[68:69]
	v_pk_add_f32 v[118:119], v[118:119], v[68:69] neg_lo:[0,1] neg_hi:[0,1]
	v_pk_mul_f32 v[68:69], v[118:119], s[84:85] op_sel_hi:[1,0]
	v_pk_fma_f32 v[114:115], v[118:119], s[16:17], v[68:69] op_sel:[0,0,1] op_sel_hi:[1,0,0] neg_hi:[0,0,1]
	v_pk_add_f32 v[118:119], v[6:7], v[100:101]
	v_pk_add_f32 v[6:7], v[6:7], v[100:101] neg_lo:[0,1] neg_hi:[0,1]
	v_pk_mul_f32 v[68:69], v[6:7], s[18:19] op_sel_hi:[1,0]
	v_pk_fma_f32 v[100:101], v[6:7], s[18:19], v[68:69] op_sel:[0,0,1] op_sel_hi:[1,0,0] neg_hi:[0,0,1]
	v_pk_add_f32 v[6:7], v[8:9], v[102:103]
	v_pk_add_f32 v[8:9], v[8:9], v[102:103] neg_lo:[0,1] neg_hi:[0,1]
	v_pk_mul_f32 v[68:69], v[8:9], s[16:17] op_sel_hi:[1,0]
	v_pk_fma_f32 v[102:103], v[8:9], s[84:85], v[68:69] op_sel:[0,0,1] op_sel_hi:[1,0,0] neg_hi:[0,0,1]
	v_pk_add_f32 v[8:9], v[10:11], v[104:105]
	v_pk_add_f32 v[10:11], v[10:11], v[104:105] neg_lo:[0,1] neg_hi:[0,1]
	v_pk_add_f32 v[68:69], v[10:11], 0 op_sel:[1,0] op_sel_hi:[0,0] neg_hi:[1,0]
	v_pk_add_f32 v[10:11], v[12:13], v[106:107]
	v_pk_add_f32 v[12:13], v[12:13], v[106:107] neg_lo:[0,1] neg_hi:[0,1]
	v_pk_mul_f32 v[104:105], v[12:13], s[84:85] op_sel_hi:[0,1]
	v_pk_fma_f32 v[12:13], v[12:13], s[30:31], v[104:105] op_sel:[1,0,0] neg_lo:[0,0,1] neg_hi:[0,0,1]
	v_pk_add_f32 v[104:105], v[14:15], v[108:109]
	v_pk_add_f32 v[14:15], v[14:15], v[108:109] neg_lo:[0,1] neg_hi:[0,1]
	v_mul_f32_e32 v106, 0x3f3504f3, v14
	v_pk_fma_f32 v[14:15], v[14:15], s[28:29], v[106:107] op_sel:[1,0,0] op_sel_hi:[1,1,0] neg_lo:[0,0,1] neg_hi:[0,0,1]
	v_pk_add_f32 v[106:107], v[16:17], v[110:111]
	v_pk_add_f32 v[16:17], v[16:17], v[110:111] neg_lo:[0,1] neg_hi:[0,1]
	v_pk_mul_f32 v[108:109], v[16:17], s[24:25] op_sel_hi:[0,1]
	v_pk_fma_f32 v[16:17], v[16:17], s[34:35], v[108:109] op_sel:[1,0,0] neg_lo:[0,0,1] neg_hi:[0,0,1]
	v_pk_add_f32 v[108:109], v[4:5], v[84:85]
	v_pk_add_f32 v[84:85], v[4:5], v[84:85] neg_lo:[0,1] neg_hi:[0,1]
	v_pk_add_f32 v[4:5], v[86:87], v[70:71]
	v_pk_add_f32 v[70:71], v[86:87], v[70:71] neg_lo:[0,1] neg_hi:[0,1]
	v_pk_mul_f32 v[86:87], v[70:71], s[84:85] op_sel_hi:[1,0]
	v_pk_fma_f32 v[110:111], v[70:71], s[16:17], v[86:87] op_sel:[0,0,1] op_sel_hi:[1,0,0] neg_hi:[0,0,1]
	v_pk_add_f32 v[70:71], v[88:89], v[72:73]
	v_pk_add_f32 v[72:73], v[88:89], v[72:73] neg_lo:[0,1] neg_hi:[0,1]
	v_pk_mul_f32 v[86:87], v[72:73], s[18:19] op_sel_hi:[1,0]
	v_pk_fma_f32 v[88:89], v[72:73], s[18:19], v[86:87] op_sel:[0,0,1] op_sel_hi:[1,0,0] neg_hi:[0,0,1]
	v_pk_add_f32 v[72:73], v[90:91], v[74:75]
	v_pk_add_f32 v[74:75], v[90:91], v[74:75] neg_lo:[0,1] neg_hi:[0,1]
	v_pk_mul_f32 v[86:87], v[74:75], s[16:17] op_sel_hi:[1,0]
	v_pk_fma_f32 v[90:91], v[74:75], s[84:85], v[86:87] op_sel:[0,0,1] op_sel_hi:[1,0,0] neg_hi:[0,0,1]
	v_pk_add_f32 v[74:75], v[92:93], v[76:77]
	v_pk_add_f32 v[76:77], v[92:93], v[76:77] neg_lo:[0,1] neg_hi:[0,1]
	v_pk_add_f32 v[86:87], v[76:77], 0 op_sel:[1,0] op_sel_hi:[0,0] neg_hi:[1,0]
	v_pk_add_f32 v[76:77], v[94:95], v[78:79]
	v_pk_add_f32 v[78:79], v[94:95], v[78:79] neg_lo:[0,1] neg_hi:[0,1]
	v_pk_mul_f32 v[92:93], v[78:79], s[84:85] op_sel_hi:[0,1]
	v_pk_fma_f32 v[78:79], v[78:79], s[30:31], v[92:93] op_sel:[1,0,0] neg_lo:[0,0,1] neg_hi:[0,0,1]
	v_pk_add_f32 v[92:93], v[96:97], v[80:81]
	v_pk_add_f32 v[80:81], v[96:97], v[80:81] neg_lo:[0,1] neg_hi:[0,1]
	v_mul_f32_e32 v94, 0x3f3504f3, v80
	v_pk_fma_f32 v[80:81], v[80:81], s[28:29], v[94:95] op_sel:[1,0,0] op_sel_hi:[1,1,0] neg_lo:[0,0,1] neg_hi:[0,0,1]
	v_pk_add_f32 v[94:95], v[98:99], v[82:83]
	v_pk_add_f32 v[82:83], v[98:99], v[82:83] neg_lo:[0,1] neg_hi:[0,1]
	v_pk_mul_f32 v[96:97], v[82:83], s[24:25] op_sel_hi:[0,1]
	v_pk_fma_f32 v[82:83], v[82:83], s[34:35], v[96:97] op_sel:[1,0,0] neg_lo:[0,0,1] neg_hi:[0,0,1]
	v_pk_add_f32 v[96:97], v[112:113], v[8:9]
	v_pk_add_f32 v[8:9], v[112:113], v[8:9] neg_lo:[0,1] neg_hi:[0,1]
	v_pk_add_f32 v[112:113], v[116:117], v[10:11]
	v_pk_add_f32 v[10:11], v[116:117], v[10:11] neg_lo:[0,1] neg_hi:[0,1]
	v_pk_mul_f32 v[116:117], v[10:11], s[18:19] op_sel_hi:[1,0]
	v_pk_fma_f32 v[98:99], v[10:11], s[18:19], v[116:117] op_sel:[0,0,1] op_sel_hi:[1,0,0] neg_hi:[0,0,1]
	v_pk_add_f32 v[10:11], v[118:119], v[104:105]
	v_pk_add_f32 v[118:119], v[118:119], v[104:105] neg_lo:[0,1] neg_hi:[0,1]
	v_pk_add_f32 v[116:117], v[118:119], 0 op_sel:[1,0] op_sel_hi:[0,0] neg_hi:[1,0]
	v_pk_add_f32 v[118:119], v[6:7], v[106:107]
	v_pk_add_f32 v[6:7], v[6:7], v[106:107] neg_lo:[0,1] neg_hi:[0,1]
	v_mul_f32_e32 v104, 0x3f3504f3, v6
	v_pk_fma_f32 v[6:7], v[6:7], s[28:29], v[104:105] op_sel:[1,0,0] op_sel_hi:[1,1,0] neg_lo:[0,0,1] neg_hi:[0,0,1]
	v_pk_add_f32 v[104:105], v[18:19], v[68:69]
	v_pk_add_f32 v[68:69], v[18:19], v[68:69] neg_lo:[0,1] neg_hi:[0,1]
	v_pk_add_f32 v[18:19], v[114:115], v[12:13]
	v_pk_add_f32 v[12:13], v[114:115], v[12:13] neg_lo:[0,1] neg_hi:[0,1]
	v_pk_mul_f32 v[106:107], v[12:13], s[18:19] op_sel_hi:[1,0]
	v_pk_fma_f32 v[114:115], v[12:13], s[18:19], v[106:107] op_sel:[0,0,1] op_sel_hi:[1,0,0] neg_hi:[0,0,1]
; template <int R, bool INV> DEV void dft_regs(cf (&v)[R]) {
; #pragma unroll
;     for (int s = R; s >= 2; s >>= 1) {
;         const int h = s >> 1;
; #pragma unroll
;         for (int b = 0; b < R; b += s) {
; #pragma unroll
;             for (int k = 0; k < h; ++k) {
;                 const cf a = v[b + k], c = v[b + k + h];
;                 v[b + k] = a + c;
;                 const cf d = a - c;
;                 const int m = k * (32 / s);
;                 const float wr = tw_cos(m), wi = INV ? tw_sin(m) : -tw_sin(m);
;                 v[b + k + h] = cf{d.x * wr - d.y * wi, d.x * wi + d.y * wr};
;             }
;         }
;     }
; }
; DEV void fft_f2(LAS cf* buf, int t8) {
;     ...
;     dft_regs<32, false>(v);
	v_pk_add_f32 v[12:13], v[100:101], v[14:15]
	v_pk_add_f32 v[14:15], v[100:101], v[14:15] neg_lo:[0,1] neg_hi:[0,1]
	v_pk_add_f32 v[100:101], v[14:15], 0 op_sel:[1,0] op_sel_hi:[0,0] neg_hi:[1,0]
	v_pk_add_f32 v[14:15], v[102:103], v[16:17]
	v_pk_add_f32 v[16:17], v[102:103], v[16:17] neg_lo:[0,1] neg_hi:[0,1]
	v_mul_f32_e32 v102, 0x3f3504f3, v16
	v_pk_fma_f32 v[16:17], v[16:17], s[28:29], v[102:103] op_sel:[1,0,0] op_sel_hi:[1,1,0] neg_lo:[0,0,1] neg_hi:[0,0,1]
	v_pk_add_f32 v[102:103], v[108:109], v[74:75]
	v_pk_add_f32 v[74:75], v[108:109], v[74:75] neg_lo:[0,1] neg_hi:[0,1]
	v_pk_add_f32 v[108:109], v[4:5], v[76:77]
	v_pk_add_f32 v[76:77], v[4:5], v[76:77] neg_lo:[0,1] neg_hi:[0,1]
	v_pk_mul_f32 v[4:5], v[76:77], s[18:19] op_sel_hi:[1,0]
	v_pk_fma_f32 v[106:107], v[76:77], s[18:19], v[4:5] op_sel:[0,0,1] op_sel_hi:[1,0,0] neg_hi:[0,0,1]
	v_pk_add_f32 v[76:77], v[70:71], v[92:93]
	v_pk_add_f32 v[70:71], v[70:71], v[92:93] neg_lo:[0,1] neg_hi:[0,1]
	v_pk_add_f32 v[4:5], v[70:71], 0 op_sel:[1,0] op_sel_hi:[0,0] neg_hi:[1,0]
	v_pk_add_f32 v[70:71], v[72:73], v[94:95]
	v_pk_add_f32 v[72:73], v[72:73], v[94:95] neg_lo:[0,1] neg_hi:[0,1]
	v_mul_f32_e32 v92, 0x3f3504f3, v72
	v_pk_fma_f32 v[72:73], v[72:73], s[28:29], v[92:93] op_sel:[1,0,0] op_sel_hi:[1,1,0] neg_lo:[0,0,1] neg_hi:[0,0,1]
	v_pk_add_f32 v[92:93], v[84:85], v[86:87]
	v_pk_add_f32 v[86:87], v[84:85], v[86:87] neg_lo:[0,1] neg_hi:[0,1]
	v_mov_b32_e32 v84, v86
	v_mov_b32_e32 v85, v87
	v_pk_add_f32 v[86:87], v[110:111], v[78:79]
	v_pk_add_f32 v[78:79], v[110:111], v[78:79] neg_lo:[0,1] neg_hi:[0,1]
	v_pk_mul_f32 v[94:95], v[78:79], s[18:19] op_sel_hi:[1,0]
	v_pk_fma_f32 v[110:111], v[78:79], s[18:19], v[94:95] op_sel:[0,0,1] op_sel_hi:[1,0,0] neg_hi:[0,0,1]
	v_pk_add_f32 v[78:79], v[88:89], v[80:81]
	v_pk_add_f32 v[80:81], v[88:89], v[80:81] neg_lo:[0,1] neg_hi:[0,1]
	v_pk_add_f32 v[88:89], v[80:81], 0 op_sel:[1,0] op_sel_hi:[0,0] neg_hi:[1,0]
	v_pk_add_f32 v[80:81], v[90:91], v[82:83]
	v_pk_add_f32 v[82:83], v[90:91], v[82:83] neg_lo:[0,1] neg_hi:[0,1]
	v_mul_f32_e32 v90, 0x3f3504f3, v82
	v_pk_fma_f32 v[82:83], v[82:83], s[28:29], v[90:91] op_sel:[1,0,0] op_sel_hi:[1,1,0] neg_lo:[0,0,1] neg_hi:[0,0,1]
	v_pk_add_f32 v[90:91], v[96:97], v[10:11]
	v_pk_add_f32 v[10:11], v[96:97], v[10:11] neg_lo:[0,1] neg_hi:[0,1]
	v_pk_add_f32 v[96:97], v[112:113], v[118:119]
	v_pk_add_f32 v[118:119], v[112:113], v[118:119] neg_lo:[0,1] neg_hi:[0,1]
	v_pk_add_f32 v[112:113], v[118:119], 0 op_sel:[1,0] op_sel_hi:[0,0] neg_hi:[1,0]
	v_pk_add_f32 v[118:119], v[8:9], v[116:117]
	v_pk_add_f32 v[116:117], v[8:9], v[116:117] neg_lo:[0,1] neg_hi:[0,1]
	v_pk_add_f32 v[8:9], v[98:99], v[6:7]
	v_pk_add_f32 v[6:7], v[98:99], v[6:7] neg_lo:[0,1] neg_hi:[0,1]
	v_pk_add_f32 v[94:95], v[6:7], 0 op_sel:[1,0] op_sel_hi:[0,0] neg_hi:[1,0]
	v_pk_add_f32 v[6:7], v[104:105], v[12:13]
	v_pk_add_f32 v[12:13], v[104:105], v[12:13] neg_lo:[0,1] neg_hi:[0,1]
	v_pk_add_f32 v[98:99], v[68:69], v[100:101] neg_lo:[0,1] neg_hi:[0,1]
	v_pk_add_f32 v[104:105], v[18:19], v[14:15]
	v_pk_add_f32 v[14:15], v[18:19], v[14:15] neg_lo:[0,1] neg_hi:[0,1]
	v_pk_add_f32 v[18:19], v[14:15], 0 op_sel:[1,0] op_sel_hi:[0,0] neg_hi:[1,0]
	v_pk_add_f32 v[14:15], v[68:69], v[100:101]
	v_pk_add_f32 v[68:69], v[114:115], v[16:17]
	v_pk_add_f32 v[16:17], v[114:115], v[16:17] neg_lo:[0,1] neg_hi:[0,1]
	v_pk_add_f32 v[100:101], v[16:17], 0 op_sel:[1,0] op_sel_hi:[0,0] neg_hi:[1,0]
	v_pk_add_f32 v[16:17], v[102:103], v[76:77]
	v_pk_add_f32 v[76:77], v[102:103], v[76:77] neg_lo:[0,1] neg_hi:[0,1]
	v_pk_add_f32 v[114:115], v[108:109], v[70:71]
	v_pk_add_f32 v[70:71], v[108:109], v[70:71] neg_lo:[0,1] neg_hi:[0,1]
	v_pk_add_f32 v[108:109], v[70:71], 0 op_sel:[1,0] op_sel_hi:[0,0] neg_hi:[1,0]
	v_pk_add_f32 v[70:71], v[74:75], v[4:5]
	v_pk_add_f32 v[4:5], v[74:75], v[4:5] neg_lo:[0,1] neg_hi:[0,1]
	v_pk_add_f32 v[74:75], v[106:107], v[72:73]
	v_pk_add_f32 v[72:73], v[106:107], v[72:73] neg_lo:[0,1] neg_hi:[0,1]
	v_pk_add_f32 v[102:103], v[72:73], 0 op_sel:[1,0] op_sel_hi:[0,0] neg_hi:[1,0]
	v_pk_add_f32 v[72:73], v[92:93], v[78:79]
	v_pk_add_f32 v[78:79], v[92:93], v[78:79] neg_lo:[0,1] neg_hi:[0,1]
	v_pk_add_f32 v[106:107], v[86:87], v[80:81]
	v_pk_add_f32 v[80:81], v[86:87], v[80:81] neg_lo:[0,1] neg_hi:[0,1]
	v_pk_add_f32 v[86:87], v[80:81], 0 op_sel:[1,0] op_sel_hi:[0,0] neg_hi:[1,0]
	v_pk_add_f32 v[80:81], v[84:85], v[88:89]
	v_pk_add_f32 v[88:89], v[84:85], v[88:89] neg_lo:[0,1] neg_hi:[0,1]
	v_pk_add_f32 v[84:85], v[110:111], v[82:83]
	v_pk_add_f32 v[82:83], v[110:111], v[82:83] neg_lo:[0,1] neg_hi:[0,1]
	v_pk_add_f32 v[92:93], v[82:83], 0 op_sel:[1,0] op_sel_hi:[0,0] neg_hi:[1,0]
	v_pk_add_f32 v[82:83], v[90:91], v[96:97]
	v_pk_add_f32 v[96:97], v[90:91], v[96:97] neg_lo:[0,1] neg_hi:[0,1]
	v_pk_add_f32 v[110:111], v[10:11], v[112:113]
	v_pk_add_f32 v[112:113], v[10:11], v[112:113] neg_lo:[0,1] neg_hi:[0,1]
	v_pk_add_f32 v[10:11], v[118:119], v[8:9]
	v_pk_add_f32 v[118:119], v[118:119], v[8:9] neg_lo:[0,1] neg_hi:[0,1]
	v_pk_add_f32 v[8:9], v[116:117], v[94:95] neg_lo:[0,1] neg_hi:[0,1]
	v_pk_add_f32 v[90:91], v[116:117], v[94:95]
	v_pk_add_f32 v[116:117], v[6:7], v[104:105]
	v_pk_add_f32 v[6:7], v[6:7], v[104:105] neg_lo:[0,1] neg_hi:[0,1]
	v_pk_add_f32 v[104:105], v[12:13], v[18:19] neg_lo:[0,1] neg_hi:[0,1]
	v_pk_add_f32 v[94:95], v[12:13], v[18:19]
	v_pk_add_f32 v[12:13], v[14:15], v[68:69]
	v_pk_add_f32 v[14:15], v[14:15], v[68:69] neg_lo:[0,1] neg_hi:[0,1]
	v_pk_add_f32 v[18:19], v[98:99], v[100:101] neg_lo:[0,1] neg_hi:[0,1]
	v_pk_add_f32 v[68:69], v[98:99], v[100:101]
	v_pk_add_f32 v[98:99], v[16:17], v[114:115]
; #define SINCOSPI(x, s, c) do { const float hx_ = 0.5f * (x); *(s) = __builtin_amdgcn_sinf(hx_); *(c) = __builtin_amdgcn_cosf(hx_); } while (0)
; template <int R, bool INV> DEV void dft_regs(cf (&v)[R]) {
; #pragma unroll
;     for (int s = R; s >= 2; s >>= 1) {
;         const int h = s >> 1;
; #pragma unroll
;         for (int b = 0; b < R; b += s) {
; #pragma unroll
;             for (int k = 0; k < h; ++k) {
;                 const cf a = v[b + k], c = v[b + k + h];
;                 v[b + k] = a + c;
;                 const cf d = a - c;
;                 const int m = k * (32 / s);
;                 const float wr = tw_cos(m), wi = INV ? tw_sin(m) : -tw_sin(m);
;                 v[b + k + h] = cf{d.x * wr - d.y * wi, d.x * wi + d.y * wr};
;             }
;         }
;     }
; }
; DEV void fft_f2(LAS cf* buf, int t8) {
;     ...
;     float sn, cs; SINCOSPI(-(float)(t8 & 15) * (2.0f / 512.0f), &sn, &cs);
;     const cf w = cf{cs, sn}; cf wp = cf{1.f, 0.f};
; #pragma unroll
;     for (int p = 0; p < 32; ++p) { pb[17 * p] = cmul(v[BR32[p]], wp); wp = cmul(wp, w); }
	v_pk_add_f32 v[16:17], v[16:17], v[114:115] neg_lo:[0,1] neg_hi:[0,1]
	v_pk_add_f32 v[100:101], v[76:77], v[108:109]
	v_pk_add_f32 v[108:109], v[76:77], v[108:109] neg_lo:[0,1] neg_hi:[0,1]
	v_pk_add_f32 v[76:77], v[70:71], v[74:75]
	v_pk_add_f32 v[70:71], v[70:71], v[74:75] neg_lo:[0,1] neg_hi:[0,1]
	v_pk_add_f32 v[114:115], v[4:5], v[102:103] neg_lo:[0,1] neg_hi:[0,1]
	v_pk_add_f32 v[74:75], v[4:5], v[102:103]
	v_pk_add_f32 v[4:5], v[72:73], v[106:107]
	v_pk_add_f32 v[72:73], v[72:73], v[106:107] neg_lo:[0,1] neg_hi:[0,1]
	v_pk_add_f32 v[106:107], v[78:79], v[86:87] neg_lo:[0,1] neg_hi:[0,1]
	v_pk_add_f32 v[102:103], v[78:79], v[86:87]
	v_pk_add_f32 v[78:79], v[80:81], v[84:85]
	v_pk_add_f32 v[80:81], v[80:81], v[84:85] neg_lo:[0,1] neg_hi:[0,1]
	v_pk_add_f32 v[86:87], v[88:89], v[92:93] neg_lo:[0,1] neg_hi:[0,1]
	v_pk_add_f32 v[84:85], v[88:89], v[92:93]
	v_mov_b32_e32 v88, v86
	v_mov_b32_e32 v89, v87
	v_pk_mul_f32 v[92:93], v[82:83], v[66:67] op_sel:[1,1] op_sel_hi:[1,0] neg_lo:[1,0]
	v_pk_fma_f32 v[82:83], v[82:83], v[66:67], v[92:93] op_sel_hi:[0,1,1]
	s_nop 0
	v_sin_f32_e32 v87, v3
	v_cos_f32_e32 v86, v3
	v_pk_mul_f32 v[92:93], v[66:67], v[86:87] op_sel:[1,1] op_sel_hi:[1,0] neg_lo:[1,0]
	v_pk_fma_f32 v[120:121], v[66:67], v[86:87], v[92:93] op_sel_hi:[0,1,1]
	v_pk_mul_f32 v[92:93], v[98:99], v[120:121] op_sel:[1,1] op_sel_hi:[1,0] neg_lo:[1,0]
	v_pk_fma_f32 v[98:99], v[98:99], v[120:121], v[92:93] op_sel_hi:[0,1,1]
	ds_write2_b64 v2, v[82:83], v[98:99] offset1:17
	v_pk_mul_f32 v[98:99], v[120:121], v[86:87] op_sel:[1,1] op_sel_hi:[1,0] neg_lo:[1,0]
	v_pk_fma_f32 v[82:83], v[120:121], v[86:87], v[98:99] op_sel_hi:[0,1,1]
	v_pk_mul_f32 v[98:99], v[116:117], v[82:83] op_sel:[1,1] op_sel_hi:[1,0] neg_lo:[1,0]
	v_pk_fma_f32 v[116:117], v[116:117], v[82:83], v[98:99] op_sel_hi:[0,1,1]
	s_nop 0
	v_pk_mul_f32 v[98:99], v[82:83], v[86:87] op_sel:[1,1] op_sel_hi:[1,0] neg_lo:[1,0]
	v_pk_fma_f32 v[82:83], v[82:83], v[86:87], v[98:99] op_sel_hi:[0,1,1]
	v_pk_mul_f32 v[92:93], v[4:5], v[82:83] op_sel:[1,1] op_sel_hi:[1,0] neg_lo:[1,0]
	v_pk_fma_f32 v[98:99], v[4:5], v[82:83], v[92:93] op_sel_hi:[0,1,1]
	ds_write2_b64 v2, v[116:117], v[98:99] offset0:34 offset1:51
	v_pk_mul_f32 v[116:117], v[82:83], v[86:87] op_sel:[1,1] op_sel_hi:[1,0] neg_lo:[1,0]
	v_pk_fma_f32 v[98:99], v[82:83], v[86:87], v[116:117] op_sel_hi:[0,1,1]
	v_pk_mul_f32 v[116:117], v[10:11], v[98:99] op_sel:[1,1] op_sel_hi:[1,0] neg_lo:[1,0]
	v_pk_fma_f32 v[10:11], v[10:11], v[98:99], v[116:117] op_sel_hi:[0,1,1]
	s_nop 0
	v_pk_mul_f32 v[116:117], v[98:99], v[86:87] op_sel:[1,1] op_sel_hi:[1,0] neg_lo:[1,0]
	v_pk_fma_f32 v[98:99], v[98:99], v[86:87], v[116:117] op_sel_hi:[0,1,1]
	v_pk_mul_f32 v[4:5], v[76:77], v[98:99] op_sel:[1,1] op_sel_hi:[1,0] neg_lo:[1,0]
	v_pk_fma_f32 v[116:117], v[76:77], v[98:99], v[4:5] op_sel_hi:[0,1,1]
	ds_write2_b64 v2, v[10:11], v[116:117] offset0:68 offset1:85
	v_pk_mul_f32 v[10:11], v[98:99], v[86:87] op_sel:[1,1] op_sel_hi:[1,0] neg_lo:[1,0]
	v_pk_fma_f32 v[116:117], v[98:99], v[86:87], v[10:11] op_sel_hi:[0,1,1]
	v_pk_mul_f32 v[98:99], v[12:13], v[116:117] op_sel:[1,1] op_sel_hi:[1,0] neg_lo:[1,0]
	v_pk_fma_f32 v[10:11], v[12:13], v[116:117], v[98:99] op_sel_hi:[0,1,1]
	v_pk_mul_f32 v[12:13], v[116:117], v[86:87] op_sel:[1,1] op_sel_hi:[1,0] neg_lo:[1,0]
	v_pk_fma_f32 v[116:117], v[116:117], v[86:87], v[12:13] op_sel_hi:[0,1,1]
	v_pk_mul_f32 v[98:99], v[78:79], v[116:117] op_sel:[1,1] op_sel_hi:[1,0] neg_lo:[1,0]
	v_pk_fma_f32 v[12:13], v[78:79], v[116:117], v[98:99] op_sel_hi:[0,1,1]
	ds_write2_b64 v2, v[10:11], v[12:13] offset0:102 offset1:119
	v_pk_mul_f32 v[10:11], v[116:117], v[86:87] op_sel:[1,1] op_sel_hi:[1,0] neg_lo:[1,0]
	v_pk_fma_f32 v[12:13], v[116:117], v[86:87], v[10:11] op_sel_hi:[0,1,1]
	v_pk_mul_f32 v[116:117], v[110:111], v[12:13] op_sel:[1,1] op_sel_hi:[1,0] neg_lo:[1,0]
	v_pk_fma_f32 v[10:11], v[110:111], v[12:13], v[116:117] op_sel_hi:[0,1,1]
	v_pk_mul_f32 v[110:111], v[12:13], v[86:87] op_sel:[1,1] op_sel_hi:[1,0] neg_lo:[1,0]
	v_pk_fma_f32 v[12:13], v[12:13], v[86:87], v[110:111] op_sel_hi:[0,1,1]
	v_pk_mul_f32 v[116:117], v[100:101], v[12:13] op_sel:[1,1] op_sel_hi:[1,0] neg_lo:[1,0]
	v_pk_fma_f32 v[110:111], v[100:101], v[12:13], v[116:117] op_sel_hi:[0,1,1]
	ds_write2_b64 v2, v[10:11], v[110:111] offset0:136 offset1:153
	v_pk_mul_f32 v[10:11], v[12:13], v[86:87] op_sel:[1,1] op_sel_hi:[1,0] neg_lo:[1,0]
	v_pk_fma_f32 v[110:111], v[12:13], v[86:87], v[10:11] op_sel_hi:[0,1,1]
	v_pk_mul_f32 v[10:11], v[94:95], v[110:111] op_sel:[1,1] op_sel_hi:[1,0] neg_lo:[1,0]
	v_pk_fma_f32 v[94:95], v[94:95], v[110:111], v[10:11] op_sel_hi:[0,1,1]
	s_nop 0
	v_pk_mul_f32 v[10:11], v[110:111], v[86:87] op_sel:[1,1] op_sel_hi:[1,0] neg_lo:[1,0]
	v_pk_fma_f32 v[110:111], v[110:111], v[86:87], v[10:11] op_sel_hi:[0,1,1]
	v_pk_mul_f32 v[12:13], v[102:103], v[110:111] op_sel:[1,1] op_sel_hi:[1,0] neg_lo:[1,0]
	v_pk_fma_f32 v[10:11], v[102:103], v[110:111], v[12:13] op_sel_hi:[0,1,1]
	ds_write2_b64 v2, v[94:95], v[10:11] offset0:170 offset1:187
	v_pk_mul_f32 v[94:95], v[110:111], v[86:87] op_sel:[1,1] op_sel_hi:[1,0] neg_lo:[1,0]
	v_pk_fma_f32 v[10:11], v[110:111], v[86:87], v[94:95] op_sel_hi:[0,1,1]
	v_pk_mul_f32 v[94:95], v[90:91], v[10:11] op_sel:[1,1] op_sel_hi:[1,0] neg_lo:[1,0]
	v_pk_fma_f32 v[90:91], v[90:91], v[10:11], v[94:95] op_sel_hi:[0,1,1]
	s_nop 0
	v_pk_mul_f32 v[94:95], v[10:11], v[86:87] op_sel:[1,1] op_sel_hi:[1,0] neg_lo:[1,0]
	v_pk_fma_f32 v[10:11], v[10:11], v[86:87], v[94:95] op_sel_hi:[0,1,1]
	v_pk_mul_f32 v[110:111], v[74:75], v[10:11] op_sel:[1,1] op_sel_hi:[1,0] neg_lo:[1,0]
	v_pk_fma_f32 v[94:95], v[74:75], v[10:11], v[110:111] op_sel_hi:[0,1,1]
; DEV void fft_f2(LAS cf* buf, int t8) {
;     ...
;     const cf w = cf{cs, sn}; cf wp = cf{1.f, 0.f};
; #pragma unroll
;     for (int p = 0; p < 32; ++p) { pb[17 * p] = cmul(v[BR32[p]], wp); wp = cmul(wp, w); }
	ds_write2_b64 v2, v[90:91], v[94:95] offset0:204 offset1:221
	v_pk_mul_f32 v[90:91], v[10:11], v[86:87] op_sel:[1,1] op_sel_hi:[1,0] neg_lo:[1,0]
	v_pk_fma_f32 v[94:95], v[10:11], v[86:87], v[90:91] op_sel_hi:[0,1,1]
	v_pk_mul_f32 v[10:11], v[68:69], v[94:95] op_sel:[1,1] op_sel_hi:[1,0] neg_lo:[1,0]
	v_pk_fma_f32 v[90:91], v[68:69], v[94:95], v[10:11] op_sel_hi:[0,1,1]
	s_nop 0
	v_pk_mul_f32 v[10:11], v[94:95], v[86:87] op_sel:[1,1] op_sel_hi:[1,0] neg_lo:[1,0]
	v_pk_fma_f32 v[94:95], v[94:95], v[86:87], v[10:11] op_sel_hi:[0,1,1]
	v_pk_mul_f32 v[110:111], v[84:85], v[94:95] op_sel:[1,1] op_sel_hi:[1,0] neg_lo:[1,0]
	v_pk_fma_f32 v[10:11], v[84:85], v[94:95], v[110:111] op_sel_hi:[0,1,1]
	ds_write2_b64 v2, v[90:91], v[10:11] offset0:238 offset1:255
	v_pk_mul_f32 v[2:3], v[94:95], v[86:87] op_sel:[1,1] op_sel_hi:[1,0] neg_lo:[1,0]
	v_pk_fma_f32 v[90:91], v[94:95], v[86:87], v[2:3] op_sel_hi:[0,1,1]
	v_pk_mul_f32 v[94:95], v[96:97], v[90:91] op_sel:[1,1] op_sel_hi:[1,0] neg_lo:[1,0]
	v_pk_fma_f32 v[2:3], v[96:97], v[90:91], v[94:95] op_sel_hi:[0,1,1]
	s_nop 0
	v_pk_mul_f32 v[94:95], v[90:91], v[86:87] op_sel:[1,1] op_sel_hi:[1,0] neg_lo:[1,0]
	v_pk_fma_f32 v[90:91], v[90:91], v[86:87], v[94:95] op_sel_hi:[0,1,1]
	v_pk_mul_f32 v[10:11], v[16:17], v[90:91] op_sel:[1,1] op_sel_hi:[1,0] neg_lo:[1,0]
	v_pk_fma_f32 v[94:95], v[16:17], v[90:91], v[10:11] op_sel_hi:[0,1,1]
	ds_write2_b64 v0, v[2:3], v[94:95] offset0:16 offset1:33
	v_pk_mul_f32 v[2:3], v[90:91], v[86:87] op_sel:[1,1] op_sel_hi:[1,0] neg_lo:[1,0]
	v_pk_fma_f32 v[90:91], v[90:91], v[86:87], v[2:3] op_sel_hi:[0,1,1]
	v_pk_mul_f32 v[94:95], v[6:7], v[90:91] op_sel:[1,1] op_sel_hi:[1,0] neg_lo:[1,0]
	v_pk_fma_f32 v[2:3], v[6:7], v[90:91], v[94:95] op_sel_hi:[0,1,1]
	s_nop 0
	v_pk_mul_f32 v[6:7], v[90:91], v[86:87] op_sel:[1,1] op_sel_hi:[1,0] neg_lo:[1,0]
	v_pk_fma_f32 v[90:91], v[90:91], v[86:87], v[6:7] op_sel_hi:[0,1,1]
	v_pk_mul_f32 v[10:11], v[72:73], v[90:91] op_sel:[1,1] op_sel_hi:[1,0] neg_lo:[1,0]
	v_pk_fma_f32 v[6:7], v[72:73], v[90:91], v[10:11] op_sel_hi:[0,1,1]
	ds_write2_b64 v0, v[2:3], v[6:7] offset0:50 offset1:67
	v_pk_mul_f32 v[2:3], v[90:91], v[86:87] op_sel:[1,1] op_sel_hi:[1,0] neg_lo:[1,0]
	v_pk_fma_f32 v[90:91], v[90:91], v[86:87], v[2:3] op_sel_hi:[0,1,1]
	v_pk_mul_f32 v[6:7], v[118:119], v[90:91] op_sel:[1,1] op_sel_hi:[1,0] neg_lo:[1,0]
	v_pk_fma_f32 v[2:3], v[118:119], v[90:91], v[6:7] op_sel_hi:[0,1,1]
	s_nop 0
	v_pk_mul_f32 v[6:7], v[90:91], v[86:87] op_sel:[1,1] op_sel_hi:[1,0] neg_lo:[1,0]
	v_pk_fma_f32 v[118:119], v[90:91], v[86:87], v[6:7] op_sel_hi:[0,1,1]
	v_pk_mul_f32 v[10:11], v[70:71], v[118:119] op_sel:[1,1] op_sel_hi:[1,0] neg_lo:[1,0]
	v_pk_fma_f32 v[6:7], v[70:71], v[118:119], v[10:11] op_sel_hi:[0,1,1]
	ds_write2_b64 v0, v[2:3], v[6:7] offset0:84 offset1:101
	v_pk_mul_f32 v[2:3], v[118:119], v[86:87] op_sel:[1,1] op_sel_hi:[1,0] neg_lo:[1,0]
	v_pk_fma_f32 v[118:119], v[118:119], v[86:87], v[2:3] op_sel_hi:[0,1,1]
	v_pk_mul_f32 v[6:7], v[14:15], v[118:119] op_sel:[1,1] op_sel_hi:[1,0] neg_lo:[1,0]
	v_pk_fma_f32 v[2:3], v[14:15], v[118:119], v[6:7] op_sel_hi:[0,1,1]
	s_nop 0
	v_pk_mul_f32 v[6:7], v[118:119], v[86:87] op_sel:[1,1] op_sel_hi:[1,0] neg_lo:[1,0]
	v_pk_fma_f32 v[118:119], v[118:119], v[86:87], v[6:7] op_sel_hi:[0,1,1]
	v_pk_mul_f32 v[10:11], v[80:81], v[118:119] op_sel:[1,1] op_sel_hi:[1,0] neg_lo:[1,0]
	v_pk_fma_f32 v[6:7], v[80:81], v[118:119], v[10:11] op_sel_hi:[0,1,1]
	ds_write2_b64 v0, v[2:3], v[6:7] offset0:118 offset1:135
	v_pk_mul_f32 v[2:3], v[118:119], v[86:87] op_sel:[1,1] op_sel_hi:[1,0] neg_lo:[1,0]
	v_pk_fma_f32 v[118:119], v[118:119], v[86:87], v[2:3] op_sel_hi:[0,1,1]
	v_pk_mul_f32 v[6:7], v[112:113], v[118:119] op_sel:[1,1] op_sel_hi:[1,0] neg_lo:[1,0]
	v_pk_fma_f32 v[2:3], v[112:113], v[118:119], v[6:7] op_sel_hi:[0,1,1]
	s_nop 0
	v_pk_mul_f32 v[6:7], v[118:119], v[86:87] op_sel:[1,1] op_sel_hi:[1,0] neg_lo:[1,0]
	v_pk_fma_f32 v[118:119], v[118:119], v[86:87], v[6:7] op_sel_hi:[0,1,1]
	v_pk_mul_f32 v[112:113], v[108:109], v[118:119] op_sel:[1,1] op_sel_hi:[1,0] neg_lo:[1,0]
	v_pk_fma_f32 v[6:7], v[108:109], v[118:119], v[112:113] op_sel_hi:[0,1,1]
	ds_write2_b64 v0, v[2:3], v[6:7] offset0:152 offset1:169
	v_pk_mul_f32 v[2:3], v[118:119], v[86:87] op_sel:[1,1] op_sel_hi:[1,0] neg_lo:[1,0]
	v_pk_fma_f32 v[118:119], v[118:119], v[86:87], v[2:3] op_sel_hi:[0,1,1]
	v_pk_mul_f32 v[6:7], v[104:105], v[118:119] op_sel:[1,1] op_sel_hi:[1,0] neg_lo:[1,0]
	v_pk_fma_f32 v[2:3], v[104:105], v[118:119], v[6:7] op_sel_hi:[0,1,1]
	s_nop 0
	v_pk_mul_f32 v[6:7], v[118:119], v[86:87] op_sel:[1,1] op_sel_hi:[1,0] neg_lo:[1,0]
	v_pk_fma_f32 v[118:119], v[118:119], v[86:87], v[6:7] op_sel_hi:[0,1,1]
	v_pk_mul_f32 v[112:113], v[106:107], v[118:119] op_sel:[1,1] op_sel_hi:[1,0] neg_lo:[1,0]
	v_pk_fma_f32 v[6:7], v[106:107], v[118:119], v[112:113] op_sel_hi:[0,1,1]
	ds_write2_b64 v0, v[2:3], v[6:7] offset0:186 offset1:203
	v_pk_mul_f32 v[2:3], v[118:119], v[86:87] op_sel:[1,1] op_sel_hi:[1,0] neg_lo:[1,0]
	v_pk_fma_f32 v[118:119], v[118:119], v[86:87], v[2:3] op_sel_hi:[0,1,1]
	v_pk_mul_f32 v[6:7], v[8:9], v[118:119] op_sel:[1,1] op_sel_hi:[1,0] neg_lo:[1,0]
	v_pk_fma_f32 v[2:3], v[8:9], v[118:119], v[6:7] op_sel_hi:[0,1,1]
	s_nop 0
	v_pk_mul_f32 v[6:7], v[118:119], v[86:87] op_sel:[1,1] op_sel_hi:[1,0] neg_lo:[1,0]
	v_pk_fma_f32 v[118:119], v[118:119], v[86:87], v[6:7] op_sel_hi:[0,1,1]
	v_pk_mul_f32 v[8:9], v[114:115], v[118:119] op_sel:[1,1] op_sel_hi:[1,0] neg_lo:[1,0]
	v_pk_fma_f32 v[6:7], v[114:115], v[118:119], v[8:9] op_sel_hi:[0,1,1]
	ds_write2_b64 v0, v[2:3], v[6:7] offset0:220 offset1:237
	v_pk_mul_f32 v[2:3], v[118:119], v[86:87] op_sel:[1,1] op_sel_hi:[1,0] neg_lo:[1,0]
	v_pk_fma_f32 v[118:119], v[118:119], v[86:87], v[2:3] op_sel_hi:[0,1,1]
	v_pk_mul_f32 v[6:7], v[18:19], v[118:119] op_sel:[1,1] op_sel_hi:[1,0] neg_lo:[1,0]
	v_pk_fma_f32 v[2:3], v[18:19], v[118:119], v[6:7] op_sel_hi:[0,1,1]
	s_nop 0
	v_pk_mul_f32 v[6:7], v[118:119], v[86:87] op_sel:[1,1] op_sel_hi:[1,0] neg_lo:[1,0]
	v_pk_fma_f32 v[118:119], v[118:119], v[86:87], v[6:7] op_sel_hi:[0,1,1]
	v_pk_mul_f32 v[6:7], v[88:89], v[118:119] op_sel:[1,1] op_sel_hi:[1,0] neg_lo:[1,0]
	v_pk_fma_f32 v[118:119], v[88:89], v[118:119], v[6:7] op_sel_hi:[0,1,1]
	ds_write2_b64 v1, v[2:3], v[118:119] offset0:126 offset1:143
	s_waitcnt lgkmcnt(0)
	s_barrier
; #define LAS __attribute__((address_space(3)))
; DEV void fft_midx2(LAS cf* buf0, LAS cf* buf1, const unsigned* Kp, int blk) {
;     ...
;     LAS cf* p0 = buf0 + 17 * blk; LAS cf* p1 = buf1 + 17 * blk;
;     cf v[16], u[16];
; #pragma unroll
;     for (int q = 0; q < 16; ++q) { v[q] = p0[q]; u[q] = p1[q]; }
;     dft_regs<16, false>(v); dft_regs<16, false>(u);
	ds_read2_b64 v[68:71], v161 offset1:1
	ds_read2_b64 v[8:11], v162 offset1:1
	ds_read2_b64 v[72:75], v161 offset0:2 offset1:3
	ds_read2_b64 v[12:15], v162 offset0:2 offset1:3
	ds_read2_b64 v[76:79], v161 offset0:4 offset1:5
	ds_read2_b64 v[0:3], v162 offset0:4 offset1:5
	ds_read2_b64 v[80:83], v161 offset0:6 offset1:7
	ds_read2_b64 v[4:7], v162 offset0:6 offset1:7
	ds_read2_b64 v[84:87], v161 offset0:8 offset1:9
	ds_read2_b64 v[100:103], v162 offset0:8 offset1:9
	ds_read2_b64 v[88:91], v161 offset0:10 offset1:11
	ds_read2_b64 v[104:107], v162 offset0:10 offset1:11
	ds_read2_b64 v[92:95], v161 offset0:12 offset1:13
	ds_read2_b64 v[16:19], v162 offset0:12 offset1:13
	ds_read2_b64 v[96:99], v161 offset0:14 offset1:15
	ds_read2_b64 v[108:111], v162 offset0:14 offset1:15
	s_waitcnt lgkmcnt(7)
	v_pk_add_f32 v[112:113], v[68:69], v[84:85]
	v_pk_add_f32 v[68:69], v[68:69], v[84:85] neg_lo:[0,1] neg_hi:[0,1]
	v_pk_add_f32 v[114:115], v[70:71], v[86:87]
	v_pk_add_f32 v[70:71], v[70:71], v[86:87] neg_lo:[0,1] neg_hi:[0,1]
	v_pk_mul_f32 v[84:85], v[70:71], s[84:85] op_sel_hi:[1,0]
	v_pk_fma_f32 v[86:87], v[70:71], s[16:17], v[84:85] op_sel:[0,0,1] op_sel_hi:[1,0,0] neg_hi:[0,0,1]
	s_waitcnt lgkmcnt(5)
	v_pk_add_f32 v[70:71], v[72:73], v[88:89]
	v_pk_add_f32 v[72:73], v[72:73], v[88:89] neg_lo:[0,1] neg_hi:[0,1]
	v_pk_mul_f32 v[84:85], v[72:73], s[18:19] op_sel_hi:[1,0]
	v_pk_fma_f32 v[88:89], v[72:73], s[18:19], v[84:85] op_sel:[0,0,1] op_sel_hi:[1,0,0]
	v_pk_fma_f32 v[72:73], v[72:73], s[18:19], v[84:85] op_sel_hi:[1,0,0] neg_lo:[0,0,1] neg_hi:[0,0,1]
	v_pk_add_f32 v[84:85], v[74:75], v[90:91]
	v_pk_add_f32 v[74:75], v[74:75], v[90:91] neg_lo:[0,1] neg_hi:[0,1]
	v_mov_b32_e32 v89, v73
	v_pk_mul_f32 v[90:91], v[74:75], s[16:17] op_sel_hi:[1,0]
	v_pk_fma_f32 v[116:117], v[74:75], s[84:85], v[90:91] op_sel:[0,0,1] op_sel_hi:[1,0,0] neg_hi:[0,0,1]
	s_waitcnt lgkmcnt(3)
	v_pk_add_f32 v[74:75], v[76:77], v[92:93]
	v_pk_add_f32 v[76:77], v[76:77], v[92:93] neg_lo:[0,1] neg_hi:[0,1]
	v_pk_add_f32 v[90:91], v[76:77], 0 op_sel:[1,0] op_sel_hi:[0,0] neg_hi:[1,0]
	v_pk_add_f32 v[76:77], v[78:79], v[94:95]
	v_pk_add_f32 v[78:79], v[78:79], v[94:95] neg_lo:[0,1] neg_hi:[0,1]
	s_waitcnt lgkmcnt(1)
	v_pk_add_f32 v[94:95], v[82:83], v[98:99]
	v_pk_mul_f32 v[92:93], v[78:79], s[84:85] op_sel_hi:[0,1]
	v_pk_add_f32 v[82:83], v[82:83], v[98:99] neg_lo:[0,1] neg_hi:[0,1]
	v_pk_fma_f32 v[78:79], v[78:79], s[30:31], v[92:93] op_sel:[1,0,0] neg_lo:[0,0,1] neg_hi:[0,0,1]
	v_pk_add_f32 v[92:93], v[80:81], v[96:97]
	v_pk_add_f32 v[80:81], v[80:81], v[96:97] neg_lo:[0,1] neg_hi:[0,1]
	v_pk_mul_f32 v[96:97], v[82:83], s[24:25] op_sel_hi:[0,1]
	v_pk_fma_f32 v[82:83], v[82:83], s[34:35], v[96:97] op_sel:[1,0,0] neg_lo:[0,0,1] neg_hi:[0,0,1]
	v_pk_add_f32 v[96:97], v[112:113], v[74:75]
	v_pk_add_f32 v[74:75], v[112:113], v[74:75] neg_lo:[0,1] neg_hi:[0,1]
	v_mul_f32_e32 v72, 0x3f3504f3, v80
	v_pk_fma_f32 v[80:81], v[80:81], s[28:29], v[72:73] op_sel:[1,0,0] op_sel_hi:[1,1,0] neg_lo:[0,0,1] neg_hi:[0,0,1]
	v_pk_add_f32 v[72:73], v[88:89], v[80:81]
	v_pk_add_f32 v[112:113], v[114:115], v[76:77]
	v_pk_add_f32 v[114:115], v[114:115], v[76:77] neg_lo:[0,1] neg_hi:[0,1]
	v_pk_mul_f32 v[76:77], v[114:115], s[18:19] op_sel_hi:[1,0]
	v_pk_fma_f32 v[98:99], v[114:115], s[18:19], v[76:77] op_sel:[0,0,1] op_sel_hi:[1,0,0]
	v_pk_fma_f32 v[114:115], v[114:115], s[18:19], v[76:77] op_sel_hi:[1,0,0] neg_lo:[0,0,1] neg_hi:[0,0,1]
	v_pk_add_f32 v[76:77], v[70:71], v[92:93]
	v_pk_add_f32 v[70:71], v[70:71], v[92:93] neg_lo:[0,1] neg_hi:[0,1]
	v_mov_b32_e32 v99, v115
	v_pk_add_f32 v[92:93], v[70:71], 0 op_sel:[1,0] op_sel_hi:[0,0] neg_hi:[1,0]
	v_pk_add_f32 v[70:71], v[84:85], v[94:95]
	v_pk_add_f32 v[84:85], v[84:85], v[94:95] neg_lo:[0,1] neg_hi:[0,1]
	v_pk_add_f32 v[94:95], v[68:69], v[90:91]
	v_pk_add_f32 v[90:91], v[68:69], v[90:91] neg_lo:[0,1] neg_hi:[0,1]
	v_mul_f32_e32 v114, 0x3f3504f3, v84
	v_pk_fma_f32 v[84:85], v[84:85], s[28:29], v[114:115] op_sel:[1,0,0] op_sel_hi:[1,1,0] neg_lo:[0,0,1] neg_hi:[0,0,1]
	v_pk_add_f32 v[118:119], v[86:87], v[78:79]
	v_pk_add_f32 v[78:79], v[86:87], v[78:79] neg_lo:[0,1] neg_hi:[0,1]
	v_pk_mul_f32 v[86:87], v[78:79], s[18:19] op_sel_hi:[1,0]
	v_pk_fma_f32 v[68:69], v[78:79], s[18:19], v[86:87] op_sel:[0,0,1] op_sel_hi:[1,0,0] neg_hi:[0,0,1]
	v_pk_add_f32 v[78:79], v[88:89], v[80:81] neg_lo:[0,1] neg_hi:[0,1]
	v_pk_add_f32 v[88:89], v[96:97], v[76:77]
	v_pk_add_f32 v[76:77], v[96:97], v[76:77] neg_lo:[0,1] neg_hi:[0,1]
	v_pk_add_f32 v[80:81], v[78:79], 0 op_sel:[1,0] op_sel_hi:[0,0] neg_hi:[1,0]
	v_pk_add_f32 v[96:97], v[112:113], v[70:71]
	v_pk_add_f32 v[70:71], v[112:113], v[70:71] neg_lo:[0,1] neg_hi:[0,1]
	v_pk_add_f32 v[78:79], v[116:117], v[82:83]
	v_pk_add_f32 v[112:113], v[70:71], 0 op_sel:[1,0] op_sel_hi:[0,0] neg_hi:[1,0]
	v_pk_add_f32 v[82:83], v[116:117], v[82:83] neg_lo:[0,1] neg_hi:[0,1]
	v_pk_add_f32 v[70:71], v[74:75], v[92:93] neg_lo:[0,1] neg_hi:[0,1]
	v_pk_add_f32 v[116:117], v[74:75], v[92:93]
	v_mul_f32_e32 v114, 0x3f3504f3, v82
	v_pk_fma_f32 v[82:83], v[82:83], s[28:29], v[114:115] op_sel:[1,0,0] op_sel_hi:[1,1,0] neg_lo:[0,0,1] neg_hi:[0,0,1]
	v_pk_add_f32 v[92:93], v[98:99], v[84:85] neg_lo:[0,1] neg_hi:[0,1]
	v_pk_add_f32 v[114:115], v[98:99], v[84:85]
	v_pk_add_f32 v[98:99], v[92:93], 0 op_sel:[1,0] op_sel_hi:[0,0] neg_hi:[1,0]
	v_pk_add_f32 v[74:75], v[94:95], v[72:73]
	v_pk_add_f32 v[92:93], v[94:95], v[72:73] neg_lo:[0,1] neg_hi:[0,1]
	v_pk_add_f32 v[122:123], v[90:91], v[80:81]
	v_pk_add_f32 v[124:125], v[68:69], v[82:83]
	v_pk_add_f32 v[72:73], v[118:119], v[78:79]
	v_pk_add_f32 v[120:121], v[118:119], v[78:79] neg_lo:[0,1] neg_hi:[0,1]
; template <int R, bool INV> DEV void dft_regs(cf (&v)[R]) {
; #pragma unroll
;     for (int s = R; s >= 2; s >>= 1) {
;         const int h = s >> 1;
; #pragma unroll
;         for (int b = 0; b < R; b += s) {
; #pragma unroll
;             for (int k = 0; k < h; ++k) {
;                 const cf a = v[b + k], c = v[b + k + h];
;                 v[b + k] = a + c;
;                 const cf d = a - c;
;                 const int m = k * (32 / s);
;                 const float wr = tw_cos(m), wi = INV ? tw_sin(m) : -tw_sin(m);
;                 v[b + k + h] = cf{d.x * wr - d.y * wi, d.x * wi + d.y * wr};
;             }
;         }
;     }
; }
; DEV void fft_midx2(LAS cf* buf0, LAS cf* buf1, const unsigned* Kp, int blk) {
;     ...
;     dft_regs<16, false>(v); dft_regs<16, false>(u);
	v_pk_add_f32 v[86:87], v[88:89], v[96:97]
	v_pk_add_f32 v[78:79], v[120:121], 0 op_sel:[1,0] op_sel_hi:[0,0] neg_hi:[1,0]
	v_pk_add_f32 v[94:95], v[74:75], v[72:73]
	v_pk_add_f32 v[120:121], v[90:91], v[80:81] neg_lo:[0,1] neg_hi:[0,1]
	v_pk_add_f32 v[72:73], v[74:75], v[72:73] neg_lo:[0,1] neg_hi:[0,1]
	v_pk_add_f32 v[84:85], v[70:71], v[98:99]
	v_pk_add_f32 v[74:75], v[8:9], v[100:101]
	v_pk_add_f32 v[90:91], v[68:69], v[82:83] neg_lo:[0,1] neg_hi:[0,1]
	v_pk_add_f32 v[82:83], v[76:77], v[112:113]
	v_pk_add_f32 v[68:69], v[90:91], 0 op_sel:[1,0] op_sel_hi:[0,0] neg_hi:[1,0]
	v_pk_add_f32 v[112:113], v[76:77], v[112:113] neg_lo:[0,1] neg_hi:[0,1]
	v_pk_add_f32 v[90:91], v[88:89], v[96:97] neg_lo:[0,1] neg_hi:[0,1]
	v_pk_add_f32 v[88:89], v[116:117], v[114:115]
	v_pk_add_f32 v[114:115], v[116:117], v[114:115] neg_lo:[0,1] neg_hi:[0,1]
	v_mov_b32_e32 v96, v90
	v_mov_b32_e32 v97, v91
	v_mov_b32_e32 v90, v112
	v_mov_b32_e32 v91, v113
	v_mov_b32_e32 v112, v114
	v_mov_b32_e32 v113, v115
	v_pk_add_f32 v[80:81], v[70:71], v[98:99] neg_lo:[0,1] neg_hi:[0,1]
	v_pk_add_f32 v[8:9], v[8:9], v[100:101] neg_lo:[0,1] neg_hi:[0,1]
	v_mov_b32_e32 v114, v80
	v_mov_b32_e32 v115, v81
	v_mov_b32_e32 v80, v72
	v_mov_b32_e32 v81, v73
	v_pk_add_f32 v[118:119], v[92:93], v[78:79]
	v_pk_add_f32 v[78:79], v[92:93], v[78:79] neg_lo:[0,1] neg_hi:[0,1]
	v_mov_b32_e32 v72, v78
	v_mov_b32_e32 v73, v79
	v_pk_add_f32 v[70:71], v[122:123], v[124:125] neg_lo:[0,1] neg_hi:[0,1]
	v_pk_add_f32 v[76:77], v[122:123], v[124:125]
	v_pk_add_f32 v[98:99], v[120:121], v[68:69] neg_lo:[0,1] neg_hi:[0,1]
	v_pk_add_f32 v[78:79], v[120:121], v[68:69]
	v_pk_add_f32 v[68:69], v[10:11], v[102:103]
	v_pk_add_f32 v[10:11], v[10:11], v[102:103] neg_lo:[0,1] neg_hi:[0,1]
	v_pk_mul_f32 v[100:101], v[10:11], s[84:85] op_sel_hi:[1,0]
	v_pk_fma_f32 v[102:103], v[10:11], s[16:17], v[100:101] op_sel:[0,0,1] op_sel_hi:[1,0,0] neg_hi:[0,0,1]
	v_pk_add_f32 v[10:11], v[12:13], v[104:105]
	v_pk_add_f32 v[12:13], v[12:13], v[104:105] neg_lo:[0,1] neg_hi:[0,1]
	v_pk_mul_f32 v[100:101], v[12:13], s[18:19] op_sel_hi:[1,0]
	v_pk_fma_f32 v[104:105], v[12:13], s[18:19], v[100:101] op_sel:[0,0,1] op_sel_hi:[1,0,0] neg_hi:[0,0,1]
	v_pk_add_f32 v[12:13], v[14:15], v[106:107]
	v_pk_add_f32 v[14:15], v[14:15], v[106:107] neg_lo:[0,1] neg_hi:[0,1]
	v_pk_mul_f32 v[100:101], v[14:15], s[16:17] op_sel_hi:[1,0]
	v_pk_fma_f32 v[106:107], v[14:15], s[84:85], v[100:101] op_sel:[0,0,1] op_sel_hi:[1,0,0] neg_hi:[0,0,1]
	v_pk_add_f32 v[14:15], v[0:1], v[16:17]
	v_pk_add_f32 v[0:1], v[0:1], v[16:17] neg_lo:[0,1] neg_hi:[0,1]
	v_pk_add_f32 v[16:17], v[0:1], 0 op_sel:[1,0] op_sel_hi:[0,0] neg_hi:[1,0]
	v_pk_add_f32 v[0:1], v[2:3], v[18:19]
	v_pk_add_f32 v[2:3], v[2:3], v[18:19] neg_lo:[0,1] neg_hi:[0,1]
	v_pk_mul_f32 v[18:19], v[2:3], s[84:85] op_sel_hi:[0,1]
	v_pk_fma_f32 v[2:3], v[2:3], s[30:31], v[18:19] op_sel:[1,0,0] neg_lo:[0,0,1] neg_hi:[0,0,1]
	s_waitcnt lgkmcnt(0)
	v_pk_add_f32 v[18:19], v[4:5], v[108:109]
	v_pk_add_f32 v[4:5], v[4:5], v[108:109] neg_lo:[0,1] neg_hi:[0,1]
	v_mul_f32_e32 v100, 0x3f3504f3, v4
	v_pk_fma_f32 v[4:5], v[4:5], s[28:29], v[100:101] op_sel:[1,0,0] op_sel_hi:[1,1,0] neg_lo:[0,0,1] neg_hi:[0,0,1]
	v_pk_add_f32 v[100:101], v[6:7], v[110:111]
	v_pk_add_f32 v[6:7], v[6:7], v[110:111] neg_lo:[0,1] neg_hi:[0,1]
	v_pk_mul_f32 v[108:109], v[6:7], s[24:25] op_sel_hi:[0,1]
	v_pk_fma_f32 v[6:7], v[6:7], s[34:35], v[108:109] op_sel:[1,0,0] neg_lo:[0,0,1] neg_hi:[0,0,1]
	v_pk_add_f32 v[108:109], v[74:75], v[14:15]
	v_pk_add_f32 v[14:15], v[74:75], v[14:15] neg_lo:[0,1] neg_hi:[0,1]
	v_pk_add_f32 v[74:75], v[68:69], v[0:1]
	v_pk_add_f32 v[0:1], v[68:69], v[0:1] neg_lo:[0,1] neg_hi:[0,1]
	v_pk_mul_f32 v[68:69], v[0:1], s[18:19] op_sel_hi:[1,0]
	v_pk_fma_f32 v[110:111], v[0:1], s[18:19], v[68:69] op_sel:[0,0,1] op_sel_hi:[1,0,0] neg_hi:[0,0,1]
	v_pk_add_f32 v[68:69], v[10:11], v[18:19] neg_lo:[0,1] neg_hi:[0,1]
	v_pk_add_f32 v[0:1], v[10:11], v[18:19]
	v_pk_add_f32 v[10:11], v[68:69], 0 op_sel:[1,0] op_sel_hi:[0,0] neg_hi:[1,0]
	v_pk_add_f32 v[68:69], v[12:13], v[100:101]
	v_pk_add_f32 v[12:13], v[12:13], v[100:101] neg_lo:[0,1] neg_hi:[0,1]
	v_mul_f32_e32 v18, 0x3f3504f3, v12
	v_pk_fma_f32 v[12:13], v[12:13], s[28:29], v[18:19] op_sel:[1,0,0] op_sel_hi:[1,1,0] neg_lo:[0,0,1] neg_hi:[0,0,1]
	v_pk_add_f32 v[18:19], v[8:9], v[16:17]
	v_pk_add_f32 v[16:17], v[8:9], v[16:17] neg_lo:[0,1] neg_hi:[0,1]
	v_pk_add_f32 v[8:9], v[102:103], v[2:3]
	v_pk_add_f32 v[2:3], v[102:103], v[2:3] neg_lo:[0,1] neg_hi:[0,1]
	v_pk_mul_f32 v[100:101], v[2:3], s[18:19] op_sel_hi:[1,0]
	v_pk_fma_f32 v[102:103], v[2:3], s[18:19], v[100:101] op_sel:[0,0,1] op_sel_hi:[1,0,0] neg_hi:[0,0,1]
	v_pk_add_f32 v[2:3], v[104:105], v[4:5]
	v_pk_add_f32 v[4:5], v[104:105], v[4:5] neg_lo:[0,1] neg_hi:[0,1]
	v_pk_add_f32 v[100:101], v[4:5], 0 op_sel:[1,0] op_sel_hi:[0,0] neg_hi:[1,0]
	v_pk_add_f32 v[4:5], v[106:107], v[6:7]
	v_pk_add_f32 v[6:7], v[106:107], v[6:7] neg_lo:[0,1] neg_hi:[0,1]
	v_mul_f32_e32 v104, 0x3f3504f3, v6
	v_pk_fma_f32 v[6:7], v[6:7], s[28:29], v[104:105] op_sel:[1,0,0] op_sel_hi:[1,1,0] neg_lo:[0,0,1] neg_hi:[0,0,1]
	v_pk_add_f32 v[104:105], v[108:109], v[0:1]
	v_pk_add_f32 v[0:1], v[108:109], v[0:1] neg_lo:[0,1] neg_hi:[0,1]
	v_pk_add_f32 v[166:167], v[102:103], v[6:7]
	v_pk_add_f32 v[6:7], v[102:103], v[6:7] neg_lo:[0,1] neg_hi:[0,1]
	v_pk_add_f32 v[168:169], v[6:7], 0 op_sel:[1,0] op_sel_hi:[0,0] neg_hi:[1,0]
	v_pk_add_f32 v[108:109], v[74:75], v[68:69]
	v_pk_add_f32 v[68:69], v[74:75], v[68:69] neg_lo:[0,1] neg_hi:[0,1]
	v_pk_add_f32 v[74:75], v[68:69], 0 op_sel:[1,0] op_sel_hi:[0,0] neg_hi:[1,0]
	v_pk_add_f32 v[122:123], v[104:105], v[108:109]
; DEV cf kunpack(unsigned w) { return cf{U2F(w << 16), U2F(w & 0xffff0000u)}; }
; DEV void fft_midx2(LAS cf* buf0, LAS cf* buf1, const unsigned* Kp, int blk) {
;     ...
;     dft_regs<16, false>(v); dft_regs<16, false>(u);
;     cf w[16], x[16];
;     u32x4 kw[4];
; #pragma unroll
;     for (int j = 0; j < 4; ++j) kw[j] = *(const u32x4*)(Kp + base + 4 * j);
; #pragma unroll
;     for (int p = 0; p < 16; ++p) { const cf k = kunpack(kw[p >> 2][p & 3]); w[p] = cmul(v[BR16[p]], k); x[p] = cmul(u[BR16[p]], k); }
	v_pk_add_f32 v[68:69], v[14:15], v[10:11]
	v_pk_add_f32 v[10:11], v[14:15], v[10:11] neg_lo:[0,1] neg_hi:[0,1]
	v_pk_add_f32 v[108:109], v[104:105], v[108:109] neg_lo:[0,1] neg_hi:[0,1]
	v_pk_add_f32 v[116:117], v[110:111], v[12:13]
	v_pk_add_f32 v[12:13], v[110:111], v[12:13] neg_lo:[0,1] neg_hi:[0,1]
	v_pk_add_f32 v[110:111], v[12:13], 0 op_sel:[1,0] op_sel_hi:[0,0] neg_hi:[1,0]
	v_pk_add_f32 v[12:13], v[18:19], v[2:3]
	v_pk_add_f32 v[2:3], v[18:19], v[2:3] neg_lo:[0,1] neg_hi:[0,1]
	v_pk_add_f32 v[106:107], v[0:1], v[74:75] neg_lo:[0,1] neg_hi:[0,1]
	v_pk_add_f32 v[124:125], v[8:9], v[4:5]
	v_pk_add_f32 v[4:5], v[8:9], v[4:5] neg_lo:[0,1] neg_hi:[0,1]
	v_pk_add_f32 v[8:9], v[16:17], v[100:101] neg_lo:[0,1] neg_hi:[0,1]
	v_pk_add_f32 v[164:165], v[4:5], 0 op_sel:[1,0] op_sel_hi:[0,0] neg_hi:[1,0]
	v_pk_add_f32 v[4:5], v[16:17], v[100:101]
	v_pk_add_f32 v[18:19], v[68:69], v[116:117] neg_lo:[0,1] neg_hi:[0,1]
	v_pk_add_f32 v[126:127], v[12:13], v[124:125]
	v_pk_add_f32 v[14:15], v[10:11], v[110:111]
	v_mov_b32_e32 v104, v18
	v_mov_b32_e32 v105, v19
	v_pk_add_f32 v[100:101], v[0:1], v[74:75]
	v_pk_add_f32 v[0:1], v[10:11], v[110:111] neg_lo:[0,1] neg_hi:[0,1]
	v_pk_add_f32 v[10:11], v[8:9], v[168:169]
	v_pk_add_f32 v[92:93], v[68:69], v[116:117]
	v_pk_add_f32 v[120:121], v[2:3], v[164:165]
	v_pk_add_f32 v[16:17], v[12:13], v[124:125] neg_lo:[0,1] neg_hi:[0,1]
	s_mov_b32 s28, s95
	s_mov_b32 s29, s94
	v_pk_add_f32 v[110:111], v[2:3], v[164:165] neg_lo:[0,1] neg_hi:[0,1]
	v_pk_add_f32 v[124:125], v[4:5], v[166:167]
	v_pk_add_f32 v[102:103], v[4:5], v[166:167] neg_lo:[0,1] neg_hi:[0,1]
	v_mov_b32_e32 v166, v98
	v_mov_b32_e32 v167, v99
	v_pk_add_f32 v[18:19], v[8:9], v[168:169] neg_lo:[0,1] neg_hi:[0,1]
	s_nop 0
	s_waitcnt vmcnt(0)
	v_lshlrev_b32_e32 v98, 16, v182
	v_and_b32_e32 v99, 0xffff0000, v182
	v_lshlrev_b32_e32 v12, 16, v183
	v_and_b32_e32 v13, 0xffff0000, v183
	v_pk_mul_f32 v[168:169], v[86:87], v[98:99] op_sel:[1,1] op_sel_hi:[1,0] neg_lo:[1,0]
	v_pk_fma_f32 v[164:165], v[86:87], v[98:99], v[168:169] op_sel_hi:[0,1,1]
	s_nop 0
	v_pk_mul_f32 v[168:169], v[122:123], v[98:99] op_sel:[1,1] op_sel_hi:[1,0] neg_lo:[1,0]
	v_pk_fma_f32 v[86:87], v[122:123], v[98:99], v[168:169] op_sel_hi:[0,1,1]
	v_pk_mul_f32 v[98:99], v[94:95], v[12:13] op_sel:[1,1] op_sel_hi:[1,0] neg_lo:[1,0]
	v_pk_fma_f32 v[94:95], v[94:95], v[12:13], v[98:99] op_sel_hi:[0,1,1]
	s_nop 0
	v_pk_mul_f32 v[98:99], v[126:127], v[12:13] op_sel:[1,1] op_sel_hi:[1,0] neg_lo:[1,0]
	v_pk_fma_f32 v[12:13], v[126:127], v[12:13], v[98:99] op_sel_hi:[0,1,1]
	s_nop 0
	v_lshlrev_b32_e32 v98, 16, v184
	v_and_b32_e32 v99, 0xffff0000, v184
	v_lshlrev_b32_e32 v74, 16, v185
	v_and_b32_e32 v75, 0xffff0000, v185
	v_pk_mul_f32 v[126:127], v[88:89], v[98:99] op_sel:[1,1] op_sel_hi:[1,0] neg_lo:[1,0]
	v_pk_fma_f32 v[122:123], v[88:89], v[98:99], v[126:127] op_sel_hi:[0,1,1]
	s_nop 0
	v_pk_mul_f32 v[126:127], v[92:93], v[98:99] op_sel:[1,1] op_sel_hi:[1,0] neg_lo:[1,0]
	v_pk_fma_f32 v[88:89], v[92:93], v[98:99], v[126:127] op_sel_hi:[0,1,1]
	v_pk_mul_f32 v[98:99], v[76:77], v[74:75] op_sel:[1,1] op_sel_hi:[1,0] neg_lo:[1,0]
	v_pk_fma_f32 v[76:77], v[76:77], v[74:75], v[98:99] op_sel_hi:[0,1,1]
	s_nop 0
	v_pk_mul_f32 v[98:99], v[124:125], v[74:75] op_sel:[1,1] op_sel_hi:[1,0] neg_lo:[1,0]
	v_pk_fma_f32 v[74:75], v[124:125], v[74:75], v[98:99] op_sel_hi:[0,1,1]
	s_nop 0
	v_lshlrev_b32_e32 v98, 16, v178
	v_and_b32_e32 v99, 0xffff0000, v178
	v_lshlrev_b32_e32 v68, 16, v179
	v_and_b32_e32 v69, 0xffff0000, v179
	v_pk_mul_f32 v[124:125], v[82:83], v[98:99] op_sel:[1,1] op_sel_hi:[1,0] neg_lo:[1,0]
	v_pk_fma_f32 v[92:93], v[82:83], v[98:99], v[124:125] op_sel_hi:[0,1,1]
	s_nop 0
	v_pk_mul_f32 v[124:125], v[100:101], v[98:99] op_sel:[1,1] op_sel_hi:[1,0] neg_lo:[1,0]
	v_pk_fma_f32 v[82:83], v[100:101], v[98:99], v[124:125] op_sel_hi:[0,1,1]
	v_pk_mul_f32 v[98:99], v[118:119], v[68:69] op_sel:[1,1] op_sel_hi:[1,0] neg_lo:[1,0]
	v_pk_fma_f32 v[118:119], v[118:119], v[68:69], v[98:99] op_sel_hi:[0,1,1]
	s_nop 0
	v_pk_mul_f32 v[98:99], v[120:121], v[68:69] op_sel:[1,1] op_sel_hi:[1,0] neg_lo:[1,0]
	v_pk_fma_f32 v[100:101], v[120:121], v[68:69], v[98:99] op_sel_hi:[0,1,1]
	s_nop 0
	v_lshlrev_b32_e32 v98, 16, v180
	v_and_b32_e32 v99, 0xffff0000, v180
	v_lshlrev_b32_e32 v116, 16, v181
	v_and_b32_e32 v117, 0xffff0000, v181
	v_pk_mul_f32 v[120:121], v[84:85], v[98:99] op_sel:[1,1] op_sel_hi:[1,0] neg_lo:[1,0]
	v_pk_fma_f32 v[68:69], v[84:85], v[98:99], v[120:121] op_sel_hi:[0,1,1]
	s_nop 0
	v_pk_mul_f32 v[120:121], v[14:15], v[98:99] op_sel:[1,1] op_sel_hi:[1,0] neg_lo:[1,0]
	v_pk_fma_f32 v[84:85], v[14:15], v[98:99], v[120:121] op_sel_hi:[0,1,1]
	v_pk_mul_f32 v[98:99], v[78:79], v[116:117] op_sel:[1,1] op_sel_hi:[1,0] neg_lo:[1,0]
	v_pk_fma_f32 v[78:79], v[78:79], v[116:117], v[98:99] op_sel_hi:[0,1,1]
	s_nop 0
	v_pk_mul_f32 v[98:99], v[10:11], v[116:117] op_sel:[1,1] op_sel_hi:[1,0] neg_lo:[1,0]
	v_pk_fma_f32 v[116:117], v[10:11], v[116:117], v[98:99] op_sel_hi:[0,1,1]
	s_nop 0
	v_lshlrev_b32_e32 v98, 16, v174
	v_and_b32_e32 v99, 0xffff0000, v174
	v_pk_mul_f32 v[14:15], v[96:97], v[98:99] op_sel:[1,1] op_sel_hi:[1,0] neg_lo:[1,0]
	v_pk_fma_f32 v[96:97], v[96:97], v[98:99], v[14:15] op_sel_hi:[0,1,1]
	v_lshlrev_b32_e32 v4, 16, v175
	v_pk_mul_f32 v[14:15], v[108:109], v[98:99] op_sel:[1,1] op_sel_hi:[1,0] neg_lo:[1,0]
	v_pk_fma_f32 v[98:99], v[108:109], v[98:99], v[14:15] op_sel_hi:[0,1,1]
	v_and_b32_e32 v5, 0xffff0000, v175
	v_pk_mul_f32 v[108:109], v[80:81], v[4:5] op_sel:[1,1] op_sel_hi:[1,0] neg_lo:[1,0]
	v_pk_fma_f32 v[80:81], v[80:81], v[4:5], v[108:109] op_sel_hi:[0,1,1]
	s_nop 0
; DEV cf kunpack(unsigned w) { return cf{U2F(w << 16), U2F(w & 0xffff0000u)}; }
; template <int R, bool INV> DEV void dft_regs(cf (&v)[R]) {
; #pragma unroll
;     for (int s = R; s >= 2; s >>= 1) {
;         const int h = s >> 1;
; #pragma unroll
;         for (int b = 0; b < R; b += s) {
; #pragma unroll
;             for (int k = 0; k < h; ++k) {
;                 const cf a = v[b + k], c = v[b + k + h];
;                 v[b + k] = a + c;
;                 const cf d = a - c;
;                 const int m = k * (32 / s);
;                 const float wr = tw_cos(m), wi = INV ? tw_sin(m) : -tw_sin(m);
;                 v[b + k + h] = cf{d.x * wr - d.y * wi, d.x * wi + d.y * wr};
;             }
;         }
;     }
; DEV void fft_midx2(LAS cf* buf0, LAS cf* buf1, const unsigned* Kp, int blk) {
;     ...
; #pragma unroll
;     for (int p = 0; p < 16; ++p) { const cf k = kunpack(kw[p >> 2][p & 3]); w[p] = cmul(v[BR16[p]], k); x[p] = cmul(u[BR16[p]], k); }
;     dft_regs<16, true>(w); dft_regs<16, true>(x);
; #pragma unroll
;     for (int q = 0; q < 16; ++q) { p0[q] = w[BR16[q]]; p1[q] = x[BR16[q]]; }
	v_pk_mul_f32 v[14:15], v[16:17], v[4:5] op_sel:[1,1] op_sel_hi:[1,0] neg_lo:[1,0]
	v_pk_fma_f32 v[108:109], v[16:17], v[4:5], v[14:15] op_sel_hi:[0,1,1]
	v_lshlrev_b32_e32 v4, 16, v176
	v_and_b32_e32 v5, 0xffff0000, v176
	v_pk_mul_f32 v[8:9], v[112:113], v[4:5] op_sel:[1,1] op_sel_hi:[1,0] neg_lo:[1,0]
	v_pk_fma_f32 v[14:15], v[112:113], v[4:5], v[8:9] op_sel_hi:[0,1,1]
	s_nop 0
	v_pk_mul_f32 v[8:9], v[104:105], v[4:5] op_sel:[1,1] op_sel_hi:[1,0] neg_lo:[1,0]
	v_pk_fma_f32 v[104:105], v[104:105], v[4:5], v[8:9] op_sel_hi:[0,1,1]
	v_lshlrev_b32_e32 v4, 16, v177
	v_and_b32_e32 v5, 0xffff0000, v177
	v_pk_mul_f32 v[8:9], v[70:71], v[4:5] op_sel:[1,1] op_sel_hi:[1,0] neg_lo:[1,0]
	v_pk_fma_f32 v[6:7], v[70:71], v[4:5], v[8:9] op_sel_hi:[0,1,1]
	v_pk_mul_f32 v[70:71], v[102:103], v[4:5] op_sel:[1,1] op_sel_hi:[1,0] neg_lo:[1,0]
	v_pk_fma_f32 v[8:9], v[102:103], v[4:5], v[70:71] op_sel_hi:[0,1,1]
	v_lshlrev_b32_e32 v4, 16, v170
	v_and_b32_e32 v5, 0xffff0000, v170
	v_lshlrev_b32_e32 v16, 16, v171
	v_and_b32_e32 v17, 0xffff0000, v171
	v_pk_mul_f32 v[70:71], v[90:91], v[4:5] op_sel:[1,1] op_sel_hi:[1,0] neg_lo:[1,0]
	v_pk_fma_f32 v[120:121], v[90:91], v[4:5], v[70:71] op_sel_hi:[0,1,1]
	s_nop 0
	v_pk_mul_f32 v[70:71], v[106:107], v[4:5] op_sel:[1,1] op_sel_hi:[1,0] neg_lo:[1,0]
	v_pk_fma_f32 v[102:103], v[106:107], v[4:5], v[70:71] op_sel_hi:[0,1,1]
	v_pk_mul_f32 v[106:107], v[72:73], v[16:17] op_sel:[1,1] op_sel_hi:[1,0] neg_lo:[1,0]
	v_pk_fma_f32 v[4:5], v[72:73], v[16:17], v[106:107] op_sel_hi:[0,1,1]
	s_nop 0
	v_pk_mul_f32 v[106:107], v[110:111], v[16:17] op_sel:[1,1] op_sel_hi:[1,0] neg_lo:[1,0]
	v_pk_fma_f32 v[110:111], v[110:111], v[16:17], v[106:107] op_sel_hi:[0,1,1]
	v_lshlrev_b32_e32 v16, 16, v172
	v_and_b32_e32 v17, 0xffff0000, v172
	v_pk_mul_f32 v[72:73], v[114:115], v[16:17] op_sel:[1,1] op_sel_hi:[1,0] neg_lo:[1,0]
	v_pk_fma_f32 v[106:107], v[114:115], v[16:17], v[72:73] op_sel_hi:[0,1,1]
	v_pk_mul_f32 v[114:115], v[0:1], v[16:17] op_sel:[1,1] op_sel_hi:[1,0] neg_lo:[1,0]
	v_pk_fma_f32 v[112:113], v[0:1], v[16:17], v[114:115] op_sel_hi:[0,1,1]
	v_lshlrev_b32_e32 v16, 16, v173
	v_and_b32_e32 v17, 0xffff0000, v173
	v_pk_mul_f32 v[0:1], v[166:167], v[16:17] op_sel:[1,1] op_sel_hi:[1,0] neg_lo:[1,0]
	v_pk_fma_f32 v[2:3], v[166:167], v[16:17], v[0:1] op_sel_hi:[0,1,1]
	s_nop 0
	v_pk_mul_f32 v[0:1], v[18:19], v[16:17] op_sel:[1,1] op_sel_hi:[1,0] neg_lo:[1,0]
	v_pk_fma_f32 v[18:19], v[18:19], v[16:17], v[0:1] op_sel_hi:[0,1,1]
	v_pk_add_f32 v[0:1], v[164:165], v[96:97]
	v_pk_add_f32 v[16:17], v[164:165], v[96:97] neg_lo:[0,1] neg_hi:[0,1]
	v_pk_add_f32 v[114:115], v[94:95], v[80:81] neg_lo:[0,1] neg_hi:[0,1]
	v_pk_mul_f32 v[96:97], v[114:115], s[84:85] op_sel_hi:[1,0]
	v_pk_add_f32 v[72:73], v[94:95], v[80:81]
	v_pk_fma_f32 v[70:71], v[114:115], s[16:17], v[96:97] op_sel:[0,0,1] op_sel_hi:[1,0,0] neg_lo:[0,0,1]
	v_pk_add_f32 v[114:115], v[122:123], v[14:15]
	v_pk_add_f32 v[14:15], v[122:123], v[14:15] neg_lo:[0,1] neg_hi:[0,1]
	v_pk_mul_f32 v[96:97], v[14:15], s[18:19] op_sel_hi:[1,0]
	v_pk_fma_f32 v[80:81], v[14:15], s[18:19], v[96:97] op_sel:[0,0,1] op_sel_hi:[1,0,0] neg_lo:[0,0,1]
	v_pk_add_f32 v[14:15], v[76:77], v[6:7]
	v_pk_add_f32 v[6:7], v[76:77], v[6:7] neg_lo:[0,1] neg_hi:[0,1]
	v_pk_mul_f32 v[96:97], v[6:7], s[16:17] op_sel_hi:[1,0]
	v_pk_fma_f32 v[94:95], v[6:7], s[84:85], v[96:97] op_sel:[0,0,1] op_sel_hi:[1,0,0] neg_lo:[0,0,1]
	v_pk_add_f32 v[6:7], v[92:93], v[120:121]
	v_pk_add_f32 v[120:121], v[92:93], v[120:121] neg_lo:[0,1] neg_hi:[0,1]
	v_pk_add_f32 v[96:97], v[120:121], 0 op_sel:[1,0] op_sel_hi:[0,0] neg_lo:[1,0]
	v_pk_add_f32 v[92:93], v[118:119], v[4:5]
	v_pk_add_f32 v[4:5], v[118:119], v[4:5] neg_lo:[0,1] neg_hi:[0,1]
	v_pk_mul_f32 v[90:91], v[4:5], s[24:25] op_sel:[1,0]
	v_pk_fma_f32 v[4:5], v[4:5], s[0:1], v[90:91] op_sel_hi:[0,1,1] neg_lo:[0,0,1] neg_hi:[0,0,1]
	v_pk_add_f32 v[90:91], v[68:69], v[106:107]
	v_pk_add_f32 v[106:107], v[68:69], v[106:107] neg_lo:[0,1] neg_hi:[0,1]
	v_mul_f32_e32 v76, 0x3f3504f3, v107
	v_pk_fma_f32 v[106:107], v[106:107], s[96:97], v[76:77] op_sel_hi:[0,1,0] neg_lo:[0,0,1] neg_hi:[0,0,1]
	v_pk_add_f32 v[76:77], v[78:79], v[2:3]
	v_pk_add_f32 v[2:3], v[78:79], v[2:3] neg_lo:[0,1] neg_hi:[0,1]
	v_pk_mul_f32 v[78:79], v[2:3], s[84:85] op_sel:[1,0]
	v_pk_fma_f32 v[2:3], v[2:3], s[88:89], v[78:79] op_sel_hi:[0,1,1] neg_lo:[0,0,1] neg_hi:[0,0,1]
	v_pk_add_f32 v[78:79], v[0:1], v[6:7]
	v_pk_add_f32 v[0:1], v[0:1], v[6:7] neg_lo:[0,1] neg_hi:[0,1]
	v_pk_add_f32 v[6:7], v[72:73], v[92:93] neg_lo:[0,1] neg_hi:[0,1]
	v_pk_add_f32 v[68:69], v[72:73], v[92:93]
	v_pk_mul_f32 v[72:73], v[6:7], s[18:19] op_sel_hi:[1,0]
	v_pk_fma_f32 v[92:93], v[6:7], s[18:19], v[72:73] op_sel:[0,0,1] op_sel_hi:[1,0,0] neg_lo:[0,0,1]
	v_pk_add_f32 v[72:73], v[114:115], v[90:91] neg_lo:[0,1] neg_hi:[0,1]
	v_pk_add_f32 v[6:7], v[114:115], v[90:91]
	v_pk_add_f32 v[114:115], v[72:73], 0 op_sel:[1,0] op_sel_hi:[0,0] neg_lo:[1,0]
	v_pk_add_f32 v[72:73], v[14:15], v[76:77]
	v_pk_add_f32 v[14:15], v[14:15], v[76:77] neg_lo:[0,1] neg_hi:[0,1]
	v_mul_f32_e32 v90, 0x3f3504f3, v15
	v_pk_fma_f32 v[14:15], v[14:15], s[96:97], v[90:91] op_sel_hi:[0,1,0] neg_lo:[0,0,1] neg_hi:[0,0,1]
	v_pk_add_f32 v[90:91], v[16:17], v[96:97]
	v_pk_add_f32 v[16:17], v[16:17], v[96:97] neg_lo:[0,1] neg_hi:[0,1]
	v_pk_add_f32 v[76:77], v[70:71], v[4:5]
	v_pk_add_f32 v[4:5], v[70:71], v[4:5] neg_lo:[0,1] neg_hi:[0,1]
	v_pk_mul_f32 v[96:97], v[4:5], s[18:19] op_sel_hi:[1,0]
	v_pk_fma_f32 v[70:71], v[4:5], s[18:19], v[96:97] op_sel:[0,0,1] op_sel_hi:[1,0,0] neg_lo:[0,0,1]
	v_pk_add_f32 v[4:5], v[80:81], v[106:107]
; template <int R, bool INV> DEV void dft_regs(cf (&v)[R]) {
; #pragma unroll
;     for (int s = R; s >= 2; s >>= 1) {
;         const int h = s >> 1;
; #pragma unroll
;         for (int b = 0; b < R; b += s) {
; #pragma unroll
;             for (int k = 0; k < h; ++k) {
;                 const cf a = v[b + k], c = v[b + k + h];
;                 v[b + k] = a + c;
;                 const cf d = a - c;
;                 const int m = k * (32 / s);
;                 const float wr = tw_cos(m), wi = INV ? tw_sin(m) : -tw_sin(m);
;                 v[b + k + h] = cf{d.x * wr - d.y * wi, d.x * wi + d.y * wr};
;             }
;         }
;     }
; DEV void fft_midx2(LAS cf* buf0, LAS cf* buf1, const unsigned* Kp, int blk) {
;     ...
;     dft_regs<16, true>(w); dft_regs<16, true>(x);
; #pragma unroll
;     for (int q = 0; q < 16; ++q) { p0[q] = w[BR16[q]]; p1[q] = x[BR16[q]]; }
	v_pk_add_f32 v[106:107], v[80:81], v[106:107] neg_lo:[0,1] neg_hi:[0,1]
	v_pk_add_f32 v[10:11], v[90:91], v[4:5]
	v_pk_add_f32 v[96:97], v[106:107], 0 op_sel:[1,0] op_sel_hi:[0,0] neg_lo:[1,0]
	v_pk_add_f32 v[4:5], v[90:91], v[4:5] neg_lo:[0,1] neg_hi:[0,1]
	v_pk_add_f32 v[106:107], v[94:95], v[2:3]
	v_pk_add_f32 v[2:3], v[94:95], v[2:3] neg_lo:[0,1] neg_hi:[0,1]
	v_pk_add_f32 v[118:119], v[76:77], v[106:107]
	v_mul_f32_e32 v80, 0x3f3504f3, v3
	v_pk_fma_f32 v[2:3], v[2:3], s[96:97], v[80:81] op_sel_hi:[0,1,0] neg_lo:[0,0,1] neg_hi:[0,0,1]
	v_pk_add_f32 v[80:81], v[78:79], v[6:7]
	v_pk_add_f32 v[6:7], v[78:79], v[6:7] neg_lo:[0,1] neg_hi:[0,1]
	v_pk_add_f32 v[122:123], v[70:71], v[2:3]
	v_pk_add_f32 v[2:3], v[70:71], v[2:3] neg_lo:[0,1] neg_hi:[0,1]
	v_pk_add_f32 v[78:79], v[2:3], 0 op_sel:[1,0] op_sel_hi:[0,0] neg_lo:[1,0]
	v_pk_add_f32 v[94:95], v[68:69], v[72:73]
	v_pk_add_f32 v[68:69], v[68:69], v[72:73] neg_lo:[0,1] neg_hi:[0,1]
	v_pk_add_f32 v[72:73], v[68:69], 0 op_sel:[1,0] op_sel_hi:[0,0] neg_lo:[1,0]
	v_pk_add_f32 v[120:121], v[16:17], v[96:97]
	v_pk_add_f32 v[68:69], v[0:1], v[114:115]
	v_pk_add_f32 v[114:115], v[0:1], v[114:115] neg_lo:[0,1] neg_hi:[0,1]
	v_pk_add_f32 v[2:3], v[80:81], v[94:95] neg_lo:[0,1] neg_hi:[0,1]
	v_pk_add_f32 v[70:71], v[92:93], v[14:15]
	v_pk_add_f32 v[0:1], v[92:93], v[14:15] neg_lo:[0,1] neg_hi:[0,1]
	v_pk_add_f32 v[124:125], v[80:81], v[94:95]
	v_pk_add_f32 v[14:15], v[0:1], 0 op_sel:[1,0] op_sel_hi:[0,0] neg_lo:[1,0]
	v_pk_add_f32 v[80:81], v[6:7], v[72:73]
	v_pk_add_f32 v[90:91], v[76:77], v[106:107] neg_lo:[0,1] neg_hi:[0,1]
	v_pk_add_f32 v[76:77], v[90:91], 0 op_sel:[1,0] op_sel_hi:[0,0] neg_lo:[1,0]
	v_pk_add_f32 v[90:91], v[16:17], v[96:97] neg_lo:[0,1] neg_hi:[0,1]
	v_pk_add_f32 v[126:127], v[4:5], v[76:77]
	v_pk_add_f32 v[16:17], v[4:5], v[76:77] neg_lo:[0,1] neg_hi:[0,1]
	v_pk_add_f32 v[76:77], v[120:121], v[122:123]
	v_pk_add_f32 v[164:165], v[90:91], v[78:79]
	v_mov_b32_e32 v106, v2
	v_mov_b32_e32 v107, v3
	v_mov_b32_e32 v0, v2
	v_mov_b32_e32 v1, v3
	v_pk_add_f32 v[4:5], v[6:7], v[72:73] neg_lo:[0,1] neg_hi:[0,1]
	v_pk_add_f32 v[94:95], v[68:69], v[70:71]
	v_pk_add_f32 v[68:69], v[68:69], v[70:71] neg_lo:[0,1] neg_hi:[0,1]
	v_mov_b32_e32 v2, v4
	v_mov_b32_e32 v3, v5
	v_pk_add_f32 v[92:93], v[114:115], v[14:15]
	v_mov_b32_e32 v70, v68
	v_mov_b32_e32 v71, v69
	v_pk_add_f32 v[6:7], v[114:115], v[14:15] neg_lo:[0,1] neg_hi:[0,1]
	v_pk_add_f32 v[72:73], v[10:11], v[118:119]
	v_pk_add_f32 v[78:79], v[90:91], v[78:79] neg_lo:[0,1] neg_hi:[0,1]
	v_mov_b32_e32 v114, v6
	v_mov_b32_e32 v115, v7
	v_pk_add_f32 v[14:15], v[10:11], v[118:119] neg_lo:[0,1] neg_hi:[0,1]
	v_mov_b32_e32 v10, v14
	v_mov_b32_e32 v11, v15
	v_mov_b32_e32 v118, v14
	v_mov_b32_e32 v119, v15
	v_mov_b32_e32 v107, v1
	v_mov_b32_e32 v96, v16
	v_mov_b32_e32 v97, v17
	v_pk_add_f32 v[14:15], v[120:121], v[122:123] neg_lo:[0,1] neg_hi:[0,1]
	v_mov_b32_e32 v11, v119
	v_mov_b32_e32 v69, v71
	v_mov_b32_e32 v122, v14
	v_mov_b32_e32 v123, v15
	v_mov_b32_e32 v120, v14
	v_mov_b32_e32 v121, v15
	v_pk_add_f32 v[90:91], v[86:87], v[98:99]
	v_pk_add_f32 v[86:87], v[86:87], v[98:99] neg_lo:[0,1] neg_hi:[0,1]
	v_mov_b32_e32 v123, v121
	v_mov_b32_e32 v166, v86
	v_mov_b32_e32 v167, v87
	v_pk_add_f32 v[86:87], v[12:13], v[108:109]
	v_pk_add_f32 v[12:13], v[12:13], v[108:109] neg_lo:[0,1] neg_hi:[0,1]
	v_mov_b32_e32 v17, v97
	v_pk_mul_f32 v[98:99], v[12:13], s[84:85] op_sel_hi:[1,0]
	v_pk_fma_f32 v[108:109], v[12:13], s[16:17], v[98:99] op_sel:[0,0,1] op_sel_hi:[1,0,0] neg_lo:[0,0,1]
	v_pk_add_f32 v[12:13], v[88:89], v[104:105]
	v_pk_add_f32 v[88:89], v[88:89], v[104:105] neg_lo:[0,1] neg_hi:[0,1]
	v_pk_mul_f32 v[98:99], v[88:89], s[18:19] op_sel_hi:[1,0]
	v_pk_fma_f32 v[104:105], v[88:89], s[18:19], v[98:99] op_sel:[0,0,1] op_sel_hi:[1,0,0] neg_lo:[0,0,1]
	v_pk_add_f32 v[88:89], v[74:75], v[8:9]
	v_pk_add_f32 v[74:75], v[74:75], v[8:9] neg_lo:[0,1] neg_hi:[0,1]
	v_pk_mul_f32 v[98:99], v[74:75], s[16:17] op_sel_hi:[1,0]
	v_pk_fma_f32 v[8:9], v[74:75], s[84:85], v[98:99] op_sel:[0,0,1] op_sel_hi:[1,0,0] neg_lo:[0,0,1]
	v_pk_add_f32 v[74:75], v[82:83], v[102:103]
	v_pk_add_f32 v[82:83], v[82:83], v[102:103] neg_lo:[0,1] neg_hi:[0,1]
	v_pk_add_f32 v[102:103], v[116:117], v[18:19]
	v_pk_add_f32 v[116:117], v[116:117], v[18:19] neg_lo:[0,1] neg_hi:[0,1]
	v_pk_add_f32 v[98:99], v[82:83], 0 op_sel:[1,0] op_sel_hi:[0,0] neg_lo:[1,0]
	v_pk_mul_f32 v[18:19], v[116:117], s[84:85] op_sel:[1,0]
	v_pk_add_f32 v[82:83], v[100:101], v[110:111]
	v_pk_add_f32 v[100:101], v[100:101], v[110:111] neg_lo:[0,1] neg_hi:[0,1]
	v_pk_fma_f32 v[116:117], v[116:117], s[88:89], v[18:19] op_sel_hi:[0,1,1] neg_lo:[0,0,1] neg_hi:[0,0,1]
	v_pk_add_f32 v[18:19], v[90:91], v[74:75]
	v_pk_add_f32 v[74:75], v[90:91], v[74:75] neg_lo:[0,1] neg_hi:[0,1]
	v_pk_mul_f32 v[110:111], v[100:101], s[24:25] op_sel:[1,0]
	v_pk_fma_f32 v[100:101], v[100:101], s[0:1], v[110:111] op_sel_hi:[0,1,1] neg_lo:[0,0,1] neg_hi:[0,0,1]
	v_pk_add_f32 v[110:111], v[84:85], v[112:113]
	v_pk_add_f32 v[84:85], v[84:85], v[112:113] neg_lo:[0,1] neg_hi:[0,1]
	v_mul_f32_e32 v4, 0x3f3504f3, v85
	v_pk_add_f32 v[112:113], v[86:87], v[82:83]
	v_pk_add_f32 v[82:83], v[86:87], v[82:83] neg_lo:[0,1] neg_hi:[0,1]
	v_pk_fma_f32 v[84:85], v[84:85], s[96:97], v[4:5] op_sel_hi:[0,1,0] neg_lo:[0,0,1] neg_hi:[0,0,1]
	v_pk_mul_f32 v[86:87], v[82:83], s[18:19] op_sel_hi:[1,0]
	v_pk_fma_f32 v[96:97], v[82:83], s[18:19], v[86:87] op_sel:[0,0,1] op_sel_hi:[1,0,0] neg_lo:[0,0,1]
	v_pk_add_f32 v[82:83], v[12:13], v[110:111]
	v_pk_add_f32 v[12:13], v[12:13], v[110:111] neg_lo:[0,1] neg_hi:[0,1]
	v_pk_add_f32 v[110:111], v[166:167], v[98:99]
; template <int R, bool INV> DEV void dft_regs(cf (&v)[R]) {
; #pragma unroll
;     for (int s = R; s >= 2; s >>= 1) {
;         const int h = s >> 1;
; #pragma unroll
;         for (int b = 0; b < R; b += s) {
; #pragma unroll
;             for (int k = 0; k < h; ++k) {
;                 const cf a = v[b + k], c = v[b + k + h];
;                 v[b + k] = a + c;
;                 const cf d = a - c;
;                 const int m = k * (32 / s);
;                 const float wr = tw_cos(m), wi = INV ? tw_sin(m) : -tw_sin(m);
;                 v[b + k + h] = cf{d.x * wr - d.y * wi, d.x * wi + d.y * wr};
;             }
;         }
;     }
; DEV void fft_midx2(LAS cf* buf0, LAS cf* buf1, const unsigned* Kp, int blk) {
;     ...
;     dft_regs<16, true>(w); dft_regs<16, true>(x);
; #pragma unroll
;     for (int q = 0; q < 16; ++q) { p0[q] = w[BR16[q]]; p1[q] = x[BR16[q]]; }
	v_pk_add_f32 v[86:87], v[12:13], 0 op_sel:[1,0] op_sel_hi:[0,0] neg_lo:[1,0]
	v_pk_add_f32 v[98:99], v[166:167], v[98:99] neg_lo:[0,1] neg_hi:[0,1]
	v_pk_add_f32 v[12:13], v[88:89], v[102:103]
	v_pk_add_f32 v[88:89], v[88:89], v[102:103] neg_lo:[0,1] neg_hi:[0,1]
	v_mul_f32_e32 v4, 0x3f3504f3, v89
	v_pk_fma_f32 v[88:89], v[88:89], s[96:97], v[4:5] op_sel_hi:[0,1,0] neg_lo:[0,0,1] neg_hi:[0,0,1]
	v_pk_add_f32 v[166:167], v[108:109], v[100:101]
	v_pk_add_f32 v[100:101], v[108:109], v[100:101] neg_lo:[0,1] neg_hi:[0,1]
	v_pk_mul_f32 v[108:109], v[100:101], s[18:19] op_sel_hi:[1,0]
	v_pk_fma_f32 v[102:103], v[100:101], s[18:19], v[108:109] op_sel:[0,0,1] op_sel_hi:[1,0,0] neg_lo:[0,0,1]
	v_pk_add_f32 v[108:109], v[18:19], v[82:83]
	v_pk_add_f32 v[100:101], v[104:105], v[84:85]
	v_pk_add_f32 v[84:85], v[104:105], v[84:85] neg_lo:[0,1] neg_hi:[0,1]
	v_pk_add_f32 v[82:83], v[18:19], v[82:83] neg_lo:[0,1] neg_hi:[0,1]
	v_pk_add_f32 v[104:105], v[84:85], 0 op_sel:[1,0] op_sel_hi:[0,0] neg_lo:[1,0]
	v_pk_add_f32 v[84:85], v[8:9], v[116:117]
	v_pk_add_f32 v[116:117], v[8:9], v[116:117] neg_lo:[0,1] neg_hi:[0,1]
	v_mul_f32_e32 v4, 0x3f3504f3, v117
	v_pk_add_f32 v[8:9], v[112:113], v[12:13]
	v_pk_add_f32 v[12:13], v[112:113], v[12:13] neg_lo:[0,1] neg_hi:[0,1]
	v_pk_fma_f32 v[116:117], v[116:117], s[96:97], v[4:5] op_sel_hi:[0,1,0] neg_lo:[0,0,1] neg_hi:[0,0,1]
	v_pk_add_f32 v[112:113], v[12:13], 0 op_sel:[1,0] op_sel_hi:[0,0] neg_lo:[1,0]
	v_pk_add_f32 v[12:13], v[74:75], v[86:87]
	v_pk_add_f32 v[86:87], v[74:75], v[86:87] neg_lo:[0,1] neg_hi:[0,1]
	v_pk_add_f32 v[74:75], v[96:97], v[88:89]
	v_pk_add_f32 v[88:89], v[96:97], v[88:89] neg_lo:[0,1] neg_hi:[0,1]
	v_pk_add_f32 v[96:97], v[88:89], 0 op_sel:[1,0] op_sel_hi:[0,0] neg_lo:[1,0]
	v_pk_add_f32 v[88:89], v[110:111], v[100:101]
	v_pk_add_f32 v[18:19], v[110:111], v[100:101] neg_lo:[0,1] neg_hi:[0,1]
	v_pk_add_f32 v[100:101], v[98:99], v[104:105] neg_lo:[0,1] neg_hi:[0,1]
	v_pk_add_f32 v[110:111], v[166:167], v[84:85]
	v_pk_add_f32 v[84:85], v[166:167], v[84:85] neg_lo:[0,1] neg_hi:[0,1]
	v_pk_add_f32 v[166:167], v[84:85], 0 op_sel:[1,0] op_sel_hi:[0,0] neg_lo:[1,0]
	v_pk_add_f32 v[84:85], v[98:99], v[104:105]
	v_pk_add_f32 v[98:99], v[102:103], v[116:117]
	v_pk_add_f32 v[116:117], v[102:103], v[116:117] neg_lo:[0,1] neg_hi:[0,1]
	v_pk_add_f32 v[104:105], v[116:117], 0 op_sel:[1,0] op_sel_hi:[0,0] neg_lo:[1,0]
	v_pk_add_f32 v[116:117], v[108:109], v[8:9]
	v_pk_add_f32 v[8:9], v[108:109], v[8:9] neg_lo:[0,1] neg_hi:[0,1]
	v_pk_add_f32 v[108:109], v[82:83], v[112:113]
	v_pk_add_f32 v[112:113], v[82:83], v[112:113] neg_lo:[0,1] neg_hi:[0,1]
	v_pk_add_f32 v[102:103], v[12:13], v[74:75]
	v_pk_add_f32 v[12:13], v[12:13], v[74:75] neg_lo:[0,1] neg_hi:[0,1]
	v_pk_add_f32 v[74:75], v[86:87], v[96:97]
	v_pk_add_f32 v[96:97], v[86:87], v[96:97] neg_lo:[0,1] neg_hi:[0,1]
	v_pk_add_f32 v[168:169], v[88:89], v[110:111]
	v_pk_add_f32 v[110:111], v[88:89], v[110:111] neg_lo:[0,1] neg_hi:[0,1]
	v_pk_add_f32 v[88:89], v[18:19], v[166:167]
	v_pk_add_f32 v[166:167], v[18:19], v[166:167] neg_lo:[0,1] neg_hi:[0,1]
	v_mov_b32_e32 v176, v166
	v_mov_b32_e32 v177, v167
	v_pk_add_f32 v[174:175], v[84:85], v[98:99]
	v_pk_add_f32 v[84:85], v[84:85], v[98:99] neg_lo:[0,1] neg_hi:[0,1]
	v_pk_add_f32 v[98:99], v[100:101], v[104:105]
	v_pk_add_f32 v[104:105], v[100:101], v[104:105] neg_lo:[0,1] neg_hi:[0,1]
	ds_write2_b64 v161, v[124:125], v[72:73] offset1:1
	ds_write2_b64 v162, v[116:117], v[168:169] offset1:1
	ds_write2_b64 v161, v[94:95], v[76:77] offset0:2 offset1:3
	ds_write2_b64 v162, v[102:103], v[174:175] offset0:2 offset1:3
	ds_write2_b64 v161, v[80:81], v[126:127] offset0:4 offset1:5
	ds_write2_b64 v162, v[108:109], v[88:89] offset0:4 offset1:5
	ds_write2_b64 v161, v[92:93], v[164:165] offset0:6 offset1:7
	ds_write2_b64 v162, v[74:75], v[98:99] offset0:6 offset1:7
	ds_write2_b64 v161, v[114:115], v[78:79] offset0:14 offset1:15
	v_mov_b32_e32 v114, v160
	ds_write2_b64 v161, v[106:107], v[10:11] offset0:8 offset1:9
	ds_write2_b64 v162, v[8:9], v[110:111] offset0:8 offset1:9
	ds_write2_b64 v161, v[68:69], v[122:123] offset0:10 offset1:11
	ds_write2_b64 v162, v[12:13], v[84:85] offset0:10 offset1:11
	ds_write2_b64 v161, v[2:3], v[16:17] offset0:12 offset1:13
	ds_write2_b64 v162, v[112:113], v[176:177] offset0:12 offset1:13
	ds_write2_b64 v162, v[96:97], v[104:105] offset0:14 offset1:15
	s_waitcnt lgkmcnt(0)
	s_barrier
; #define LAS __attribute__((address_space(3)))
; #define SINCOSPI(x, s, c) do { const float hx_ = 0.5f * (x); *(s) = __builtin_amdgcn_sinf(hx_); *(c) = __builtin_amdgcn_cosf(hx_); } while (0)
; #define OPAQUE_I(x) asm volatile("" : "+v"(x))
; DEV void fft_i2(LAS cf* buf, int t8) {
;     OPAQUE_I(t8);
;     LAS cf* pb = buf + (t8 >> 4) * 544 + (t8 & 15);
;     float sn, cs; SINCOSPI(-(float)(t8 & 15) * (2.0f / 512.0f), &sn, &cs);
;     const cf w = cf{cs, sn}; cf wp = cf{1.f, 0.f};
;     cf v[32];
; #pragma unroll
;     for (int p = 0; p < 32; ++p) { v[p] = cmulc(pb[17 * p], wp); wp = cmul(wp, w); }
; DEV void hyena_issue_rows(const bf16_t* UT, int s, int c, u32x4 (&r)[4], int tid) {
; #pragma unroll
;     for (int b = 0; b < 4; ++b) r[b] = *(const u32x4*)(UT + ((size_t)(b * 3072 + s * 1024 + c)) * 4096 + tid * 8);
; }
	s_lshl_b32 s100, s19, 10
	s_add_i32 s100, s79, s100
	s_ashr_i32 s101, s100, 31
	s_lshl_b64 s[100:101], s[100:101], 13
	v_lshl_add_u64 v[218:219], v[56:57], 0, s[100:101]
	global_load_dwordx4 v[222:225], v[218:219], off
	s_add_u32 s100, s100, 0x1800000
	s_addc_u32 s101, s101, 0
	v_lshl_add_u64 v[220:221], v[56:57], 0, s[100:101]
	global_load_dwordx4 v[226:229], v[220:221], off
	s_add_u32 s100, s100, 0x1800000
	s_addc_u32 s101, s101, 0
	v_lshl_add_u64 v[218:219], v[56:57], 0, s[100:101]
	global_load_dwordx4 v[236:239], v[218:219], off
	s_add_u32 s100, s100, 0x1800000
	s_addc_u32 s101, s101, 0
	v_lshl_add_u64 v[220:221], v[56:57], 0, s[100:101]
	global_load_dwordx4 v[240:243], v[220:221], off
	s_nop 0
	v_lshrrev_b32_e32 v115, 4, v114
	v_and_b32_e32 v114, 15, v114
	v_mul_lo_u32 v115, v115, s15
	v_lshlrev_b32_e32 v2, 3, v114
	v_cvt_f32_ubyte0_e32 v114, v114
	v_add3_u32 v74, v159, v115, v2
	v_mul_f32_e32 v114, 0xbb800000, v114
	v_mul_f32_e32 v114, 0.5, v114
	v_add_u32_e32 v232, 0x800, v74
	v_add_u32_e32 v233, 0xc00, v74
	ds_read2_b64 v[166:169], v74 offset1:17
	ds_read2_b64 v[170:173], v74 offset0:34 offset1:51
	ds_read2_b64 v[174:177], v74 offset0:68 offset1:85
	ds_read2_b64 v[178:181], v74 offset0:102 offset1:119
	ds_read2_b64 v[182:185], v74 offset0:136 offset1:153
	ds_read2_b64 v[186:189], v74 offset0:170 offset1:187
	ds_read2_b64 v[190:193], v74 offset0:204 offset1:221
	ds_read2_b64 v[194:197], v74 offset0:238 offset1:255
	ds_read2_b64 v[198:201], v232 offset0:16 offset1:33
	ds_read2_b64 v[202:205], v232 offset0:50 offset1:67
	ds_read2_b64 v[208:211], v232 offset0:84 offset1:101
	ds_read2_b64 v[214:217], v232 offset0:118 offset1:135
	ds_read2_b64 v[218:221], v232 offset0:152 offset1:169
	v_sin_f32_e32 v115, v114
	v_cos_f32_e32 v114, v114
	s_waitcnt lgkmcnt(12)
	v_pk_mul_f32 v[2:3], v[166:167], v[66:67] op_sel:[1,1] op_sel_hi:[1,0]
	v_pk_fma_f32 v[4:5], v[166:167], v[66:67], v[2:3] op_sel_hi:[0,1,1] neg_hi:[1,0,0]
	v_add_u32_e32 v75, 0x800, v74
	v_pk_mul_f32 v[2:3], v[66:67], v[114:115] op_sel:[1,1] op_sel_hi:[1,0] neg_lo:[1,0]
	v_pk_fma_f32 v[8:9], v[66:67], v[114:115], v[2:3] op_sel_hi:[0,1,1]
	v_pk_mul_f32 v[10:11], v[168:169], v[8:9] op_sel:[1,1] op_sel_hi:[1,0]
	v_pk_fma_f32 v[2:3], v[168:169], v[8:9], v[10:11] op_sel_hi:[0,1,1] neg_hi:[1,0,0]
	v_pk_mul_f32 v[6:7], v[8:9], v[114:115] op_sel:[1,1] op_sel_hi:[1,0] neg_lo:[1,0]
	v_pk_fma_f32 v[12:13], v[8:9], v[114:115], v[6:7] op_sel_hi:[0,1,1]
	ds_read2_b64 v[166:169], v232 offset0:186 offset1:203
	s_waitcnt lgkmcnt(12)
	v_pk_mul_f32 v[14:15], v[170:171], v[12:13] op_sel:[1,1] op_sel_hi:[1,0]
	v_pk_fma_f32 v[10:11], v[170:171], v[12:13], v[14:15] op_sel_hi:[0,1,1] neg_hi:[1,0,0]
	v_pk_mul_f32 v[6:7], v[12:13], v[114:115] op_sel:[1,1] op_sel_hi:[1,0] neg_lo:[1,0]
	v_pk_fma_f32 v[12:13], v[12:13], v[114:115], v[6:7] op_sel_hi:[0,1,1]
	v_pk_mul_f32 v[14:15], v[172:173], v[12:13] op_sel:[1,1] op_sel_hi:[1,0]
	v_pk_fma_f32 v[6:7], v[172:173], v[12:13], v[14:15] op_sel_hi:[0,1,1] neg_hi:[1,0,0]
	v_pk_mul_f32 v[8:9], v[12:13], v[114:115] op_sel:[1,1] op_sel_hi:[1,0] neg_lo:[1,0]
	v_pk_fma_f32 v[16:17], v[12:13], v[114:115], v[8:9] op_sel_hi:[0,1,1]
	ds_read2_b64 v[170:173], v232 offset0:220 offset1:237
	s_waitcnt lgkmcnt(12)
	v_pk_mul_f32 v[8:9], v[174:175], v[16:17] op_sel:[1,1] op_sel_hi:[1,0]
	v_pk_fma_f32 v[12:13], v[174:175], v[16:17], v[8:9] op_sel_hi:[0,1,1] neg_hi:[1,0,0]
	s_nop 0
	v_pk_mul_f32 v[8:9], v[16:17], v[114:115] op_sel:[1,1] op_sel_hi:[1,0] neg_lo:[1,0]
	v_pk_fma_f32 v[16:17], v[16:17], v[114:115], v[8:9] op_sel_hi:[0,1,1]
	v_pk_mul_f32 v[18:19], v[176:177], v[16:17] op_sel:[1,1] op_sel_hi:[1,0]
	v_pk_fma_f32 v[8:9], v[176:177], v[16:17], v[18:19] op_sel_hi:[0,1,1] neg_hi:[1,0,0]
	v_pk_mul_f32 v[14:15], v[16:17], v[114:115] op_sel:[1,1] op_sel_hi:[1,0] neg_lo:[1,0]
	v_pk_fma_f32 v[68:69], v[16:17], v[114:115], v[14:15] op_sel_hi:[0,1,1]
	ds_read2_b64 v[174:177], v233 offset0:126 offset1:143
	s_waitcnt lgkmcnt(12)
	v_pk_mul_f32 v[14:15], v[178:179], v[68:69] op_sel:[1,1] op_sel_hi:[1,0]
	v_pk_fma_f32 v[16:17], v[178:179], v[68:69], v[14:15] op_sel_hi:[0,1,1] neg_hi:[1,0,0]
	s_nop 0
	v_pk_mul_f32 v[14:15], v[68:69], v[114:115] op_sel:[1,1] op_sel_hi:[1,0] neg_lo:[1,0]
	v_pk_fma_f32 v[68:69], v[68:69], v[114:115], v[14:15] op_sel_hi:[0,1,1]
	v_pk_mul_f32 v[70:71], v[180:181], v[68:69] op_sel:[1,1] op_sel_hi:[1,0]
	v_pk_fma_f32 v[14:15], v[180:181], v[68:69], v[70:71] op_sel_hi:[0,1,1] neg_hi:[1,0,0]
	v_pk_mul_f32 v[18:19], v[68:69], v[114:115] op_sel:[1,1] op_sel_hi:[1,0] neg_lo:[1,0]
	v_pk_fma_f32 v[72:73], v[68:69], v[114:115], v[18:19] op_sel_hi:[0,1,1]
	s_waitcnt lgkmcnt(11)
	v_pk_mul_f32 v[18:19], v[182:183], v[72:73] op_sel:[1,1] op_sel_hi:[1,0]
	v_pk_fma_f32 v[68:69], v[182:183], v[72:73], v[18:19] op_sel_hi:[0,1,1] neg_hi:[1,0,0]
	s_nop 0
	v_pk_mul_f32 v[18:19], v[72:73], v[114:115] op_sel:[1,1] op_sel_hi:[1,0] neg_lo:[1,0]
	v_pk_fma_f32 v[72:73], v[72:73], v[114:115], v[18:19] op_sel_hi:[0,1,1]
	v_pk_mul_f32 v[86:87], v[184:185], v[72:73] op_sel:[1,1] op_sel_hi:[1,0]
	v_pk_fma_f32 v[18:19], v[184:185], v[72:73], v[86:87] op_sel_hi:[0,1,1] neg_hi:[1,0,0]
	v_pk_mul_f32 v[70:71], v[72:73], v[114:115] op_sel:[1,1] op_sel_hi:[1,0] neg_lo:[1,0]
	v_pk_fma_f32 v[76:77], v[72:73], v[114:115], v[70:71] op_sel_hi:[0,1,1]
	s_waitcnt lgkmcnt(10)
; #define SINCOSPI(x, s, c) do { const float hx_ = 0.5f * (x); *(s) = __builtin_amdgcn_sinf(hx_); *(c) = __builtin_amdgcn_cosf(hx_); } while (0)
; DEV void fft_i2(LAS cf* buf, int t8) {
;     ...
;     float sn, cs; SINCOSPI(-(float)(t8 & 15) * (2.0f / 512.0f), &sn, &cs);
;     const cf w = cf{cs, sn}; cf wp = cf{1.f, 0.f};
;     cf v[32];
; #pragma unroll
;     for (int p = 0; p < 32; ++p) { v[p] = cmulc(pb[17 * p], wp); wp = cmul(wp, w); }
	v_pk_mul_f32 v[70:71], v[186:187], v[76:77] op_sel:[1,1] op_sel_hi:[1,0]
	v_pk_fma_f32 v[72:73], v[186:187], v[76:77], v[70:71] op_sel_hi:[0,1,1] neg_hi:[1,0,0]
	s_nop 0
	v_pk_mul_f32 v[70:71], v[76:77], v[114:115] op_sel:[1,1] op_sel_hi:[1,0] neg_lo:[1,0]
	v_pk_fma_f32 v[76:77], v[76:77], v[114:115], v[70:71] op_sel_hi:[0,1,1]
	v_pk_mul_f32 v[78:79], v[188:189], v[76:77] op_sel:[1,1] op_sel_hi:[1,0]
	v_pk_fma_f32 v[70:71], v[188:189], v[76:77], v[78:79] op_sel_hi:[0,1,1] neg_hi:[1,0,0]
	v_pk_mul_f32 v[86:87], v[76:77], v[114:115] op_sel:[1,1] op_sel_hi:[1,0] neg_lo:[1,0]
	v_pk_fma_f32 v[80:81], v[76:77], v[114:115], v[86:87] op_sel_hi:[0,1,1]
	s_waitcnt lgkmcnt(9)
	v_pk_mul_f32 v[86:87], v[190:191], v[80:81] op_sel:[1,1] op_sel_hi:[1,0]
	v_pk_fma_f32 v[76:77], v[190:191], v[80:81], v[86:87] op_sel_hi:[0,1,1] neg_hi:[1,0,0]
	s_nop 0
	v_pk_mul_f32 v[86:87], v[80:81], v[114:115] op_sel:[1,1] op_sel_hi:[1,0] neg_lo:[1,0]
	v_pk_fma_f32 v[80:81], v[80:81], v[114:115], v[86:87] op_sel_hi:[0,1,1]
	v_pk_mul_f32 v[82:83], v[192:193], v[80:81] op_sel:[1,1] op_sel_hi:[1,0]
	v_pk_fma_f32 v[86:87], v[192:193], v[80:81], v[82:83] op_sel_hi:[0,1,1] neg_hi:[1,0,0]
	v_pk_mul_f32 v[78:79], v[80:81], v[114:115] op_sel:[1,1] op_sel_hi:[1,0] neg_lo:[1,0]
	v_pk_fma_f32 v[84:85], v[80:81], v[114:115], v[78:79] op_sel_hi:[0,1,1]
	s_waitcnt lgkmcnt(8)
	v_pk_mul_f32 v[78:79], v[194:195], v[84:85] op_sel:[1,1] op_sel_hi:[1,0]
	v_pk_fma_f32 v[80:81], v[194:195], v[84:85], v[78:79] op_sel_hi:[0,1,1] neg_hi:[1,0,0]
	s_nop 0
	v_pk_mul_f32 v[78:79], v[84:85], v[114:115] op_sel:[1,1] op_sel_hi:[1,0] neg_lo:[1,0]
	v_pk_fma_f32 v[84:85], v[84:85], v[114:115], v[78:79] op_sel_hi:[0,1,1]
	v_pk_mul_f32 v[88:89], v[196:197], v[84:85] op_sel:[1,1] op_sel_hi:[1,0]
	v_pk_fma_f32 v[78:79], v[196:197], v[84:85], v[88:89] op_sel_hi:[0,1,1] neg_hi:[1,0,0]
	v_pk_mul_f32 v[82:83], v[84:85], v[114:115] op_sel:[1,1] op_sel_hi:[1,0] neg_lo:[1,0]
	v_pk_fma_f32 v[92:93], v[84:85], v[114:115], v[82:83] op_sel_hi:[0,1,1]
	s_waitcnt lgkmcnt(7)
	v_pk_mul_f32 v[82:83], v[198:199], v[92:93] op_sel:[1,1] op_sel_hi:[1,0]
	v_pk_fma_f32 v[84:85], v[198:199], v[92:93], v[82:83] op_sel_hi:[0,1,1] neg_hi:[1,0,0]
	s_nop 0
	v_pk_mul_f32 v[82:83], v[92:93], v[114:115] op_sel:[1,1] op_sel_hi:[1,0] neg_lo:[1,0]
	v_pk_fma_f32 v[88:89], v[92:93], v[114:115], v[82:83] op_sel_hi:[0,1,1]
	v_pk_mul_f32 v[92:93], v[200:201], v[88:89] op_sel:[1,1] op_sel_hi:[1,0]
	v_pk_fma_f32 v[82:83], v[200:201], v[88:89], v[92:93] op_sel_hi:[0,1,1] neg_hi:[1,0,0]
	s_nop 0
	v_pk_mul_f32 v[90:91], v[88:89], v[114:115] op_sel:[1,1] op_sel_hi:[1,0] neg_lo:[1,0]
	v_pk_fma_f32 v[92:93], v[88:89], v[114:115], v[90:91] op_sel_hi:[0,1,1]
	s_waitcnt lgkmcnt(6)
	v_pk_mul_f32 v[96:97], v[202:203], v[92:93] op_sel:[1,1] op_sel_hi:[1,0]
	v_pk_fma_f32 v[94:95], v[202:203], v[92:93], v[96:97] op_sel_hi:[0,1,1] neg_hi:[1,0,0]
	v_pk_mul_f32 v[88:89], v[92:93], v[114:115] op_sel:[1,1] op_sel_hi:[1,0] neg_lo:[1,0]
	v_pk_fma_f32 v[92:93], v[92:93], v[114:115], v[88:89] op_sel_hi:[0,1,1]
	v_pk_mul_f32 v[88:89], v[204:205], v[92:93] op_sel:[1,1] op_sel_hi:[1,0]
	v_pk_fma_f32 v[96:97], v[204:205], v[92:93], v[88:89] op_sel_hi:[0,1,1] neg_hi:[1,0,0]
	s_nop 0
	v_pk_mul_f32 v[88:89], v[92:93], v[114:115] op_sel:[1,1] op_sel_hi:[1,0] neg_lo:[1,0]
	v_pk_fma_f32 v[92:93], v[92:93], v[114:115], v[88:89] op_sel_hi:[0,1,1]
	s_waitcnt lgkmcnt(5)
	v_pk_mul_f32 v[100:101], v[208:209], v[92:93] op_sel:[1,1] op_sel_hi:[1,0]
	v_pk_fma_f32 v[98:99], v[208:209], v[92:93], v[100:101] op_sel_hi:[0,1,1] neg_hi:[1,0,0]
	v_pk_mul_f32 v[88:89], v[92:93], v[114:115] op_sel:[1,1] op_sel_hi:[1,0] neg_lo:[1,0]
	v_pk_fma_f32 v[92:93], v[92:93], v[114:115], v[88:89] op_sel_hi:[0,1,1]
	v_pk_mul_f32 v[88:89], v[210:211], v[92:93] op_sel:[1,1] op_sel_hi:[1,0]
	v_pk_fma_f32 v[100:101], v[210:211], v[92:93], v[88:89] op_sel_hi:[0,1,1] neg_hi:[1,0,0]
	s_nop 0
	v_pk_mul_f32 v[88:89], v[92:93], v[114:115] op_sel:[1,1] op_sel_hi:[1,0] neg_lo:[1,0]
	v_pk_fma_f32 v[92:93], v[92:93], v[114:115], v[88:89] op_sel_hi:[0,1,1]
	s_waitcnt lgkmcnt(4)
	v_pk_mul_f32 v[104:105], v[214:215], v[92:93] op_sel:[1,1] op_sel_hi:[1,0]
	v_pk_fma_f32 v[102:103], v[214:215], v[92:93], v[104:105] op_sel_hi:[0,1,1] neg_hi:[1,0,0]
	v_pk_mul_f32 v[88:89], v[92:93], v[114:115] op_sel:[1,1] op_sel_hi:[1,0] neg_lo:[1,0]
	v_pk_fma_f32 v[92:93], v[92:93], v[114:115], v[88:89] op_sel_hi:[0,1,1]
	v_pk_mul_f32 v[88:89], v[216:217], v[92:93] op_sel:[1,1] op_sel_hi:[1,0]
	v_pk_fma_f32 v[104:105], v[216:217], v[92:93], v[88:89] op_sel_hi:[0,1,1] neg_hi:[1,0,0]
	s_nop 0
	v_pk_mul_f32 v[88:89], v[92:93], v[114:115] op_sel:[1,1] op_sel_hi:[1,0] neg_lo:[1,0]
	v_pk_fma_f32 v[92:93], v[92:93], v[114:115], v[88:89] op_sel_hi:[0,1,1]
	s_waitcnt lgkmcnt(3)
	v_pk_mul_f32 v[108:109], v[218:219], v[92:93] op_sel:[1,1] op_sel_hi:[1,0]
	v_pk_fma_f32 v[106:107], v[218:219], v[92:93], v[108:109] op_sel_hi:[0,1,1] neg_hi:[1,0,0]
	v_pk_mul_f32 v[88:89], v[92:93], v[114:115] op_sel:[1,1] op_sel_hi:[1,0] neg_lo:[1,0]
	v_pk_fma_f32 v[92:93], v[92:93], v[114:115], v[88:89] op_sel_hi:[0,1,1]
	v_pk_mul_f32 v[88:89], v[220:221], v[92:93] op_sel:[1,1] op_sel_hi:[1,0]
	v_pk_fma_f32 v[108:109], v[220:221], v[92:93], v[88:89] op_sel_hi:[0,1,1] neg_hi:[1,0,0]
	s_nop 0
	v_pk_mul_f32 v[88:89], v[92:93], v[114:115] op_sel:[1,1] op_sel_hi:[1,0] neg_lo:[1,0]
	v_pk_fma_f32 v[92:93], v[92:93], v[114:115], v[88:89] op_sel_hi:[0,1,1]
	s_waitcnt lgkmcnt(2)
; template <int R, bool INV> DEV void dft_regs(cf (&v)[R]) {
; #pragma unroll
;     for (int s = R; s >= 2; s >>= 1) {
;         const int h = s >> 1;
; #pragma unroll
;         for (int b = 0; b < R; b += s) {
; #pragma unroll
;             for (int k = 0; k < h; ++k) {
;                 const cf a = v[b + k], c = v[b + k + h];
;                 v[b + k] = a + c;
;                 const cf d = a - c;
;                 const int m = k * (32 / s);
;                 const float wr = tw_cos(m), wi = INV ? tw_sin(m) : -tw_sin(m);
;                 v[b + k + h] = cf{d.x * wr - d.y * wi, d.x * wi + d.y * wr};
;             }
;         }
;     }
; DEV void fft_i2(LAS cf* buf, int t8) {
;     ...
;     for (int p = 0; p < 32; ++p) { v[p] = cmulc(pb[17 * p], wp); wp = cmul(wp, w); }
;     dft_regs<32, true>(v);
	v_pk_mul_f32 v[112:113], v[166:167], v[92:93] op_sel:[1,1] op_sel_hi:[1,0]
	v_pk_fma_f32 v[110:111], v[166:167], v[92:93], v[112:113] op_sel_hi:[0,1,1] neg_hi:[1,0,0]
	v_pk_mul_f32 v[88:89], v[92:93], v[114:115] op_sel:[1,1] op_sel_hi:[1,0] neg_lo:[1,0]
	v_pk_fma_f32 v[92:93], v[92:93], v[114:115], v[88:89] op_sel_hi:[0,1,1]
	v_pk_mul_f32 v[88:89], v[168:169], v[92:93] op_sel:[1,1] op_sel_hi:[1,0]
	v_pk_fma_f32 v[112:113], v[168:169], v[92:93], v[88:89] op_sel_hi:[0,1,1] neg_hi:[1,0,0]
	s_nop 0
	v_pk_mul_f32 v[88:89], v[92:93], v[114:115] op_sel:[1,1] op_sel_hi:[1,0] neg_lo:[1,0]
	v_pk_fma_f32 v[92:93], v[92:93], v[114:115], v[88:89] op_sel_hi:[0,1,1]
	s_waitcnt lgkmcnt(1)
	v_pk_mul_f32 v[116:117], v[170:171], v[92:93] op_sel:[1,1] op_sel_hi:[1,0]
	v_pk_fma_f32 v[0:1], v[170:171], v[92:93], v[116:117] op_sel_hi:[0,1,1] neg_hi:[1,0,0]
	v_pk_mul_f32 v[88:89], v[92:93], v[114:115] op_sel:[1,1] op_sel_hi:[1,0] neg_lo:[1,0]
	v_pk_fma_f32 v[92:93], v[92:93], v[114:115], v[88:89] op_sel_hi:[0,1,1]
	v_pk_mul_f32 v[88:89], v[172:173], v[92:93] op_sel:[1,1] op_sel_hi:[1,0]
	v_pk_fma_f32 v[116:117], v[172:173], v[92:93], v[88:89] op_sel_hi:[0,1,1] neg_hi:[1,0,0]
	s_nop 0
	v_pk_mul_f32 v[88:89], v[92:93], v[114:115] op_sel:[1,1] op_sel_hi:[1,0] neg_lo:[1,0]
	v_pk_fma_f32 v[118:119], v[92:93], v[114:115], v[88:89] op_sel_hi:[0,1,1]
	s_nop 0
	v_add_u32_e32 v88, 0xc00, v74
	v_pk_mul_f32 v[120:121], v[118:119], v[114:115] op_sel:[1,1] op_sel_hi:[1,0] neg_lo:[1,0]
	v_pk_fma_f32 v[114:115], v[118:119], v[114:115], v[120:121] op_sel_hi:[0,1,1]
	s_waitcnt lgkmcnt(0)
	v_pk_mul_f32 v[120:121], v[174:175], v[118:119] op_sel:[1,1] op_sel_hi:[1,0]
	v_pk_fma_f32 v[90:91], v[174:175], v[118:119], v[120:121] op_sel_hi:[0,1,1] neg_hi:[1,0,0]
	v_pk_mul_f32 v[118:119], v[176:177], v[114:115] op_sel:[1,1] op_sel_hi:[1,0]
	v_pk_fma_f32 v[114:115], v[176:177], v[114:115], v[118:119] op_sel_hi:[0,1,1] neg_hi:[1,0,0]
	v_pk_add_f32 v[92:93], v[4:5], v[84:85]
	v_pk_add_f32 v[4:5], v[4:5], v[84:85] neg_lo:[0,1] neg_hi:[0,1]
	v_mov_b32_e32 v118, v4
	v_mov_b32_e32 v119, v5
	v_pk_add_f32 v[4:5], v[2:3], v[82:83]
	v_pk_add_f32 v[2:3], v[2:3], v[82:83] neg_lo:[0,1] neg_hi:[0,1]
	v_pk_mul_f32 v[82:83], v[2:3], s[82:83] op_sel_hi:[1,0]
	v_pk_fma_f32 v[84:85], v[2:3], s[94:95], v[82:83] op_sel:[0,0,1] op_sel_hi:[1,0,0] neg_lo:[0,0,1]
	v_pk_add_f32 v[2:3], v[10:11], v[94:95]
	v_pk_add_f32 v[10:11], v[10:11], v[94:95] neg_lo:[0,1] neg_hi:[0,1]
	v_pk_mul_f32 v[82:83], v[10:11], s[84:85] op_sel_hi:[1,0]
	v_pk_fma_f32 v[94:95], v[10:11], s[16:17], v[82:83] op_sel:[0,0,1] op_sel_hi:[1,0,0] neg_lo:[0,0,1]
	v_pk_add_f32 v[10:11], v[6:7], v[96:97]
	v_pk_add_f32 v[6:7], v[6:7], v[96:97] neg_lo:[0,1] neg_hi:[0,1]
	v_pk_mul_f32 v[82:83], v[6:7], s[4:5] op_sel_hi:[1,0]
	v_pk_fma_f32 v[96:97], v[6:7], s[86:87], v[82:83] op_sel:[0,0,1] op_sel_hi:[1,0,0] neg_lo:[0,0,1]
	v_pk_add_f32 v[6:7], v[12:13], v[98:99]
	v_pk_add_f32 v[12:13], v[12:13], v[98:99] neg_lo:[0,1] neg_hi:[0,1]
	v_pk_mul_f32 v[82:83], v[12:13], s[18:19] op_sel_hi:[1,0]
	v_pk_fma_f32 v[98:99], v[12:13], s[18:19], v[82:83] op_sel:[0,0,1] op_sel_hi:[1,0,0] neg_lo:[0,0,1]
	v_pk_add_f32 v[12:13], v[8:9], v[100:101]
	v_pk_add_f32 v[8:9], v[8:9], v[100:101] neg_lo:[0,1] neg_hi:[0,1]
	v_pk_mul_f32 v[82:83], v[8:9], s[86:87] op_sel_hi:[1,0]
	v_pk_fma_f32 v[100:101], v[8:9], s[4:5], v[82:83] op_sel:[0,0,1] op_sel_hi:[1,0,0] neg_lo:[0,0,1]
	v_pk_add_f32 v[8:9], v[16:17], v[102:103]
	v_pk_add_f32 v[16:17], v[16:17], v[102:103] neg_lo:[0,1] neg_hi:[0,1]
	v_pk_mul_f32 v[82:83], v[16:17], s[16:17] op_sel_hi:[1,0]
	v_pk_fma_f32 v[102:103], v[16:17], s[84:85], v[82:83] op_sel:[0,0,1] op_sel_hi:[1,0,0] neg_lo:[0,0,1]
	v_pk_add_f32 v[16:17], v[14:15], v[104:105]
	v_pk_add_f32 v[14:15], v[14:15], v[104:105] neg_lo:[0,1] neg_hi:[0,1]
	v_pk_mul_f32 v[82:83], v[14:15], s[94:95] op_sel_hi:[1,0]
	v_pk_fma_f32 v[104:105], v[14:15], s[82:83], v[82:83] op_sel:[0,0,1] op_sel_hi:[1,0,0] neg_lo:[0,0,1]
	v_pk_add_f32 v[14:15], v[68:69], v[106:107]
	v_pk_add_f32 v[68:69], v[68:69], v[106:107] neg_lo:[0,1] neg_hi:[0,1]
	v_pk_add_f32 v[82:83], v[68:69], 0 op_sel:[1,0] op_sel_hi:[0,0] neg_lo:[1,0]
	v_pk_add_f32 v[68:69], v[18:19], v[108:109]
	v_pk_add_f32 v[18:19], v[18:19], v[108:109] neg_lo:[0,1] neg_hi:[0,1]
	v_pk_mul_f32 v[106:107], v[18:19], s[6:7] op_sel:[1,0]
	s_mov_b32 s6, s87
	v_pk_fma_f32 v[18:19], v[18:19], s[28:29], v[106:107] op_sel_hi:[0,1,1] neg_lo:[0,0,1] neg_hi:[0,0,1]
	v_pk_add_f32 v[106:107], v[72:73], v[110:111]
	v_pk_add_f32 v[72:73], v[72:73], v[110:111] neg_lo:[0,1] neg_hi:[0,1]
	s_mov_b32 s7, s86
	v_pk_mul_f32 v[108:109], v[72:73], s[24:25] op_sel:[1,0]
	v_pk_fma_f32 v[72:73], v[72:73], s[0:1], v[108:109] op_sel_hi:[0,1,1] neg_lo:[0,0,1] neg_hi:[0,0,1]
	v_pk_add_f32 v[108:109], v[70:71], v[112:113]
	v_pk_add_f32 v[70:71], v[70:71], v[112:113] neg_lo:[0,1] neg_hi:[0,1]
	v_pk_mul_f32 v[110:111], v[70:71], s[2:3] op_sel:[1,0]
	s_mov_b32 s2, s11
	v_pk_fma_f32 v[70:71], v[70:71], s[6:7], v[110:111] op_sel_hi:[0,1,1] neg_lo:[0,0,1] neg_hi:[0,0,1]
	v_pk_add_f32 v[110:111], v[76:77], v[0:1]
	v_pk_add_f32 v[76:77], v[76:77], v[0:1] neg_lo:[0,1] neg_hi:[0,1]
	v_mul_f32_e32 v112, 0x3f3504f3, v77
	v_pk_fma_f32 v[76:77], v[76:77], s[96:97], v[112:113] op_sel_hi:[0,1,0] neg_lo:[0,0,1] neg_hi:[0,0,1]
	v_pk_add_f32 v[112:113], v[86:87], v[116:117]
	v_pk_add_f32 v[86:87], v[86:87], v[116:117] neg_lo:[0,1] neg_hi:[0,1]
	v_pk_mul_f32 v[0:1], v[86:87], s[4:5] op_sel:[1,0]
	s_lshl_b32 s5, s19, 10
	v_pk_fma_f32 v[86:87], v[86:87], s[2:3], v[0:1] op_sel_hi:[0,1,1] neg_lo:[0,0,1] neg_hi:[0,0,1]
	v_pk_add_f32 v[0:1], v[80:81], v[90:91]
; template <int R, bool INV> DEV void dft_regs(cf (&v)[R]) {
; #pragma unroll
;     for (int s = R; s >= 2; s >>= 1) {
;         const int h = s >> 1;
; #pragma unroll
;         for (int b = 0; b < R; b += s) {
; #pragma unroll
;             for (int k = 0; k < h; ++k) {
;                 const cf a = v[b + k], c = v[b + k + h];
;                 v[b + k] = a + c;
;                 const cf d = a - c;
;                 const int m = k * (32 / s);
;                 const float wr = tw_cos(m), wi = INV ? tw_sin(m) : -tw_sin(m);
;                 v[b + k + h] = cf{d.x * wr - d.y * wi, d.x * wi + d.y * wr};
;             }
;         }
;     }
	v_pk_add_f32 v[80:81], v[80:81], v[90:91] neg_lo:[0,1] neg_hi:[0,1]
	s_mov_b32 s2, s9
	v_pk_mul_f32 v[90:91], v[80:81], s[84:85] op_sel:[1,0]
	s_mov_b32 s3, s82
	v_pk_fma_f32 v[80:81], v[80:81], s[88:89], v[90:91] op_sel_hi:[0,1,1] neg_lo:[0,0,1] neg_hi:[0,0,1]
	v_pk_add_f32 v[90:91], v[78:79], v[114:115]
	v_pk_add_f32 v[114:115], v[78:79], v[114:115] neg_lo:[0,1] neg_hi:[0,1]
	s_add_i32 s6, s79, s5
	v_pk_mul_f32 v[78:79], v[114:115], s[82:83] op_sel:[1,0]
	s_ashr_i32 s7, s6, 31
	v_pk_fma_f32 v[114:115], v[114:115], s[2:3], v[78:79] op_sel_hi:[0,1,1] neg_lo:[0,0,1] neg_hi:[0,0,1]
	v_pk_add_f32 v[78:79], v[92:93], v[14:15]
	v_pk_add_f32 v[14:15], v[92:93], v[14:15] neg_lo:[0,1] neg_hi:[0,1]
	s_lshl_b64 s[2:3], s[6:7], 13
	v_mov_b32_e32 v116, v14
	v_mov_b32_e32 v117, v15
	v_pk_add_f32 v[14:15], v[4:5], v[68:69]
	v_pk_add_f32 v[4:5], v[4:5], v[68:69] neg_lo:[0,1] neg_hi:[0,1]
	v_pk_mul_f32 v[68:69], v[4:5], s[84:85] op_sel_hi:[1,0]
	v_pk_fma_f32 v[92:93], v[4:5], s[16:17], v[68:69] op_sel:[0,0,1] op_sel_hi:[1,0,0] neg_lo:[0,0,1]
	v_pk_add_f32 v[4:5], v[2:3], v[106:107]
	v_pk_add_f32 v[2:3], v[2:3], v[106:107] neg_lo:[0,1] neg_hi:[0,1]
	v_pk_mul_f32 v[68:69], v[2:3], s[18:19] op_sel_hi:[1,0]
	v_pk_fma_f32 v[106:107], v[2:3], s[18:19], v[68:69] op_sel:[0,0,1] op_sel_hi:[1,0,0] neg_lo:[0,0,1]
	v_pk_add_f32 v[2:3], v[10:11], v[108:109]
	v_pk_add_f32 v[10:11], v[10:11], v[108:109] neg_lo:[0,1] neg_hi:[0,1]
	v_pk_mul_f32 v[68:69], v[10:11], s[16:17] op_sel_hi:[1,0]
	v_pk_fma_f32 v[108:109], v[10:11], s[84:85], v[68:69] op_sel:[0,0,1] op_sel_hi:[1,0,0] neg_lo:[0,0,1]
	v_pk_add_f32 v[10:11], v[6:7], v[110:111]
	v_pk_add_f32 v[6:7], v[6:7], v[110:111] neg_lo:[0,1] neg_hi:[0,1]
	v_pk_add_f32 v[68:69], v[6:7], 0 op_sel:[1,0] op_sel_hi:[0,0] neg_lo:[1,0]
	v_pk_add_f32 v[6:7], v[12:13], v[112:113]
	v_pk_add_f32 v[12:13], v[12:13], v[112:113] neg_lo:[0,1] neg_hi:[0,1]
	v_pk_mul_f32 v[110:111], v[12:13], s[24:25] op_sel:[1,0]
	v_pk_fma_f32 v[12:13], v[12:13], s[0:1], v[110:111] op_sel_hi:[0,1,1] neg_lo:[0,0,1] neg_hi:[0,0,1]
	v_pk_add_f32 v[110:111], v[8:9], v[0:1]
	v_pk_add_f32 v[8:9], v[8:9], v[0:1] neg_lo:[0,1] neg_hi:[0,1]
	v_mul_f32_e32 v112, 0x3f3504f3, v9
	v_pk_fma_f32 v[8:9], v[8:9], s[96:97], v[112:113] op_sel_hi:[0,1,0] neg_lo:[0,0,1] neg_hi:[0,0,1]
	v_pk_add_f32 v[112:113], v[16:17], v[90:91]
	v_pk_add_f32 v[16:17], v[16:17], v[90:91] neg_lo:[0,1] neg_hi:[0,1]
	v_pk_mul_f32 v[90:91], v[16:17], s[84:85] op_sel:[1,0]
	v_pk_fma_f32 v[16:17], v[16:17], s[88:89], v[90:91] op_sel_hi:[0,1,1] neg_lo:[0,0,1] neg_hi:[0,0,1]
	v_pk_add_f32 v[90:91], v[118:119], v[82:83]
	v_pk_add_f32 v[82:83], v[118:119], v[82:83] neg_lo:[0,1] neg_hi:[0,1]
	v_pk_add_f32 v[118:119], v[84:85], v[18:19]
	v_pk_add_f32 v[18:19], v[84:85], v[18:19] neg_lo:[0,1] neg_hi:[0,1]
	v_pk_mul_f32 v[84:85], v[18:19], s[84:85] op_sel_hi:[1,0]
	v_pk_fma_f32 v[0:1], v[18:19], s[16:17], v[84:85] op_sel:[0,0,1] op_sel_hi:[1,0,0] neg_lo:[0,0,1]
	v_pk_add_f32 v[18:19], v[94:95], v[72:73]
	v_pk_add_f32 v[72:73], v[94:95], v[72:73] neg_lo:[0,1] neg_hi:[0,1]
	v_pk_mul_f32 v[84:85], v[72:73], s[18:19] op_sel_hi:[1,0]
	v_pk_fma_f32 v[94:95], v[72:73], s[18:19], v[84:85] op_sel:[0,0,1] op_sel_hi:[1,0,0] neg_lo:[0,0,1]
	v_pk_add_f32 v[72:73], v[96:97], v[70:71]
	v_pk_add_f32 v[70:71], v[96:97], v[70:71] neg_lo:[0,1] neg_hi:[0,1]
	v_pk_mul_f32 v[84:85], v[70:71], s[16:17] op_sel_hi:[1,0]
	v_pk_fma_f32 v[96:97], v[70:71], s[84:85], v[84:85] op_sel:[0,0,1] op_sel_hi:[1,0,0] neg_lo:[0,0,1]
	v_pk_add_f32 v[70:71], v[98:99], v[76:77]
	v_pk_add_f32 v[76:77], v[98:99], v[76:77] neg_lo:[0,1] neg_hi:[0,1]
	v_pk_add_f32 v[84:85], v[76:77], 0 op_sel:[1,0] op_sel_hi:[0,0] neg_lo:[1,0]
	v_pk_add_f32 v[76:77], v[100:101], v[86:87]
	v_pk_add_f32 v[86:87], v[100:101], v[86:87] neg_lo:[0,1] neg_hi:[0,1]
	v_pk_mul_f32 v[98:99], v[86:87], s[24:25] op_sel:[1,0]
	v_pk_fma_f32 v[86:87], v[86:87], s[0:1], v[98:99] op_sel_hi:[0,1,1] neg_lo:[0,0,1] neg_hi:[0,0,1]
	v_pk_add_f32 v[98:99], v[102:103], v[80:81]
	v_pk_add_f32 v[80:81], v[102:103], v[80:81] neg_lo:[0,1] neg_hi:[0,1]
	v_mul_f32_e32 v100, 0x3f3504f3, v81
	v_pk_fma_f32 v[80:81], v[80:81], s[96:97], v[100:101] op_sel_hi:[0,1,0] neg_lo:[0,0,1] neg_hi:[0,0,1]
	v_pk_add_f32 v[100:101], v[104:105], v[114:115]
	v_pk_add_f32 v[114:115], v[104:105], v[114:115] neg_lo:[0,1] neg_hi:[0,1]
	v_pk_mul_f32 v[102:103], v[114:115], s[84:85] op_sel:[1,0]
	v_pk_fma_f32 v[114:115], v[114:115], s[88:89], v[102:103] op_sel_hi:[0,1,1] neg_lo:[0,0,1] neg_hi:[0,0,1]
	v_pk_add_f32 v[102:103], v[78:79], v[10:11]
	v_pk_add_f32 v[10:11], v[78:79], v[10:11] neg_lo:[0,1] neg_hi:[0,1]
	v_mov_b32_e32 v104, v10
	v_mov_b32_e32 v105, v11
	v_pk_add_f32 v[10:11], v[14:15], v[6:7]
	v_pk_add_f32 v[6:7], v[14:15], v[6:7] neg_lo:[0,1] neg_hi:[0,1]
	v_pk_mul_f32 v[14:15], v[6:7], s[18:19] op_sel_hi:[1,0]
	v_pk_fma_f32 v[78:79], v[6:7], s[18:19], v[14:15] op_sel:[0,0,1] op_sel_hi:[1,0,0] neg_lo:[0,0,1]
	v_pk_add_f32 v[6:7], v[4:5], v[110:111]
	v_pk_add_f32 v[4:5], v[4:5], v[110:111] neg_lo:[0,1] neg_hi:[0,1]
	v_pk_add_f32 v[14:15], v[4:5], 0 op_sel:[1,0] op_sel_hi:[0,0] neg_lo:[1,0]
	v_pk_add_f32 v[4:5], v[2:3], v[112:113]
	v_pk_add_f32 v[2:3], v[2:3], v[112:113] neg_lo:[0,1] neg_hi:[0,1]
	v_mul_f32_e32 v110, 0x3f3504f3, v3
	v_pk_fma_f32 v[2:3], v[2:3], s[96:97], v[110:111] op_sel_hi:[0,1,0] neg_lo:[0,0,1] neg_hi:[0,0,1]
	v_pk_add_f32 v[110:111], v[116:117], v[68:69]
	v_pk_add_f32 v[68:69], v[116:117], v[68:69] neg_lo:[0,1] neg_hi:[0,1]
	v_pk_add_f32 v[116:117], v[92:93], v[12:13]
	v_pk_add_f32 v[12:13], v[92:93], v[12:13] neg_lo:[0,1] neg_hi:[0,1]
	v_pk_mul_f32 v[92:93], v[12:13], s[18:19] op_sel_hi:[1,0]
; template <int R, bool INV> DEV void dft_regs(cf (&v)[R]) {
; #pragma unroll
;     for (int s = R; s >= 2; s >>= 1) {
;         const int h = s >> 1;
; #pragma unroll
;         for (int b = 0; b < R; b += s) {
; #pragma unroll
;             for (int k = 0; k < h; ++k) {
;                 const cf a = v[b + k], c = v[b + k + h];
;                 v[b + k] = a + c;
;                 const cf d = a - c;
;                 const int m = k * (32 / s);
;                 const float wr = tw_cos(m), wi = INV ? tw_sin(m) : -tw_sin(m);
;                 v[b + k + h] = cf{d.x * wr - d.y * wi, d.x * wi + d.y * wr};
;             }
;         }
;     }
	v_pk_fma_f32 v[112:113], v[12:13], s[18:19], v[92:93] op_sel:[0,0,1] op_sel_hi:[1,0,0] neg_lo:[0,0,1]
	v_pk_add_f32 v[12:13], v[106:107], v[8:9]
	v_pk_add_f32 v[8:9], v[106:107], v[8:9] neg_lo:[0,1] neg_hi:[0,1]
	v_pk_add_f32 v[92:93], v[8:9], 0 op_sel:[1,0] op_sel_hi:[0,0] neg_lo:[1,0]
	v_pk_add_f32 v[8:9], v[108:109], v[16:17]
	v_pk_add_f32 v[16:17], v[108:109], v[16:17] neg_lo:[0,1] neg_hi:[0,1]
	v_mul_f32_e32 v106, 0x3f3504f3, v17
	v_pk_fma_f32 v[16:17], v[16:17], s[96:97], v[106:107] op_sel_hi:[0,1,0] neg_lo:[0,0,1] neg_hi:[0,0,1]
	v_pk_add_f32 v[106:107], v[90:91], v[70:71]
	v_pk_add_f32 v[70:71], v[90:91], v[70:71] neg_lo:[0,1] neg_hi:[0,1]
	v_pk_add_f32 v[108:109], v[118:119], v[76:77]
	v_pk_add_f32 v[76:77], v[118:119], v[76:77] neg_lo:[0,1] neg_hi:[0,1]
	v_pk_mul_f32 v[118:119], v[76:77], s[18:19] op_sel_hi:[1,0]
	v_pk_fma_f32 v[90:91], v[76:77], s[18:19], v[118:119] op_sel:[0,0,1] op_sel_hi:[1,0,0] neg_lo:[0,0,1]
	v_pk_add_f32 v[76:77], v[18:19], v[98:99]
	v_pk_add_f32 v[18:19], v[18:19], v[98:99] neg_lo:[0,1] neg_hi:[0,1]
	v_pk_add_f32 v[118:119], v[18:19], 0 op_sel:[1,0] op_sel_hi:[0,0] neg_lo:[1,0]
	v_pk_add_f32 v[18:19], v[72:73], v[100:101]
	v_pk_add_f32 v[72:73], v[72:73], v[100:101] neg_lo:[0,1] neg_hi:[0,1]
	v_mul_f32_e32 v98, 0x3f3504f3, v73
	v_pk_fma_f32 v[72:73], v[72:73], s[96:97], v[98:99] op_sel_hi:[0,1,0] neg_lo:[0,0,1] neg_hi:[0,0,1]
	v_pk_add_f32 v[98:99], v[82:83], v[84:85]
	v_pk_add_f32 v[84:85], v[82:83], v[84:85] neg_lo:[0,1] neg_hi:[0,1]
	v_pk_add_f32 v[82:83], v[0:1], v[86:87]
	v_pk_add_f32 v[86:87], v[0:1], v[86:87] neg_lo:[0,1] neg_hi:[0,1]
	v_pk_mul_f32 v[100:101], v[86:87], s[18:19] op_sel_hi:[1,0]
	v_pk_fma_f32 v[0:1], v[86:87], s[18:19], v[100:101] op_sel:[0,0,1] op_sel_hi:[1,0,0] neg_lo:[0,0,1]
	v_pk_add_f32 v[86:87], v[94:95], v[80:81]
	v_pk_add_f32 v[80:81], v[94:95], v[80:81] neg_lo:[0,1] neg_hi:[0,1]
	v_pk_add_f32 v[94:95], v[80:81], 0 op_sel:[1,0] op_sel_hi:[0,0] neg_lo:[1,0]
	v_pk_add_f32 v[80:81], v[96:97], v[114:115]
	v_pk_add_f32 v[114:115], v[96:97], v[114:115] neg_lo:[0,1] neg_hi:[0,1]
	v_mul_f32_e32 v96, 0x3f3504f3, v115
	v_pk_fma_f32 v[114:115], v[114:115], s[96:97], v[96:97] op_sel_hi:[0,1,0] neg_lo:[0,0,1] neg_hi:[0,0,1]
	v_pk_add_f32 v[96:97], v[102:103], v[6:7]
	v_pk_add_f32 v[6:7], v[102:103], v[6:7] neg_lo:[0,1] neg_hi:[0,1]
	v_mov_b32_e32 v102, v6
	v_mov_b32_e32 v103, v7
	v_pk_add_f32 v[6:7], v[10:11], v[4:5]
	v_pk_add_f32 v[4:5], v[10:11], v[4:5] neg_lo:[0,1] neg_hi:[0,1]
	v_pk_add_f32 v[10:11], v[4:5], 0 op_sel:[1,0] op_sel_hi:[0,0] neg_lo:[1,0]
	v_pk_add_f32 v[4:5], v[104:105], v[14:15]
	v_pk_add_f32 v[14:15], v[104:105], v[14:15] neg_lo:[0,1] neg_hi:[0,1]
	v_mov_b32_e32 v104, v14
	v_mov_b32_e32 v105, v15
	v_pk_add_f32 v[14:15], v[78:79], v[2:3]
	v_pk_add_f32 v[2:3], v[78:79], v[2:3] neg_lo:[0,1] neg_hi:[0,1]
	v_pk_add_f32 v[78:79], v[2:3], 0 op_sel:[1,0] op_sel_hi:[0,0] neg_lo:[1,0]
	v_pk_add_f32 v[2:3], v[110:111], v[12:13]
	v_pk_add_f32 v[12:13], v[110:111], v[12:13] neg_lo:[0,1] neg_hi:[0,1]
	v_mov_b32_e32 v110, v12
	v_mov_b32_e32 v111, v13
	v_pk_add_f32 v[12:13], v[116:117], v[8:9]
	v_pk_add_f32 v[8:9], v[116:117], v[8:9] neg_lo:[0,1] neg_hi:[0,1]
	v_pk_add_f32 v[116:117], v[8:9], 0 op_sel:[1,0] op_sel_hi:[0,0] neg_lo:[1,0]
	v_pk_add_f32 v[8:9], v[68:69], v[92:93]
	v_pk_add_f32 v[92:93], v[68:69], v[92:93] neg_lo:[0,1] neg_hi:[0,1]
	v_mov_b32_e32 v68, v92
	v_mov_b32_e32 v69, v93
	v_pk_add_f32 v[92:93], v[112:113], v[16:17]
	v_pk_add_f32 v[16:17], v[112:113], v[16:17] neg_lo:[0,1] neg_hi:[0,1]
	v_pk_add_f32 v[100:101], v[16:17], 0 op_sel:[1,0] op_sel_hi:[0,0] neg_lo:[1,0]
	v_pk_add_f32 v[16:17], v[106:107], v[76:77]
	v_pk_add_f32 v[76:77], v[106:107], v[76:77] neg_lo:[0,1] neg_hi:[0,1]
	v_pk_add_f32 v[112:113], v[108:109], v[18:19]
	v_pk_add_f32 v[18:19], v[108:109], v[18:19] neg_lo:[0,1] neg_hi:[0,1]
	v_pk_add_f32 v[108:109], v[18:19], 0 op_sel:[1,0] op_sel_hi:[0,0] neg_lo:[1,0]
	v_pk_add_f32 v[18:19], v[70:71], v[118:119]
	v_pk_add_f32 v[118:119], v[70:71], v[118:119] neg_lo:[0,1] neg_hi:[0,1]
	v_pk_add_f32 v[70:71], v[90:91], v[72:73]
	v_pk_add_f32 v[72:73], v[90:91], v[72:73] neg_lo:[0,1] neg_hi:[0,1]
	v_pk_add_f32 v[90:91], v[72:73], 0 op_sel:[1,0] op_sel_hi:[0,0] neg_lo:[1,0]
	v_pk_add_f32 v[72:73], v[98:99], v[86:87]
	v_pk_add_f32 v[86:87], v[98:99], v[86:87] neg_lo:[0,1] neg_hi:[0,1]
	v_pk_add_f32 v[106:107], v[82:83], v[80:81]
	v_pk_add_f32 v[80:81], v[82:83], v[80:81] neg_lo:[0,1] neg_hi:[0,1]
	v_pk_add_f32 v[82:83], v[80:81], 0 op_sel:[1,0] op_sel_hi:[0,0] neg_lo:[1,0]
	v_pk_add_f32 v[80:81], v[84:85], v[94:95]
	v_pk_add_f32 v[94:95], v[84:85], v[94:95] neg_lo:[0,1] neg_hi:[0,1]
	v_pk_add_f32 v[84:85], v[0:1], v[114:115]
	v_pk_add_f32 v[114:115], v[0:1], v[114:115] neg_lo:[0,1] neg_hi:[0,1]
	v_pk_add_f32 v[98:99], v[114:115], 0 op_sel:[1,0] op_sel_hi:[0,0] neg_lo:[1,0]
	v_pk_add_f32 v[0:1], v[96:97], v[6:7]
	v_pk_add_f32 v[6:7], v[96:97], v[6:7] neg_lo:[0,1] neg_hi:[0,1]
	v_mov_b32_e32 v114, v6
	v_mov_b32_e32 v115, v7
	v_pk_add_f32 v[6:7], v[102:103], v[10:11]
	v_pk_add_f32 v[10:11], v[102:103], v[10:11] neg_lo:[0,1] neg_hi:[0,1]
	v_mov_b32_e32 v102, v10
	v_mov_b32_e32 v103, v11
	v_pk_add_f32 v[10:11], v[4:5], v[14:15]
	v_pk_add_f32 v[4:5], v[4:5], v[14:15] neg_lo:[0,1] neg_hi:[0,1]
	v_mov_b32_e32 v96, v4
	v_mov_b32_e32 v97, v5
	v_pk_add_f32 v[14:15], v[104:105], v[78:79] neg_lo:[0,1] neg_hi:[0,1]
	v_pk_add_f32 v[4:5], v[104:105], v[78:79]
	v_mov_b32_e32 v104, v14
	v_mov_b32_e32 v105, v15
	v_pk_add_f32 v[14:15], v[2:3], v[12:13]
	v_pk_add_f32 v[2:3], v[2:3], v[12:13] neg_lo:[0,1] neg_hi:[0,1]
	v_mov_b32_e32 v78, v2
	v_mov_b32_e32 v79, v3
; #define LAS __attribute__((address_space(3)))
; #define SINCOSPI(x, s, c) do { const float hx_ = 0.5f * (x); *(s) = __builtin_amdgcn_sinf(hx_); *(c) = __builtin_amdgcn_cosf(hx_); } while (0)
; #define OPAQUE_I(x) asm volatile("" : "+v"(x))
; DEV void fft_i1x2(LAS cf* buf0, LAS cf* buf1, cf (&y0)[8], cf (&y1)[8], int tid) {
;     OPAQUE_I(tid);
;     float sn, cs; SINCOSPI(-(float)tid * (2.0f / 8192.0f), &sn, &cs);
;     const cf w = cf{cs, sn}; cf wp = cf{1.f, 0.f};
;     cf v[16], u[16];
;     const LAS cf* p0 = buf0 + PADI(tid); const LAS cf* p1 = buf1 + PADI(tid);
; #pragma unroll
;     for (int p = 0; p < 16; ++p) { v[p] = cmulc(p0[544 * p], wp); u[p] = cmulc(p1[544 * p], wp); wp = cmul(wp, w); }
; DEV void fft_i2(LAS cf* buf, int t8) {
;     ...
;     dft_regs<32, true>(v);
; #pragma unroll
;     for (int q = 0; q < 32; ++q) pb[17 * q] = v[BR32[q]];
	v_pk_add_f32 v[12:13], v[110:111], v[116:117] neg_lo:[0,1] neg_hi:[0,1]
	v_pk_add_f32 v[2:3], v[110:111], v[116:117]
	v_mov_b32_e32 v110, v12
	v_mov_b32_e32 v111, v13
	v_pk_add_f32 v[12:13], v[8:9], v[92:93]
	v_pk_add_f32 v[8:9], v[8:9], v[92:93] neg_lo:[0,1] neg_hi:[0,1]
	v_mov_b32_e32 v92, v8
	v_mov_b32_e32 v93, v9
	v_pk_add_f32 v[116:117], v[68:69], v[100:101] neg_lo:[0,1] neg_hi:[0,1]
	v_pk_add_f32 v[8:9], v[68:69], v[100:101]
	v_pk_add_f32 v[68:69], v[16:17], v[112:113]
	v_pk_add_f32 v[16:17], v[16:17], v[112:113] neg_lo:[0,1] neg_hi:[0,1]
	v_pk_add_f32 v[100:101], v[76:77], v[108:109]
	v_pk_add_f32 v[108:109], v[76:77], v[108:109] neg_lo:[0,1] neg_hi:[0,1]
	v_pk_add_f32 v[76:77], v[18:19], v[70:71]
	v_pk_add_f32 v[18:19], v[18:19], v[70:71] neg_lo:[0,1] neg_hi:[0,1]
	v_pk_add_f32 v[112:113], v[118:119], v[90:91] neg_lo:[0,1] neg_hi:[0,1]
	v_pk_add_f32 v[70:71], v[118:119], v[90:91]
	v_pk_add_f32 v[118:119], v[72:73], v[106:107]
	v_pk_add_f32 v[72:73], v[72:73], v[106:107] neg_lo:[0,1] neg_hi:[0,1]
	v_pk_add_f32 v[106:107], v[86:87], v[82:83] neg_lo:[0,1] neg_hi:[0,1]
	v_pk_add_f32 v[90:91], v[86:87], v[82:83]
	v_pk_add_f32 v[86:87], v[80:81], v[84:85]
	v_pk_add_f32 v[80:81], v[80:81], v[84:85] neg_lo:[0,1] neg_hi:[0,1]
	v_pk_add_f32 v[82:83], v[94:95], v[98:99] neg_lo:[0,1] neg_hi:[0,1]
	v_pk_add_f32 v[84:85], v[94:95], v[98:99]
	v_mov_b32_e32 v94, v82
	v_mov_b32_e32 v95, v83
	ds_write2_b64 v74, v[0:1], v[68:69] offset1:17
	ds_write2_b64 v74, v[14:15], v[118:119] offset0:34 offset1:51
	ds_write2_b64 v74, v[10:11], v[76:77] offset0:68 offset1:85
	ds_write2_b64 v74, v[12:13], v[86:87] offset0:102 offset1:119
	ds_write2_b64 v74, v[6:7], v[100:101] offset0:136 offset1:153
	ds_write2_b64 v74, v[2:3], v[90:91] offset0:170 offset1:187
	ds_write2_b64 v74, v[4:5], v[70:71] offset0:204 offset1:221
	ds_write2_b64 v74, v[8:9], v[84:85] offset0:238 offset1:255
	ds_write2_b64 v75, v[114:115], v[16:17] offset0:16 offset1:33
	ds_write2_b64 v75, v[78:79], v[72:73] offset0:50 offset1:67
	ds_write2_b64 v75, v[96:97], v[18:19] offset0:84 offset1:101
	ds_write2_b64 v75, v[92:93], v[80:81] offset0:118 offset1:135
	ds_write2_b64 v75, v[102:103], v[108:109] offset0:152 offset1:169
	ds_write2_b64 v75, v[110:111], v[106:107] offset0:186 offset1:203
	ds_write2_b64 v75, v[104:105], v[112:113] offset0:220 offset1:237
	ds_write2_b64 v88, v[116:117], v[94:95] offset0:126 offset1:143
	s_mov_b32 s2, 0x1800000
	s_mov_b32 s2, 0x3000000
	s_nop 0
	s_mov_b32 s2, 0x4800000
	s_nop 0
	s_waitcnt lgkmcnt(0)
	s_barrier
	s_nop 0
	v_mov_b32_e32 v100, v21
	s_andn2_b64 vcc, exec, s[26:27]
	v_cvt_f32_i32_e32 v101, v100
	v_mul_f32_e32 v101, 0xb9800000, v101
	v_mul_f32_e32 v101, 0.5, v101
	v_sin_f32_e32 v93, v101
	v_cos_f32_e32 v92, v101
	v_ashrrev_i32_e32 v101, 4, v100
	v_add_lshl_u32 v100, v101, v100, 3
	v_add_u32_e32 v163, 0, v100
	v_add_u32_e32 v164, s33, v100
	ds_read_b64 v[166:167], v163
	ds_read_b64 v[168:169], v164
	ds_read_b64 v[170:171], v163 offset:4352
	ds_read_b64 v[172:173], v164 offset:4352
	ds_read_b64 v[174:175], v163 offset:8704
	ds_read_b64 v[176:177], v164 offset:8704
	ds_read_b64 v[178:179], v163 offset:13056
	ds_read_b64 v[180:181], v164 offset:13056
	ds_read_b64 v[182:183], v163 offset:17408
	ds_read_b64 v[184:185], v164 offset:17408
	ds_read_b64 v[186:187], v163 offset:21760
	ds_read_b64 v[188:189], v164 offset:21760
	ds_read_b64 v[190:191], v163 offset:26112
	s_waitcnt lgkmcnt(12)
	v_pk_mul_f32 v[18:19], v[166:167], v[66:67] op_sel:[1,1] op_sel_hi:[1,0]
	v_pk_fma_f32 v[76:77], v[166:167], v[66:67], v[18:19] op_sel_hi:[0,1,1] neg_hi:[1,0,0]
	ds_read_b64 v[166:167], v164 offset:26112
	s_waitcnt lgkmcnt(12)
	v_pk_mul_f32 v[18:19], v[168:169], v[66:67] op_sel:[1,1] op_sel_hi:[1,0]
	v_pk_fma_f32 v[16:17], v[168:169], v[66:67], v[18:19] op_sel_hi:[0,1,1] neg_hi:[1,0,0]
	s_nop 0
	v_pk_mul_f32 v[18:19], v[66:67], v[92:93] op_sel:[1,1] op_sel_hi:[1,0] neg_lo:[1,0]
	v_pk_fma_f32 v[66:67], v[66:67], v[92:93], v[18:19] op_sel_hi:[0,1,1]
	ds_read_b64 v[168:169], v163 offset:30464
	s_waitcnt lgkmcnt(12)
	v_pk_mul_f32 v[68:69], v[170:171], v[66:67] op_sel:[1,1] op_sel_hi:[1,0]
	v_pk_fma_f32 v[78:79], v[170:171], v[66:67], v[68:69] op_sel_hi:[0,1,1] neg_hi:[1,0,0]
	ds_read_b64 v[170:171], v164 offset:30464
	s_waitcnt lgkmcnt(12)
	v_pk_mul_f32 v[68:69], v[172:173], v[66:67] op_sel:[1,1] op_sel_hi:[1,0]
	v_pk_fma_f32 v[18:19], v[172:173], v[66:67], v[68:69] op_sel_hi:[0,1,1] neg_hi:[1,0,0]
	s_nop 0
	v_pk_mul_f32 v[68:69], v[66:67], v[92:93] op_sel:[1,1] op_sel_hi:[1,0] neg_lo:[1,0]
	v_pk_fma_f32 v[70:71], v[66:67], v[92:93], v[68:69] op_sel_hi:[0,1,1]
	ds_read_b64 v[172:173], v163 offset:34816
	s_waitcnt lgkmcnt(12)
	v_pk_mul_f32 v[68:69], v[174:175], v[70:71] op_sel:[1,1] op_sel_hi:[1,0]
	v_pk_fma_f32 v[82:83], v[174:175], v[70:71], v[68:69] op_sel_hi:[0,1,1] neg_hi:[1,0,0]
	ds_read_b64 v[174:175], v164 offset:34816
	s_waitcnt lgkmcnt(12)
	v_pk_mul_f32 v[68:69], v[176:177], v[70:71] op_sel:[1,1] op_sel_hi:[1,0]
	v_pk_fma_f32 v[66:67], v[176:177], v[70:71], v[68:69] op_sel_hi:[0,1,1] neg_hi:[1,0,0]
	s_nop 0
	v_pk_mul_f32 v[68:69], v[70:71], v[92:93] op_sel:[1,1] op_sel_hi:[1,0] neg_lo:[1,0]
	v_pk_fma_f32 v[70:71], v[70:71], v[92:93], v[68:69] op_sel_hi:[0,1,1]
	ds_read_b64 v[176:177], v163 offset:39168
	s_waitcnt lgkmcnt(12)
	v_pk_mul_f32 v[72:73], v[178:179], v[70:71] op_sel:[1,1] op_sel_hi:[1,0]
	v_pk_fma_f32 v[84:85], v[178:179], v[70:71], v[72:73] op_sel_hi:[0,1,1] neg_hi:[1,0,0]
	ds_read_b64 v[178:179], v164 offset:39168
	s_waitcnt lgkmcnt(12)
; #define LAS __attribute__((address_space(3)))
; #define SINCOSPI(x, s, c) do { const float hx_ = 0.5f * (x); *(s) = __builtin_amdgcn_sinf(hx_); *(c) = __builtin_amdgcn_cosf(hx_); } while (0)
; DEV void fft_i1x2(LAS cf* buf0, LAS cf* buf1, cf (&y0)[8], cf (&y1)[8], int tid) {
;     ...
;     float sn, cs; SINCOSPI(-(float)tid * (2.0f / 8192.0f), &sn, &cs);
;     const cf w = cf{cs, sn}; cf wp = cf{1.f, 0.f};
;     cf v[16], u[16];
;     const LAS cf* p0 = buf0 + PADI(tid); const LAS cf* p1 = buf1 + PADI(tid);
; #pragma unroll
;     for (int p = 0; p < 16; ++p) { v[p] = cmulc(p0[544 * p], wp); u[p] = cmulc(p1[544 * p], wp); wp = cmul(wp, w); }
	v_pk_mul_f32 v[72:73], v[180:181], v[70:71] op_sel:[1,1] op_sel_hi:[1,0]
	v_pk_fma_f32 v[68:69], v[180:181], v[70:71], v[72:73] op_sel_hi:[0,1,1] neg_hi:[1,0,0]
	s_nop 0
	v_pk_mul_f32 v[72:73], v[70:71], v[92:93] op_sel:[1,1] op_sel_hi:[1,0] neg_lo:[1,0]
	v_pk_fma_f32 v[74:75], v[70:71], v[92:93], v[72:73] op_sel_hi:[0,1,1]
	ds_read_b64 v[180:181], v163 offset:43520
	s_waitcnt lgkmcnt(12)
	v_pk_mul_f32 v[72:73], v[182:183], v[74:75] op_sel:[1,1] op_sel_hi:[1,0]
	v_pk_fma_f32 v[86:87], v[182:183], v[74:75], v[72:73] op_sel_hi:[0,1,1] neg_hi:[1,0,0]
	ds_read_b64 v[182:183], v164 offset:43520
	s_waitcnt lgkmcnt(12)
	v_pk_mul_f32 v[72:73], v[184:185], v[74:75] op_sel:[1,1] op_sel_hi:[1,0]
	v_pk_fma_f32 v[70:71], v[184:185], v[74:75], v[72:73] op_sel_hi:[0,1,1] neg_hi:[1,0,0]
	s_nop 0
	v_pk_mul_f32 v[72:73], v[74:75], v[92:93] op_sel:[1,1] op_sel_hi:[1,0] neg_lo:[1,0]
	v_pk_fma_f32 v[74:75], v[74:75], v[92:93], v[72:73] op_sel_hi:[0,1,1]
	ds_read_b64 v[184:185], v163 offset:47872
	s_waitcnt lgkmcnt(12)
	v_pk_mul_f32 v[80:81], v[186:187], v[74:75] op_sel:[1,1] op_sel_hi:[1,0]
	v_pk_fma_f32 v[90:91], v[186:187], v[74:75], v[80:81] op_sel_hi:[0,1,1] neg_hi:[1,0,0]
	ds_read_b64 v[186:187], v164 offset:47872
	s_waitcnt lgkmcnt(12)
	v_pk_mul_f32 v[80:81], v[188:189], v[74:75] op_sel:[1,1] op_sel_hi:[1,0]
	v_pk_fma_f32 v[72:73], v[188:189], v[74:75], v[80:81] op_sel_hi:[0,1,1] neg_hi:[1,0,0]
	s_nop 0
	v_pk_mul_f32 v[80:81], v[74:75], v[92:93] op_sel:[1,1] op_sel_hi:[1,0] neg_lo:[1,0]
	v_pk_fma_f32 v[88:89], v[74:75], v[92:93], v[80:81] op_sel_hi:[0,1,1]
	ds_read_b64 v[188:189], v163 offset:52224
	s_waitcnt lgkmcnt(12)
	v_pk_mul_f32 v[80:81], v[190:191], v[88:89] op_sel:[1,1] op_sel_hi:[1,0]
	v_pk_fma_f32 v[94:95], v[190:191], v[88:89], v[80:81] op_sel_hi:[0,1,1] neg_hi:[1,0,0]
	ds_read_b64 v[190:191], v164 offset:52224
	s_waitcnt lgkmcnt(12)
	v_pk_mul_f32 v[80:81], v[166:167], v[88:89] op_sel:[1,1] op_sel_hi:[1,0]
	v_pk_fma_f32 v[74:75], v[166:167], v[88:89], v[80:81] op_sel_hi:[0,1,1] neg_hi:[1,0,0]
	s_nop 0
	v_pk_mul_f32 v[80:81], v[88:89], v[92:93] op_sel:[1,1] op_sel_hi:[1,0] neg_lo:[1,0]
	v_pk_fma_f32 v[88:89], v[88:89], v[92:93], v[80:81] op_sel_hi:[0,1,1]
	ds_read_b64 v[166:167], v163 offset:56576
	s_waitcnt lgkmcnt(12)
	v_pk_mul_f32 v[96:97], v[168:169], v[88:89] op_sel:[1,1] op_sel_hi:[1,0]
	v_pk_fma_f32 v[98:99], v[168:169], v[88:89], v[96:97] op_sel_hi:[0,1,1] neg_hi:[1,0,0]
	ds_read_b64 v[168:169], v164 offset:56576
	s_waitcnt lgkmcnt(12)
	v_pk_mul_f32 v[96:97], v[170:171], v[88:89] op_sel:[1,1] op_sel_hi:[1,0]
	v_pk_fma_f32 v[80:81], v[170:171], v[88:89], v[96:97] op_sel_hi:[0,1,1] neg_hi:[1,0,0]
	s_nop 0
	v_pk_mul_f32 v[96:97], v[88:89], v[92:93] op_sel:[1,1] op_sel_hi:[1,0] neg_lo:[1,0]
	v_pk_fma_f32 v[102:103], v[88:89], v[92:93], v[96:97] op_sel_hi:[0,1,1]
	ds_read_b64 v[170:171], v163 offset:60928
	s_waitcnt lgkmcnt(12)
	v_pk_mul_f32 v[96:97], v[172:173], v[102:103] op_sel:[1,1] op_sel_hi:[1,0]
	v_pk_fma_f32 v[100:101], v[172:173], v[102:103], v[96:97] op_sel_hi:[0,1,1] neg_hi:[1,0,0]
	ds_read_b64 v[172:173], v164 offset:60928
	s_waitcnt lgkmcnt(12)
	v_pk_mul_f32 v[96:97], v[174:175], v[102:103] op_sel:[1,1] op_sel_hi:[1,0]
	v_pk_fma_f32 v[88:89], v[174:175], v[102:103], v[96:97] op_sel_hi:[0,1,1] neg_hi:[1,0,0]
	s_nop 0
	v_pk_mul_f32 v[96:97], v[102:103], v[92:93] op_sel:[1,1] op_sel_hi:[1,0] neg_lo:[1,0]
	v_pk_fma_f32 v[102:103], v[102:103], v[92:93], v[96:97] op_sel_hi:[0,1,1]
	ds_read_b64 v[174:175], v163 offset:65280
	s_waitcnt lgkmcnt(12)
	v_pk_mul_f32 v[104:105], v[176:177], v[102:103] op_sel:[1,1] op_sel_hi:[1,0]
	v_pk_fma_f32 v[112:113], v[176:177], v[102:103], v[104:105] op_sel_hi:[0,1,1] neg_hi:[1,0,0]
	ds_read_b64 v[176:177], v164 offset:65280
	s_waitcnt lgkmcnt(12)
; #define LAS __attribute__((address_space(3)))
; #define SINCOSPI(x, s, c) do { const float hx_ = 0.5f * (x); *(s) = __builtin_amdgcn_sinf(hx_); *(c) = __builtin_amdgcn_cosf(hx_); } while (0)
; #define OPAQUE_I(x) asm volatile("" : "+v"(x))
; DEV void fft_i1x2(LAS cf* buf0, LAS cf* buf1, cf (&y0)[8], cf (&y1)[8], int tid) {
;     OPAQUE_I(tid);
;     float sn, cs; SINCOSPI(-(float)tid * (2.0f / 8192.0f), &sn, &cs);
;     const cf w = cf{cs, sn}; cf wp = cf{1.f, 0.f};
;     cf v[16], u[16];
;     const LAS cf* p0 = buf0 + PADI(tid); const LAS cf* p1 = buf1 + PADI(tid);
; #pragma unroll
;     for (int p = 0; p < 16; ++p) { v[p] = cmulc(p0[544 * p], wp); u[p] = cmulc(p1[544 * p], wp); wp = cmul(wp, w); }
; DEV void hyena_issue_rows(const bf16_t* UT, int s, int c, u32x4 (&r)[4], int tid) {
; #pragma unroll
;     for (int b = 0; b < 4; ++b) r[b] = *(const u32x4*)(UT + ((size_t)(b * 3072 + s * 1024 + c)) * 4096 + tid * 8);
; }
; DEV void hyena_commit_rows(LAS unsigned char* lds, const u32x4 (&r)[4], int tid) {
; #pragma unroll
;     for (int b = 0; b < 4; ++b) *(LAS u32x4*)(lds + b * 8192 + tid * 16) = r[b];
; }
	v_pk_mul_f32 v[104:105], v[178:179], v[102:103] op_sel:[1,1] op_sel_hi:[1,0]
	v_pk_fma_f32 v[96:97], v[178:179], v[102:103], v[104:105] op_sel_hi:[0,1,1] neg_hi:[1,0,0]
	s_nop 0
	v_pk_mul_f32 v[104:105], v[102:103], v[92:93] op_sel:[1,1] op_sel_hi:[1,0] neg_lo:[1,0]
	v_pk_fma_f32 v[106:107], v[102:103], v[92:93], v[104:105] op_sel_hi:[0,1,1]
	s_waitcnt lgkmcnt(11)
	v_pk_mul_f32 v[104:105], v[180:181], v[106:107] op_sel:[1,1] op_sel_hi:[1,0]
	v_pk_fma_f32 v[116:117], v[180:181], v[106:107], v[104:105] op_sel_hi:[0,1,1] neg_hi:[1,0,0]
	s_waitcnt lgkmcnt(10)
	v_pk_mul_f32 v[104:105], v[182:183], v[106:107] op_sel:[1,1] op_sel_hi:[1,0]
	v_pk_fma_f32 v[102:103], v[182:183], v[106:107], v[104:105] op_sel_hi:[0,1,1] neg_hi:[1,0,0]
	s_nop 0
	v_pk_mul_f32 v[104:105], v[106:107], v[92:93] op_sel:[1,1] op_sel_hi:[1,0] neg_lo:[1,0]
	v_pk_fma_f32 v[106:107], v[106:107], v[92:93], v[104:105] op_sel_hi:[0,1,1]
	s_waitcnt lgkmcnt(9)
	v_pk_mul_f32 v[108:109], v[184:185], v[106:107] op_sel:[1,1] op_sel_hi:[1,0]
	v_pk_fma_f32 v[118:119], v[184:185], v[106:107], v[108:109] op_sel_hi:[0,1,1] neg_hi:[1,0,0]
	s_waitcnt lgkmcnt(8)
	v_pk_mul_f32 v[108:109], v[186:187], v[106:107] op_sel:[1,1] op_sel_hi:[1,0]
	v_pk_fma_f32 v[104:105], v[186:187], v[106:107], v[108:109] op_sel_hi:[0,1,1] neg_hi:[1,0,0]
	s_nop 0
	v_pk_mul_f32 v[108:109], v[106:107], v[92:93] op_sel:[1,1] op_sel_hi:[1,0] neg_lo:[1,0]
	v_pk_fma_f32 v[110:111], v[106:107], v[92:93], v[108:109] op_sel_hi:[0,1,1]
	s_waitcnt lgkmcnt(7)
	v_pk_mul_f32 v[108:109], v[188:189], v[110:111] op_sel:[1,1] op_sel_hi:[1,0]
	v_pk_fma_f32 v[120:121], v[188:189], v[110:111], v[108:109] op_sel_hi:[0,1,1] neg_hi:[1,0,0]
	s_waitcnt lgkmcnt(6)
	v_pk_mul_f32 v[108:109], v[190:191], v[110:111] op_sel:[1,1] op_sel_hi:[1,0]
	v_pk_fma_f32 v[106:107], v[190:191], v[110:111], v[108:109] op_sel_hi:[0,1,1] neg_hi:[1,0,0]
	s_nop 0
	v_pk_mul_f32 v[108:109], v[110:111], v[92:93] op_sel:[1,1] op_sel_hi:[1,0] neg_lo:[1,0]
	v_pk_fma_f32 v[110:111], v[110:111], v[92:93], v[108:109] op_sel_hi:[0,1,1]
	s_waitcnt lgkmcnt(5)
	v_pk_mul_f32 v[114:115], v[166:167], v[110:111] op_sel:[1,1] op_sel_hi:[1,0]
	v_pk_fma_f32 v[122:123], v[166:167], v[110:111], v[114:115] op_sel_hi:[0,1,1] neg_hi:[1,0,0]
	s_waitcnt lgkmcnt(4)
	v_pk_mul_f32 v[114:115], v[168:169], v[110:111] op_sel:[1,1] op_sel_hi:[1,0]
	v_pk_fma_f32 v[108:109], v[168:169], v[110:111], v[114:115] op_sel_hi:[0,1,1] neg_hi:[1,0,0]
	s_nop 0
	v_pk_mul_f32 v[114:115], v[110:111], v[92:93] op_sel:[1,1] op_sel_hi:[1,0] neg_lo:[1,0]
	v_pk_fma_f32 v[126:127], v[110:111], v[92:93], v[114:115] op_sel_hi:[0,1,1]
	s_waitcnt lgkmcnt(3)
	v_pk_mul_f32 v[114:115], v[170:171], v[126:127] op_sel:[1,1] op_sel_hi:[1,0]
	v_pk_fma_f32 v[124:125], v[170:171], v[126:127], v[114:115] op_sel_hi:[0,1,1] neg_hi:[1,0,0]
	s_waitcnt lgkmcnt(2)
	v_pk_mul_f32 v[114:115], v[172:173], v[126:127] op_sel:[1,1] op_sel_hi:[1,0]
	v_pk_fma_f32 v[110:111], v[172:173], v[126:127], v[114:115] op_sel_hi:[0,1,1] neg_hi:[1,0,0]
	s_nop 0
	v_pk_mul_f32 v[114:115], v[126:127], v[92:93] op_sel:[1,1] op_sel_hi:[1,0] neg_lo:[1,0]
	v_pk_fma_f32 v[126:127], v[126:127], v[92:93], v[114:115] op_sel_hi:[0,1,1]
	s_waitcnt lgkmcnt(1)
	v_pk_mul_f32 v[114:115], v[174:175], v[126:127] op_sel:[1,1] op_sel_hi:[1,0]
	v_pk_fma_f32 v[92:93], v[174:175], v[126:127], v[114:115] op_sel_hi:[0,1,1] neg_hi:[1,0,0]
	s_waitcnt lgkmcnt(0)
	v_pk_mul_f32 v[164:165], v[176:177], v[126:127] op_sel:[1,1] op_sel_hi:[1,0]
	v_pk_fma_f32 v[114:115], v[176:177], v[126:127], v[164:165] op_sel_hi:[0,1,1] neg_hi:[1,0,0]
	s_barrier
	s_waitcnt vmcnt(3)
	ds_write_b128 v128, v[222:225]
	s_waitcnt vmcnt(2)
	ds_write_b128 v128, v[226:229] offset:8192
	s_waitcnt vmcnt(1)
	ds_write_b128 v128, v[236:239] offset:16384
	s_waitcnt vmcnt(0)
	ds_write_b128 v128, v[240:243] offset:24576
	s_cbranch_vccnz .LBB0_518
	s_andn2_b64 vcc, exec, s[20:21]
	s_cbranch_vccnz .LBB0_518
	global_load_dwordx4 v[0:3], v[58:59], off
	global_load_dwordx4 v[4:7], v[60:61], off
	global_load_dwordx4 v[8:11], v[62:63], off
	global_load_dwordx4 v[12:15], v[64:65], off
	s_branch .LBB0_518
